# all 11 GEMM main loops: LDS-DMA loads use SGPR base + 32-bit VGPR offset (172 per-iteration 64-bit VALU adds removed)
# speedup vs baseline: 1.0133x; 1.0028x over previous
.LBB0_137:
	s_add_u32 s30, s28, 0xfff80080
	s_addc_u32 s31, s29, -1
	s_add_i32 s48, 0, 0x10000
	s_cmp_eq_u32 s47, 28
	s_cselect_b32 s35, s13, s31
	s_cselect_b32 s34, s43, s30
	v_add_u32_e32 v140, s48, v143
	s_cselect_b32 s31, s15, s46
	s_cselect_b32 s30, s44, s45
	s_add_i32 s50, 0, 0x14000
	ds_read_b128 v[146:149], v140
	ds_read_b128 v[150:153], v140 offset:1024
	ds_read_b128 v[154:157], v140 offset:2048
	ds_read_b128 v[158:161], v140 offset:3072
	v_add_u32_e32 v140, s50, v143
	ds_read_b128 v[162:165], v140
	ds_read_b128 v[166:169], v140 offset:1024
	ds_read_b128 v[170:173], v140 offset:2048
	ds_read_b128 v[178:181], v140 offset:3072
	s_add_i32 m0, s27, 0xc000
	ds_read_b128 v[182:185], v144
	ds_read_b128 v[186:189], v144 offset:1024
	ds_read_b128 v[190:193], v144 offset:2048
	ds_read_b128 v[194:197], v144 offset:3072
	ds_read_b128 v[198:201], v144 offset:4096
	ds_read_b128 v[202:205], v144 offset:5120
	ds_read_b128 v[206:209], v144 offset:6144
	ds_read_b128 v[220:223], v144 offset:7168
	global_load_lds_dwordx4 v136, s[28:29]
	s_add_i32 m0, s27, 0xe000
	s_nop 0
	global_load_lds_dwordx4 v138, s[28:29]
	s_waitcnt vmcnt(8)
	s_waitcnt lgkmcnt(0)
	s_barrier
	s_setprio 1
	s_waitcnt lgkmcnt(0)
	v_mfma_f32_16x16x32_bf16 v[124:127], v[146:149], v[182:185], v[124:127]
	v_mfma_f32_16x16x32_bf16 v[120:123], v[154:157], v[182:185], v[120:123]
	v_mfma_f32_16x16x32_bf16 v[108:111], v[146:149], v[190:193], v[108:111]
	v_mfma_f32_16x16x32_bf16 v[104:107], v[154:157], v[190:193], v[104:107]
	v_mfma_f32_16x16x32_bf16 v[92:95], v[146:149], v[198:201], v[92:95]
	v_mfma_f32_16x16x32_bf16 v[88:91], v[154:157], v[198:201], v[88:91]
	v_mfma_f32_16x16x32_bf16 v[76:79], v[146:149], v[206:209], v[76:79]
	v_mfma_f32_16x16x32_bf16 v[72:75], v[154:157], v[206:209], v[72:75]
	v_mfma_f32_16x16x32_bf16 v[124:127], v[150:153], v[186:189], v[124:127]
	v_mfma_f32_16x16x32_bf16 v[120:123], v[158:161], v[186:189], v[120:123]
	v_mfma_f32_16x16x32_bf16 v[108:111], v[150:153], v[194:197], v[108:111]
	v_mfma_f32_16x16x32_bf16 v[104:107], v[158:161], v[194:197], v[104:107]
	v_mfma_f32_16x16x32_bf16 v[92:95], v[150:153], v[202:205], v[92:95]
	v_mfma_f32_16x16x32_bf16 v[88:91], v[158:161], v[202:205], v[88:91]
	v_mfma_f32_16x16x32_bf16 v[76:79], v[150:153], v[220:223], v[76:79]
	v_mfma_f32_16x16x32_bf16 v[72:75], v[158:161], v[220:223], v[72:75]
	s_setprio 0
	s_setprio 1
	v_mfma_f32_16x16x32_bf16 v[116:119], v[162:165], v[182:185], v[116:119]
	v_mfma_f32_16x16x32_bf16 v[112:115], v[170:173], v[182:185], v[112:115]
	v_mfma_f32_16x16x32_bf16 v[100:103], v[162:165], v[190:193], v[100:103]
	v_mfma_f32_16x16x32_bf16 v[96:99], v[170:173], v[190:193], v[96:99]
	v_mfma_f32_16x16x32_bf16 v[84:87], v[162:165], v[198:201], v[84:87]
	v_mfma_f32_16x16x32_bf16 v[80:83], v[170:173], v[198:201], v[80:83]
	v_mfma_f32_16x16x32_bf16 v[68:71], v[162:165], v[206:209], v[68:71]
	v_mfma_f32_16x16x32_bf16 v[64:67], v[170:173], v[206:209], v[64:67]
	v_mfma_f32_16x16x32_bf16 v[116:119], v[166:169], v[186:189], v[116:119]
	v_mfma_f32_16x16x32_bf16 v[112:115], v[178:181], v[186:189], v[112:115]
	v_mfma_f32_16x16x32_bf16 v[100:103], v[166:169], v[194:197], v[100:103]
	v_mfma_f32_16x16x32_bf16 v[96:99], v[178:181], v[194:197], v[96:99]
	v_mfma_f32_16x16x32_bf16 v[84:87], v[166:169], v[202:205], v[84:87]
	v_mfma_f32_16x16x32_bf16 v[80:83], v[178:181], v[202:205], v[80:83]
	v_mfma_f32_16x16x32_bf16 v[68:71], v[166:169], v[220:223], v[68:71]
	v_mfma_f32_16x16x32_bf16 v[64:67], v[178:181], v[220:223], v[64:67]
	s_setprio 0
	s_barrier
	s_add_i32 s48, s48, s26
	s_mov_b32 m0, s48
	ds_read_b128 v[182:185], v144 offset:16384
	ds_read_b128 v[186:189], v144 offset:17408
	ds_read_b128 v[190:193], v144 offset:18432
	ds_read_b128 v[194:197], v144 offset:19456
	ds_read_b128 v[198:201], v144 offset:20480
	ds_read_b128 v[202:205], v144 offset:21504
	ds_read_b128 v[206:209], v144 offset:22528
	ds_read_b128 v[220:223], v144 offset:23552
	global_load_lds_dwordx4 v132, s[30:31]
	s_add_i32 m0, s48, 0x2000
	s_add_u32 s48, s30, 0x80000
	s_addc_u32 s49, s31, 0
	s_add_i32 s50, s50, s26
	global_load_lds_dwordx4 v128, s[30:31]
	s_mov_b32 m0, s50
	s_nop 0
	global_load_lds_dwordx4 v132, s[48:49]
	s_add_i32 m0, s50, 0x2000
	s_nop 0
	global_load_lds_dwordx4 v128, s[48:49]
	s_add_u32 s60, s34, 0x80
	s_addc_u32 s61, s35, 0
	s_mov_b32 m0, s27
	s_nop 0
	global_load_lds_dwordx4 v134, s[34:35]
	s_mov_b32 m0, s33
	s_nop 0
	global_load_lds_dwordx4 v130, s[34:35]
	s_waitcnt vmcnt(8)
	s_waitcnt lgkmcnt(0)
	s_barrier
	s_setprio 1
	s_waitcnt lgkmcnt(0)
	v_mfma_f32_16x16x32_bf16 v[60:63], v[146:149], v[182:185], v[60:63]
	v_mfma_f32_16x16x32_bf16 v[56:59], v[154:157], v[182:185], v[56:59]
	v_mfma_f32_16x16x32_bf16 v[44:47], v[146:149], v[190:193], v[44:47]
	v_mfma_f32_16x16x32_bf16 v[40:43], v[154:157], v[190:193], v[40:43]
	v_mfma_f32_16x16x32_bf16 v[28:31], v[146:149], v[198:201], v[28:31]
	v_mfma_f32_16x16x32_bf16 v[24:27], v[154:157], v[198:201], v[24:27]
	v_mfma_f32_16x16x32_bf16 v[12:15], v[146:149], v[206:209], v[12:15]
	v_mfma_f32_16x16x32_bf16 v[8:11], v[154:157], v[206:209], v[8:11]
	v_mfma_f32_16x16x32_bf16 v[60:63], v[150:153], v[186:189], v[60:63]
	v_mfma_f32_16x16x32_bf16 v[56:59], v[158:161], v[186:189], v[56:59]
	v_mfma_f32_16x16x32_bf16 v[44:47], v[150:153], v[194:197], v[44:47]
	v_mfma_f32_16x16x32_bf16 v[40:43], v[158:161], v[194:197], v[40:43]
	v_mfma_f32_16x16x32_bf16 v[28:31], v[150:153], v[202:205], v[28:31]
	v_mfma_f32_16x16x32_bf16 v[24:27], v[158:161], v[202:205], v[24:27]
	v_mfma_f32_16x16x32_bf16 v[12:15], v[150:153], v[220:223], v[12:15]
	v_mfma_f32_16x16x32_bf16 v[8:11], v[158:161], v[220:223], v[8:11]
	s_setprio 0
	s_setprio 1
	v_mfma_f32_16x16x32_bf16 v[52:55], v[162:165], v[182:185], v[52:55]
	v_mfma_f32_16x16x32_bf16 v[48:51], v[170:173], v[182:185], v[48:51]
	v_mfma_f32_16x16x32_bf16 v[36:39], v[162:165], v[190:193], v[36:39]
	v_mfma_f32_16x16x32_bf16 v[32:35], v[170:173], v[190:193], v[32:35]
	v_mfma_f32_16x16x32_bf16 v[20:23], v[162:165], v[198:201], v[20:23]
	v_mfma_f32_16x16x32_bf16 v[16:19], v[170:173], v[198:201], v[16:19]
	v_mfma_f32_16x16x32_bf16 v[4:7], v[162:165], v[206:209], v[4:7]
	v_mfma_f32_16x16x32_bf16 v[0:3], v[170:173], v[206:209], v[0:3]
	v_mfma_f32_16x16x32_bf16 v[52:55], v[166:169], v[186:189], v[52:55]
	v_mfma_f32_16x16x32_bf16 v[48:51], v[178:181], v[186:189], v[48:51]
	v_mfma_f32_16x16x32_bf16 v[36:39], v[166:169], v[194:197], v[36:39]
	v_mfma_f32_16x16x32_bf16 v[32:35], v[178:181], v[194:197], v[32:35]
	v_mfma_f32_16x16x32_bf16 v[20:23], v[166:169], v[202:205], v[20:23]
	v_mfma_f32_16x16x32_bf16 v[16:19], v[178:181], v[202:205], v[16:19]
	v_mfma_f32_16x16x32_bf16 v[4:7], v[166:169], v[220:223], v[4:7]
	v_mfma_f32_16x16x32_bf16 v[0:3], v[178:181], v[220:223], v[0:3]
	s_setprio 0
	s_barrier
	s_add_i32 s48, 0, 0x18000
	v_add_u32_e32 v145, s48, v143
	s_add_i32 s49, 0, 0x1c000
	ds_read_b128 v[146:149], v145
	ds_read_b128 v[150:153], v145 offset:1024
	ds_read_b128 v[154:157], v145 offset:2048
	ds_read_b128 v[158:161], v145 offset:3072
	v_add_u32_e32 v145, s49, v143
	ds_read_b128 v[162:165], v145
	ds_read_b128 v[166:169], v145 offset:1024
	ds_read_b128 v[170:173], v145 offset:2048
	ds_read_b128 v[178:181], v145 offset:3072
	s_add_u32 s34, s34, 0x80000
	s_addc_u32 s35, s35, 0
	s_mov_b32 m0, s36
	ds_read_b128 v[182:185], v144 offset:32768
	ds_read_b128 v[186:189], v144 offset:33792
	ds_read_b128 v[190:193], v144 offset:34816
	ds_read_b128 v[194:197], v144 offset:35840
	ds_read_b128 v[198:201], v144 offset:36864
	ds_read_b128 v[202:205], v144 offset:37888
	ds_read_b128 v[206:209], v144 offset:38912
	ds_read_b128 v[220:223], v144 offset:39936
	global_load_lds_dwordx4 v134, s[34:35]
	s_mov_b32 m0, s37
	s_nop 0
	global_load_lds_dwordx4 v130, s[34:35]
	s_waitcnt vmcnt(8)
	s_waitcnt lgkmcnt(0)
	s_barrier
	s_setprio 1
	s_waitcnt lgkmcnt(0)
	v_mfma_f32_16x16x32_bf16 v[124:127], v[146:149], v[182:185], v[124:127]
	v_mfma_f32_16x16x32_bf16 v[120:123], v[154:157], v[182:185], v[120:123]
	v_mfma_f32_16x16x32_bf16 v[108:111], v[146:149], v[190:193], v[108:111]
	v_mfma_f32_16x16x32_bf16 v[104:107], v[154:157], v[190:193], v[104:107]
	v_mfma_f32_16x16x32_bf16 v[92:95], v[146:149], v[198:201], v[92:95]
	v_mfma_f32_16x16x32_bf16 v[88:91], v[154:157], v[198:201], v[88:91]
	v_mfma_f32_16x16x32_bf16 v[76:79], v[146:149], v[206:209], v[76:79]
	v_mfma_f32_16x16x32_bf16 v[72:75], v[154:157], v[206:209], v[72:75]
	v_mfma_f32_16x16x32_bf16 v[124:127], v[150:153], v[186:189], v[124:127]
	v_mfma_f32_16x16x32_bf16 v[120:123], v[158:161], v[186:189], v[120:123]
	v_mfma_f32_16x16x32_bf16 v[108:111], v[150:153], v[194:197], v[108:111]
	v_mfma_f32_16x16x32_bf16 v[104:107], v[158:161], v[194:197], v[104:107]
	v_mfma_f32_16x16x32_bf16 v[92:95], v[150:153], v[202:205], v[92:95]
	v_mfma_f32_16x16x32_bf16 v[88:91], v[158:161], v[202:205], v[88:91]
	v_mfma_f32_16x16x32_bf16 v[76:79], v[150:153], v[220:223], v[76:79]
	v_mfma_f32_16x16x32_bf16 v[72:75], v[158:161], v[220:223], v[72:75]
	s_setprio 0
	s_setprio 1
	v_mfma_f32_16x16x32_bf16 v[116:119], v[162:165], v[182:185], v[116:119]
	v_mfma_f32_16x16x32_bf16 v[112:115], v[170:173], v[182:185], v[112:115]
	v_mfma_f32_16x16x32_bf16 v[100:103], v[162:165], v[190:193], v[100:103]
	v_mfma_f32_16x16x32_bf16 v[96:99], v[170:173], v[190:193], v[96:99]
	v_mfma_f32_16x16x32_bf16 v[84:87], v[162:165], v[198:201], v[84:87]
	v_mfma_f32_16x16x32_bf16 v[80:83], v[170:173], v[198:201], v[80:83]
	v_mfma_f32_16x16x32_bf16 v[68:71], v[162:165], v[206:209], v[68:71]
	v_mfma_f32_16x16x32_bf16 v[64:67], v[170:173], v[206:209], v[64:67]
	v_mfma_f32_16x16x32_bf16 v[116:119], v[166:169], v[186:189], v[116:119]
	v_mfma_f32_16x16x32_bf16 v[112:115], v[178:181], v[186:189], v[112:115]
	v_mfma_f32_16x16x32_bf16 v[100:103], v[166:169], v[194:197], v[100:103]
	v_mfma_f32_16x16x32_bf16 v[96:99], v[178:181], v[194:197], v[96:99]
	v_mfma_f32_16x16x32_bf16 v[84:87], v[166:169], v[202:205], v[84:87]
	v_mfma_f32_16x16x32_bf16 v[80:83], v[178:181], v[202:205], v[80:83]
	v_mfma_f32_16x16x32_bf16 v[68:71], v[166:169], v[220:223], v[68:71]
	v_mfma_f32_16x16x32_bf16 v[64:67], v[178:181], v[220:223], v[64:67]
	s_setprio 0
	s_barrier
	s_add_i32 s34, s48, s26
	s_mov_b32 m0, s34
	ds_read_b128 v[182:185], v144 offset:49152
	ds_read_b128 v[186:189], v144 offset:50176
	ds_read_b128 v[190:193], v144 offset:51200
	ds_read_b128 v[194:197], v144 offset:52224
	ds_read_b128 v[198:201], v144 offset:53248
	ds_read_b128 v[202:205], v144 offset:54272
	ds_read_b128 v[206:209], v144 offset:55296
	ds_read_b128 v[220:223], v144 offset:56320
	s_add_u32 s98, s30, 0x80
	s_addc_u32 s99, s31, 0
	global_load_lds_dwordx4 v132, s[98:99]
	s_add_i32 m0, s34, 0x2000
	s_add_u32 s30, s30, 0x80080
	s_addc_u32 s31, s31, 0
	s_add_i32 s34, s49, s26
	s_add_u32 s98, s30, 0xfff80000
	s_addc_u32 s99, s31, -1
	global_load_lds_dwordx4 v128, s[98:99]
	s_mov_b32 m0, s34
	s_nop 0
	global_load_lds_dwordx4 v132, s[30:31]
	s_add_i32 m0, s34, 0x2000
	s_nop 0
	global_load_lds_dwordx4 v128, s[30:31]
	s_mov_b32 m0, s38
	s_nop 0
	global_load_lds_dwordx4 v134, s[60:61]
	s_mov_b32 m0, s39
	s_nop 0
	global_load_lds_dwordx4 v130, s[60:61]
	s_waitcnt vmcnt(8)
	s_waitcnt lgkmcnt(0)
	s_barrier
	s_setprio 1
	s_waitcnt lgkmcnt(0)
	v_mfma_f32_16x16x32_bf16 v[60:63], v[146:149], v[182:185], v[60:63]
	v_mfma_f32_16x16x32_bf16 v[56:59], v[154:157], v[182:185], v[56:59]
	v_mfma_f32_16x16x32_bf16 v[44:47], v[146:149], v[190:193], v[44:47]
	v_mfma_f32_16x16x32_bf16 v[40:43], v[154:157], v[190:193], v[40:43]
	v_mfma_f32_16x16x32_bf16 v[28:31], v[146:149], v[198:201], v[28:31]
	v_mfma_f32_16x16x32_bf16 v[24:27], v[154:157], v[198:201], v[24:27]
	v_mfma_f32_16x16x32_bf16 v[12:15], v[146:149], v[206:209], v[12:15]
	v_mfma_f32_16x16x32_bf16 v[8:11], v[154:157], v[206:209], v[8:11]
	v_mfma_f32_16x16x32_bf16 v[60:63], v[150:153], v[186:189], v[60:63]
	v_mfma_f32_16x16x32_bf16 v[56:59], v[158:161], v[186:189], v[56:59]
	v_mfma_f32_16x16x32_bf16 v[44:47], v[150:153], v[194:197], v[44:47]
	v_mfma_f32_16x16x32_bf16 v[40:43], v[158:161], v[194:197], v[40:43]
	v_mfma_f32_16x16x32_bf16 v[28:31], v[150:153], v[202:205], v[28:31]
	v_mfma_f32_16x16x32_bf16 v[24:27], v[158:161], v[202:205], v[24:27]
	v_mfma_f32_16x16x32_bf16 v[12:15], v[150:153], v[220:223], v[12:15]
	v_mfma_f32_16x16x32_bf16 v[8:11], v[158:161], v[220:223], v[8:11]
	s_setprio 0
	s_setprio 1
	v_mfma_f32_16x16x32_bf16 v[52:55], v[162:165], v[182:185], v[52:55]
	v_mfma_f32_16x16x32_bf16 v[48:51], v[170:173], v[182:185], v[48:51]
	v_mfma_f32_16x16x32_bf16 v[36:39], v[162:165], v[190:193], v[36:39]
	v_mfma_f32_16x16x32_bf16 v[32:35], v[170:173], v[190:193], v[32:35]
	v_mfma_f32_16x16x32_bf16 v[20:23], v[162:165], v[198:201], v[20:23]
	v_mfma_f32_16x16x32_bf16 v[16:19], v[170:173], v[198:201], v[16:19]
	v_mfma_f32_16x16x32_bf16 v[4:7], v[162:165], v[206:209], v[4:7]
	v_mfma_f32_16x16x32_bf16 v[0:3], v[170:173], v[206:209], v[0:3]
	v_mfma_f32_16x16x32_bf16 v[52:55], v[166:169], v[186:189], v[52:55]
	v_mfma_f32_16x16x32_bf16 v[48:51], v[178:181], v[186:189], v[48:51]
	v_mfma_f32_16x16x32_bf16 v[36:39], v[166:169], v[194:197], v[36:39]
	v_mfma_f32_16x16x32_bf16 v[32:35], v[178:181], v[194:197], v[32:35]
	v_mfma_f32_16x16x32_bf16 v[20:23], v[166:169], v[202:205], v[20:23]
	v_mfma_f32_16x16x32_bf16 v[16:19], v[178:181], v[202:205], v[16:19]
	v_mfma_f32_16x16x32_bf16 v[4:7], v[166:169], v[220:223], v[4:7]
	v_mfma_f32_16x16x32_bf16 v[0:3], v[178:181], v[220:223], v[0:3]
	s_setprio 0
	s_barrier
	s_add_i32 s47, s47, 2
	s_add_u32 s28, s28, 0x100
	s_addc_u32 s29, s29, 0
	s_add_u32 s45, s45, 0x100
	s_addc_u32 s46, s46, 0
	s_cmp_gt_u32 s47, 29
	s_cbranch_scc0 .LBB0_137
	s_and_b64 vcc, exec, s[10:11]
	s_cbranch_vccz .LBB0_140
	s_barrier

.LBB0_208:
	s_add_u32 s12, s0, 0xfff80080
	s_addc_u32 s13, s1, -1
	s_add_i32 s55, 0, 0x10000
	s_cmp_eq_u32 s53, 28
	s_cselect_b32 s15, s23, s13
	s_cselect_b32 s14, s26, s12
	s_cselect_b32 s13, s33, s51
	s_cselect_b32 s12, s45, s50
	s_add_i32 s60, 0, 0x14000
	v_add_u32_e32 v136, s55, v197
	v_add_u32_e32 v156, s60, v197
	ds_read_b128 v[120:123], v136
	ds_read_b128 v[124:127], v136 offset:1024
	ds_read_b128 v[132:135], v136 offset:2048
	ds_read_b128 v[136:139], v136 offset:3072
	ds_read_b128 v[140:143], v156
	ds_read_b128 v[144:147], v156 offset:1024
	ds_read_b128 v[152:155], v156 offset:2048
	ds_read_b128 v[156:159], v156 offset:3072
	s_add_i32 m0, s27, 0xc000
	ds_read_b128 v[160:163], v199
	ds_read_b128 v[178:181], v199 offset:1024
	ds_read_b128 v[182:185], v199 offset:2048
	ds_read_b128 v[186:189], v199 offset:3072
	ds_read_b128 v[190:193], v199 offset:4096
	ds_read_b128 v[200:203], v199 offset:5120
	ds_read_b128 v[204:207], v199 offset:6144
	ds_read_b128 v[220:223], v199 offset:7168
	global_load_lds_dwordx4 v170, s[0:1]
	s_add_i32 m0, s27, 0xe000
	s_nop 0
	global_load_lds_dwordx4 v172, s[0:1]
	s_waitcnt vmcnt(8)
	s_waitcnt lgkmcnt(0)
	s_barrier
	s_setprio 1
	s_waitcnt lgkmcnt(0)
	v_mfma_f32_16x16x32_bf16 v[148:151], v[120:123], v[160:163], v[148:151]
	v_mfma_f32_16x16x32_bf16 v[128:131], v[132:135], v[160:163], v[128:131]
	v_mfma_f32_16x16x32_bf16 v[116:119], v[120:123], v[182:185], v[116:119]
	v_mfma_f32_16x16x32_bf16 v[112:115], v[132:135], v[182:185], v[112:115]
	v_mfma_f32_16x16x32_bf16 v[108:111], v[120:123], v[190:193], v[108:111]
	v_mfma_f32_16x16x32_bf16 v[104:107], v[132:135], v[190:193], v[104:107]
	v_mfma_f32_16x16x32_bf16 v[100:103], v[120:123], v[204:207], v[100:103]
	v_mfma_f32_16x16x32_bf16 v[96:99], v[132:135], v[204:207], v[96:99]
	v_mfma_f32_16x16x32_bf16 v[148:151], v[124:127], v[178:181], v[148:151]
	v_mfma_f32_16x16x32_bf16 v[128:131], v[136:139], v[178:181], v[128:131]
	v_mfma_f32_16x16x32_bf16 v[116:119], v[124:127], v[186:189], v[116:119]
	v_mfma_f32_16x16x32_bf16 v[112:115], v[136:139], v[186:189], v[112:115]
	v_mfma_f32_16x16x32_bf16 v[108:111], v[124:127], v[200:203], v[108:111]
	v_mfma_f32_16x16x32_bf16 v[104:107], v[136:139], v[200:203], v[104:107]
	v_mfma_f32_16x16x32_bf16 v[100:103], v[124:127], v[220:223], v[100:103]
	v_mfma_f32_16x16x32_bf16 v[96:99], v[136:139], v[220:223], v[96:99]
	s_setprio 0
	s_setprio 1
	v_mfma_f32_16x16x32_bf16 v[60:63], v[140:143], v[160:163], v[60:63]
	v_mfma_f32_16x16x32_bf16 v[56:59], v[152:155], v[160:163], v[56:59]
	v_mfma_f32_16x16x32_bf16 v[52:55], v[140:143], v[182:185], v[52:55]
	v_mfma_f32_16x16x32_bf16 v[48:51], v[152:155], v[182:185], v[48:51]
	v_mfma_f32_16x16x32_bf16 v[44:47], v[140:143], v[190:193], v[44:47]
	v_mfma_f32_16x16x32_bf16 v[40:43], v[152:155], v[190:193], v[40:43]
	v_mfma_f32_16x16x32_bf16 v[36:39], v[140:143], v[204:207], v[36:39]
	v_mfma_f32_16x16x32_bf16 v[32:35], v[152:155], v[204:207], v[32:35]
	v_mfma_f32_16x16x32_bf16 v[60:63], v[144:147], v[178:181], v[60:63]
	v_mfma_f32_16x16x32_bf16 v[56:59], v[156:159], v[178:181], v[56:59]
	v_mfma_f32_16x16x32_bf16 v[52:55], v[144:147], v[186:189], v[52:55]
	v_mfma_f32_16x16x32_bf16 v[48:51], v[156:159], v[186:189], v[48:51]
	v_mfma_f32_16x16x32_bf16 v[44:47], v[144:147], v[200:203], v[44:47]
	v_mfma_f32_16x16x32_bf16 v[40:43], v[156:159], v[200:203], v[40:43]
	v_mfma_f32_16x16x32_bf16 v[36:39], v[144:147], v[220:223], v[36:39]
	v_mfma_f32_16x16x32_bf16 v[32:35], v[156:159], v[220:223], v[32:35]
	s_setprio 0
	s_barrier
	s_add_i32 s55, s55, s25
	s_mov_b32 m0, s55
	ds_read_b128 v[160:163], v199 offset:16384
	ds_read_b128 v[178:181], v199 offset:17408
	ds_read_b128 v[182:185], v199 offset:18432
	ds_read_b128 v[186:189], v199 offset:19456
	ds_read_b128 v[190:193], v199 offset:20480
	ds_read_b128 v[200:203], v199 offset:21504
	ds_read_b128 v[204:207], v199 offset:22528
	ds_read_b128 v[220:223], v199 offset:23552
	global_load_lds_dwordx4 v176, s[12:13]
	s_add_i32 m0, s55, 0x2000
	s_add_u32 s58, s12, 0x80000
	s_addc_u32 s59, s13, 0
	s_add_i32 s55, s60, s25
	global_load_lds_dwordx4 v164, s[12:13]
	s_mov_b32 m0, s55
	v_lshl_add_u64 v[224:225], s[14:15], 0, v[166:167]
	global_load_lds_dwordx4 v176, s[58:59]
	s_add_i32 m0, s55, 0x2000
	s_nop 0
	global_load_lds_dwordx4 v164, s[58:59]
	v_lshl_add_u64 v[208:209], s[14:15], 0, v[168:169]
	s_mov_b32 m0, s27
	s_nop 0
	global_load_lds_dwordx4 v168, s[14:15]
	s_mov_b32 m0, s28
	s_nop 0
	global_load_lds_dwordx4 v166, s[14:15]
	s_waitcnt vmcnt(8)
	s_waitcnt lgkmcnt(0)
	s_barrier
	s_setprio 1
	s_waitcnt lgkmcnt(0)
	v_mfma_f32_16x16x32_bf16 v[92:95], v[120:123], v[160:163], v[92:95]
	v_mfma_f32_16x16x32_bf16 v[88:91], v[132:135], v[160:163], v[88:91]
	v_mfma_f32_16x16x32_bf16 v[84:87], v[120:123], v[182:185], v[84:87]
	v_mfma_f32_16x16x32_bf16 v[80:83], v[132:135], v[182:185], v[80:83]
	v_mfma_f32_16x16x32_bf16 v[76:79], v[120:123], v[190:193], v[76:79]
	v_mfma_f32_16x16x32_bf16 v[72:75], v[132:135], v[190:193], v[72:75]
	v_mfma_f32_16x16x32_bf16 v[68:71], v[120:123], v[204:207], v[68:71]
	v_mfma_f32_16x16x32_bf16 v[64:67], v[132:135], v[204:207], v[64:67]
	v_mfma_f32_16x16x32_bf16 v[92:95], v[124:127], v[178:181], v[92:95]
	v_mfma_f32_16x16x32_bf16 v[88:91], v[136:139], v[178:181], v[88:91]
	v_mfma_f32_16x16x32_bf16 v[84:87], v[124:127], v[186:189], v[84:87]
	v_mfma_f32_16x16x32_bf16 v[80:83], v[136:139], v[186:189], v[80:83]
	v_mfma_f32_16x16x32_bf16 v[76:79], v[124:127], v[200:203], v[76:79]
	v_mfma_f32_16x16x32_bf16 v[72:75], v[136:139], v[200:203], v[72:75]
	v_mfma_f32_16x16x32_bf16 v[68:71], v[124:127], v[220:223], v[68:71]
	v_mfma_f32_16x16x32_bf16 v[64:67], v[136:139], v[220:223], v[64:67]
	s_setprio 0
	s_setprio 1
	v_mfma_f32_16x16x32_bf16 v[28:31], v[140:143], v[160:163], v[28:31]
	v_mfma_f32_16x16x32_bf16 v[24:27], v[152:155], v[160:163], v[24:27]
	v_mfma_f32_16x16x32_bf16 v[20:23], v[140:143], v[182:185], v[20:23]
	v_mfma_f32_16x16x32_bf16 v[16:19], v[152:155], v[182:185], v[16:19]
	v_mfma_f32_16x16x32_bf16 v[12:15], v[140:143], v[190:193], v[12:15]
	v_mfma_f32_16x16x32_bf16 v[8:11], v[152:155], v[190:193], v[8:11]
	v_mfma_f32_16x16x32_bf16 v[4:7], v[140:143], v[204:207], v[4:7]
	v_mfma_f32_16x16x32_bf16 v[0:3], v[152:155], v[204:207], v[0:3]
	v_mfma_f32_16x16x32_bf16 v[28:31], v[144:147], v[178:181], v[28:31]
	v_mfma_f32_16x16x32_bf16 v[24:27], v[156:159], v[178:181], v[24:27]
	v_mfma_f32_16x16x32_bf16 v[20:23], v[144:147], v[186:189], v[20:23]
	v_mfma_f32_16x16x32_bf16 v[16:19], v[156:159], v[186:189], v[16:19]
	v_mfma_f32_16x16x32_bf16 v[12:15], v[144:147], v[200:203], v[12:15]
	v_mfma_f32_16x16x32_bf16 v[8:11], v[156:159], v[200:203], v[8:11]
	v_mfma_f32_16x16x32_bf16 v[4:7], v[144:147], v[220:223], v[4:7]
	v_mfma_f32_16x16x32_bf16 v[0:3], v[156:159], v[220:223], v[0:3]
	s_setprio 0
	s_barrier
	s_add_i32 s55, 0, 0x18000
	s_add_i32 s58, 0, 0x1c000
	v_add_u32_e32 v136, s55, v197
	v_add_u32_e32 v156, s58, v197
	ds_read_b128 v[120:123], v136
	ds_read_b128 v[124:127], v136 offset:1024
	ds_read_b128 v[132:135], v136 offset:2048
	ds_read_b128 v[136:139], v136 offset:3072
	ds_read_b128 v[140:143], v156
	ds_read_b128 v[144:147], v156 offset:1024
	ds_read_b128 v[152:155], v156 offset:2048
	ds_read_b128 v[156:159], v156 offset:3072
	s_add_u32 s14, s14, 0x80000
	s_addc_u32 s15, s15, 0
	s_mov_b32 m0, s29
	ds_read_b128 v[160:163], v199 offset:32768
	ds_read_b128 v[178:181], v199 offset:33792
	ds_read_b128 v[182:185], v199 offset:34816
	ds_read_b128 v[186:189], v199 offset:35840
	ds_read_b128 v[190:193], v199 offset:36864
	ds_read_b128 v[200:203], v199 offset:37888
	ds_read_b128 v[204:207], v199 offset:38912
	ds_read_b128 v[220:223], v199 offset:39936
	global_load_lds_dwordx4 v168, s[14:15]
	s_mov_b32 m0, s38
	s_nop 0
	global_load_lds_dwordx4 v166, s[14:15]
	s_waitcnt vmcnt(8)
	s_waitcnt lgkmcnt(0)
	s_barrier
	s_setprio 1
	s_waitcnt lgkmcnt(0)
	v_mfma_f32_16x16x32_bf16 v[148:151], v[120:123], v[160:163], v[148:151]
	v_mfma_f32_16x16x32_bf16 v[128:131], v[132:135], v[160:163], v[128:131]
	v_mfma_f32_16x16x32_bf16 v[116:119], v[120:123], v[182:185], v[116:119]
	v_mfma_f32_16x16x32_bf16 v[112:115], v[132:135], v[182:185], v[112:115]
	v_mfma_f32_16x16x32_bf16 v[108:111], v[120:123], v[190:193], v[108:111]
	v_mfma_f32_16x16x32_bf16 v[104:107], v[132:135], v[190:193], v[104:107]
	v_mfma_f32_16x16x32_bf16 v[100:103], v[120:123], v[204:207], v[100:103]
	v_mfma_f32_16x16x32_bf16 v[96:99], v[132:135], v[204:207], v[96:99]
	v_mfma_f32_16x16x32_bf16 v[148:151], v[124:127], v[178:181], v[148:151]
	v_mfma_f32_16x16x32_bf16 v[128:131], v[136:139], v[178:181], v[128:131]
	v_mfma_f32_16x16x32_bf16 v[116:119], v[124:127], v[186:189], v[116:119]
	v_mfma_f32_16x16x32_bf16 v[112:115], v[136:139], v[186:189], v[112:115]
	v_mfma_f32_16x16x32_bf16 v[108:111], v[124:127], v[200:203], v[108:111]
	v_mfma_f32_16x16x32_bf16 v[104:107], v[136:139], v[200:203], v[104:107]
	v_mfma_f32_16x16x32_bf16 v[100:103], v[124:127], v[220:223], v[100:103]
	v_mfma_f32_16x16x32_bf16 v[96:99], v[136:139], v[220:223], v[96:99]
	s_setprio 0
	s_setprio 1
	v_mfma_f32_16x16x32_bf16 v[60:63], v[140:143], v[160:163], v[60:63]
	v_mfma_f32_16x16x32_bf16 v[56:59], v[152:155], v[160:163], v[56:59]
	v_mfma_f32_16x16x32_bf16 v[52:55], v[140:143], v[182:185], v[52:55]
	v_mfma_f32_16x16x32_bf16 v[48:51], v[152:155], v[182:185], v[48:51]
	v_mfma_f32_16x16x32_bf16 v[44:47], v[140:143], v[190:193], v[44:47]
	v_mfma_f32_16x16x32_bf16 v[40:43], v[152:155], v[190:193], v[40:43]
	v_mfma_f32_16x16x32_bf16 v[36:39], v[140:143], v[204:207], v[36:39]
	v_mfma_f32_16x16x32_bf16 v[32:35], v[152:155], v[204:207], v[32:35]
	v_mfma_f32_16x16x32_bf16 v[60:63], v[144:147], v[178:181], v[60:63]
	v_mfma_f32_16x16x32_bf16 v[56:59], v[156:159], v[178:181], v[56:59]
	v_mfma_f32_16x16x32_bf16 v[52:55], v[144:147], v[186:189], v[52:55]
	v_mfma_f32_16x16x32_bf16 v[48:51], v[156:159], v[186:189], v[48:51]
	v_mfma_f32_16x16x32_bf16 v[44:47], v[144:147], v[200:203], v[44:47]
	v_mfma_f32_16x16x32_bf16 v[40:43], v[156:159], v[200:203], v[40:43]
	v_mfma_f32_16x16x32_bf16 v[36:39], v[144:147], v[220:223], v[36:39]
	v_mfma_f32_16x16x32_bf16 v[32:35], v[156:159], v[220:223], v[32:35]
	s_setprio 0
	s_barrier
	s_add_i32 s14, s55, s25
	s_mov_b32 m0, s14
	ds_read_b128 v[160:163], v199 offset:49152
	ds_read_b128 v[178:181], v199 offset:50176
	ds_read_b128 v[182:185], v199 offset:51200
	ds_read_b128 v[186:189], v199 offset:52224
	ds_read_b128 v[190:193], v199 offset:53248
	ds_read_b128 v[200:203], v199 offset:54272
	ds_read_b128 v[204:207], v199 offset:55296
	ds_read_b128 v[220:223], v199 offset:56320
	s_add_u32 s98, s12, 0x80
	s_addc_u32 s99, s13, 0
	global_load_lds_dwordx4 v176, s[98:99]
	s_add_i32 m0, s14, 0x2000
	s_add_u32 s12, s12, 0x80080
	s_addc_u32 s13, s13, 0
	s_add_i32 s14, s58, s25
	s_add_u32 s98, s12, 0xfff80000
	s_addc_u32 s99, s13, -1
	global_load_lds_dwordx4 v164, s[98:99]
	s_mov_b32 m0, s14
	s_nop 0
	global_load_lds_dwordx4 v176, s[12:13]
	s_add_i32 m0, s14, 0x2000
	s_nop 0
	global_load_lds_dwordx4 v164, s[12:13]
	v_lshl_add_u64 v[174:175], v[208:209], 0, s[74:75]
	s_mov_b32 m0, s42
	s_nop 0
	global_load_lds_dwordx4 v[174:175], off
	v_lshl_add_u64 v[174:175], v[224:225], 0, s[74:75]
	s_mov_b32 m0, s43
	s_nop 0
	global_load_lds_dwordx4 v[174:175], off
	s_waitcnt vmcnt(8)
	s_waitcnt lgkmcnt(0)
	s_barrier
	s_setprio 1
	s_waitcnt lgkmcnt(0)
	v_mfma_f32_16x16x32_bf16 v[92:95], v[120:123], v[160:163], v[92:95]
	v_mfma_f32_16x16x32_bf16 v[88:91], v[132:135], v[160:163], v[88:91]
	v_mfma_f32_16x16x32_bf16 v[84:87], v[120:123], v[182:185], v[84:87]
	v_mfma_f32_16x16x32_bf16 v[80:83], v[132:135], v[182:185], v[80:83]
	v_mfma_f32_16x16x32_bf16 v[76:79], v[120:123], v[190:193], v[76:79]
	v_mfma_f32_16x16x32_bf16 v[72:75], v[132:135], v[190:193], v[72:75]
	v_mfma_f32_16x16x32_bf16 v[68:71], v[120:123], v[204:207], v[68:71]
	v_mfma_f32_16x16x32_bf16 v[64:67], v[132:135], v[204:207], v[64:67]
	v_mfma_f32_16x16x32_bf16 v[92:95], v[124:127], v[178:181], v[92:95]
	v_mfma_f32_16x16x32_bf16 v[88:91], v[136:139], v[178:181], v[88:91]
	v_mfma_f32_16x16x32_bf16 v[84:87], v[124:127], v[186:189], v[84:87]
	v_mfma_f32_16x16x32_bf16 v[80:83], v[136:139], v[186:189], v[80:83]
	v_mfma_f32_16x16x32_bf16 v[76:79], v[124:127], v[200:203], v[76:79]
	v_mfma_f32_16x16x32_bf16 v[72:75], v[136:139], v[200:203], v[72:75]
	v_mfma_f32_16x16x32_bf16 v[68:71], v[124:127], v[220:223], v[68:71]
	v_mfma_f32_16x16x32_bf16 v[64:67], v[136:139], v[220:223], v[64:67]
	s_setprio 0
	s_setprio 1
	v_mfma_f32_16x16x32_bf16 v[28:31], v[140:143], v[160:163], v[28:31]
	v_mfma_f32_16x16x32_bf16 v[24:27], v[152:155], v[160:163], v[24:27]
	v_mfma_f32_16x16x32_bf16 v[20:23], v[140:143], v[182:185], v[20:23]
	v_mfma_f32_16x16x32_bf16 v[16:19], v[152:155], v[182:185], v[16:19]
	v_mfma_f32_16x16x32_bf16 v[12:15], v[140:143], v[190:193], v[12:15]
	v_mfma_f32_16x16x32_bf16 v[8:11], v[152:155], v[190:193], v[8:11]
	v_mfma_f32_16x16x32_bf16 v[4:7], v[140:143], v[204:207], v[4:7]
	v_mfma_f32_16x16x32_bf16 v[0:3], v[152:155], v[204:207], v[0:3]
	v_mfma_f32_16x16x32_bf16 v[28:31], v[144:147], v[178:181], v[28:31]
	v_mfma_f32_16x16x32_bf16 v[24:27], v[156:159], v[178:181], v[24:27]
	v_mfma_f32_16x16x32_bf16 v[20:23], v[144:147], v[186:189], v[20:23]
	v_mfma_f32_16x16x32_bf16 v[16:19], v[156:159], v[186:189], v[16:19]
	v_mfma_f32_16x16x32_bf16 v[12:15], v[144:147], v[200:203], v[12:15]
	v_mfma_f32_16x16x32_bf16 v[8:11], v[156:159], v[200:203], v[8:11]
	v_mfma_f32_16x16x32_bf16 v[4:7], v[144:147], v[220:223], v[4:7]
	v_mfma_f32_16x16x32_bf16 v[0:3], v[156:159], v[220:223], v[0:3]
	s_setprio 0
	s_barrier
	s_add_i32 s53, s53, 2
	s_add_u32 s0, s0, 0x100
	s_addc_u32 s1, s1, 0
	s_add_u32 s50, s50, 0x100
	s_addc_u32 s51, s51, 0
	s_cmp_gt_u32 s53, 29
	s_cbranch_scc0 .LBB0_208
	s_and_b64 vcc, exec, s[40:41]
	s_cbranch_vccz .LBB0_211
	s_barrier

.LBB0_290:
	s_add_u32 s10, s8, 0xfff80080
	s_addc_u32 s11, s9, -1
	s_add_i32 s15, 0, 0x10000
	s_cmp_eq_u32 s14, 28
	s_cselect_b32 s13, s35, s11
	s_cselect_b32 s12, s34, s10
	s_cselect_b32 s11, s31, s3
	s_cselect_b32 s10, s30, s1
	s_add_i32 s22, 0, 0x14000
	v_add_u32_e32 v124, s15, v209
	v_add_u32_e32 v156, s22, v209
	ds_read_b128 v[112:115], v124
	ds_read_b128 v[116:119], v124 offset:1024
	ds_read_b128 v[120:123], v124 offset:2048
	ds_read_b128 v[124:127], v124 offset:3072
	ds_read_b128 v[136:139], v156
	ds_read_b128 v[140:143], v156 offset:1024
	ds_read_b128 v[152:155], v156 offset:2048
	ds_read_b128 v[156:159], v156 offset:3072
	s_add_i32 m0, s38, 0xc000
	ds_read_b128 v[160:163], v228
	ds_read_b128 v[164:167], v228 offset:1024
	ds_read_b128 v[168:171], v228 offset:2048
	ds_read_b128 v[172:175], v228 offset:3072
	ds_read_b128 v[230:233], v228 offset:4096
	ds_read_b128 v[234:237], v228 offset:5120
	ds_read_b128 v[238:241], v228 offset:6144
	ds_read_b128 v[242:245], v228 offset:7168
	global_load_lds_dwordx4 v202, s[8:9]
	s_add_i32 m0, s38, 0xe000
	s_nop 0
	global_load_lds_dwordx4 v204, s[8:9]
	s_waitcnt vmcnt(8)
	s_waitcnt lgkmcnt(0)
	s_barrier
	s_setprio 1
	s_waitcnt lgkmcnt(0)
	v_mfma_f32_16x16x32_bf16 v[148:151], v[112:115], v[160:163], v[148:151]
	v_mfma_f32_16x16x32_bf16 v[144:147], v[120:123], v[160:163], v[144:147]
	v_mfma_f32_16x16x32_bf16 v[108:111], v[112:115], v[168:171], v[108:111]
	v_mfma_f32_16x16x32_bf16 v[104:107], v[120:123], v[168:171], v[104:107]
	v_mfma_f32_16x16x32_bf16 v[92:95], v[112:115], v[230:233], v[92:95]
	v_mfma_f32_16x16x32_bf16 v[88:91], v[120:123], v[230:233], v[88:91]
	v_mfma_f32_16x16x32_bf16 v[76:79], v[112:115], v[238:241], v[76:79]
	v_mfma_f32_16x16x32_bf16 v[72:75], v[120:123], v[238:241], v[72:75]
	v_mfma_f32_16x16x32_bf16 v[148:151], v[116:119], v[164:167], v[148:151]
	v_mfma_f32_16x16x32_bf16 v[144:147], v[124:127], v[164:167], v[144:147]
	v_mfma_f32_16x16x32_bf16 v[108:111], v[116:119], v[172:175], v[108:111]
	v_mfma_f32_16x16x32_bf16 v[104:107], v[124:127], v[172:175], v[104:107]
	v_mfma_f32_16x16x32_bf16 v[92:95], v[116:119], v[234:237], v[92:95]
	v_mfma_f32_16x16x32_bf16 v[88:91], v[124:127], v[234:237], v[88:91]
	v_mfma_f32_16x16x32_bf16 v[76:79], v[116:119], v[242:245], v[76:79]
	v_mfma_f32_16x16x32_bf16 v[72:75], v[124:127], v[242:245], v[72:75]
	s_setprio 0
	s_setprio 1
	v_mfma_f32_16x16x32_bf16 v[132:135], v[136:139], v[160:163], v[132:135]
	v_mfma_f32_16x16x32_bf16 v[128:131], v[152:155], v[160:163], v[128:131]
	v_mfma_f32_16x16x32_bf16 v[100:103], v[136:139], v[168:171], v[100:103]
	v_mfma_f32_16x16x32_bf16 v[96:99], v[152:155], v[168:171], v[96:99]
	v_mfma_f32_16x16x32_bf16 v[84:87], v[136:139], v[230:233], v[84:87]
	v_mfma_f32_16x16x32_bf16 v[80:83], v[152:155], v[230:233], v[80:83]
	v_mfma_f32_16x16x32_bf16 v[68:71], v[136:139], v[238:241], v[68:71]
	v_mfma_f32_16x16x32_bf16 v[64:67], v[152:155], v[238:241], v[64:67]
	v_mfma_f32_16x16x32_bf16 v[132:135], v[140:143], v[164:167], v[132:135]
	v_mfma_f32_16x16x32_bf16 v[128:131], v[156:159], v[164:167], v[128:131]
	v_mfma_f32_16x16x32_bf16 v[100:103], v[140:143], v[172:175], v[100:103]
	v_mfma_f32_16x16x32_bf16 v[96:99], v[156:159], v[172:175], v[96:99]
	v_mfma_f32_16x16x32_bf16 v[84:87], v[140:143], v[234:237], v[84:87]
	v_mfma_f32_16x16x32_bf16 v[80:83], v[156:159], v[234:237], v[80:83]
	v_mfma_f32_16x16x32_bf16 v[68:71], v[140:143], v[242:245], v[68:71]
	v_mfma_f32_16x16x32_bf16 v[64:67], v[156:159], v[242:245], v[64:67]
	s_setprio 0
	s_barrier
	s_add_i32 s15, s15, s29
	s_mov_b32 m0, s15
	ds_read_b128 v[160:163], v228 offset:16384
	ds_read_b128 v[164:167], v228 offset:17408
	ds_read_b128 v[168:171], v228 offset:18432
	ds_read_b128 v[172:175], v228 offset:19456
	ds_read_b128 v[230:233], v228 offset:20480
	ds_read_b128 v[234:237], v228 offset:21504
	ds_read_b128 v[238:241], v228 offset:22528
	ds_read_b128 v[242:245], v228 offset:23552
	global_load_lds_dwordx4 v176, s[10:11]
	s_add_i32 m0, s15, 0x2000
	s_add_u32 s20, s10, 0x80000
	s_addc_u32 s21, s11, 0
	s_add_i32 s15, s22, s29
	global_load_lds_dwordx4 v182, s[10:11]
	s_mov_b32 m0, s15
	s_nop 0
	global_load_lds_dwordx4 v176, s[20:21]
	s_add_i32 m0, s15, 0x2000
	s_nop 0
	global_load_lds_dwordx4 v182, s[20:21]
	s_add_u32 s50, s12, 0x80
	s_addc_u32 s51, s13, 0
	s_mov_b32 m0, s38
	s_nop 0
	global_load_lds_dwordx4 v178, s[12:13]
	s_mov_b32 m0, s39
	s_nop 0
	global_load_lds_dwordx4 v180, s[12:13]
	s_waitcnt vmcnt(8)
	s_waitcnt lgkmcnt(0)
	s_barrier
	s_setprio 1
	s_waitcnt lgkmcnt(0)
	v_mfma_f32_16x16x32_bf16 v[60:63], v[112:115], v[160:163], v[60:63]
	v_mfma_f32_16x16x32_bf16 v[56:59], v[120:123], v[160:163], v[56:59]
	v_mfma_f32_16x16x32_bf16 v[44:47], v[112:115], v[168:171], v[44:47]
	v_mfma_f32_16x16x32_bf16 v[40:43], v[120:123], v[168:171], v[40:43]
	v_mfma_f32_16x16x32_bf16 v[28:31], v[112:115], v[230:233], v[28:31]
	v_mfma_f32_16x16x32_bf16 v[24:27], v[120:123], v[230:233], v[24:27]
	v_mfma_f32_16x16x32_bf16 v[12:15], v[112:115], v[238:241], v[12:15]
	v_mfma_f32_16x16x32_bf16 v[8:11], v[120:123], v[238:241], v[8:11]
	v_mfma_f32_16x16x32_bf16 v[60:63], v[116:119], v[164:167], v[60:63]
	v_mfma_f32_16x16x32_bf16 v[56:59], v[124:127], v[164:167], v[56:59]
	v_mfma_f32_16x16x32_bf16 v[44:47], v[116:119], v[172:175], v[44:47]
	v_mfma_f32_16x16x32_bf16 v[40:43], v[124:127], v[172:175], v[40:43]
	v_mfma_f32_16x16x32_bf16 v[28:31], v[116:119], v[234:237], v[28:31]
	v_mfma_f32_16x16x32_bf16 v[24:27], v[124:127], v[234:237], v[24:27]
	v_mfma_f32_16x16x32_bf16 v[12:15], v[116:119], v[242:245], v[12:15]
	v_mfma_f32_16x16x32_bf16 v[8:11], v[124:127], v[242:245], v[8:11]
	s_setprio 0
	s_setprio 1
	v_mfma_f32_16x16x32_bf16 v[52:55], v[136:139], v[160:163], v[52:55]
	v_mfma_f32_16x16x32_bf16 v[48:51], v[152:155], v[160:163], v[48:51]
	v_mfma_f32_16x16x32_bf16 v[36:39], v[136:139], v[168:171], v[36:39]
	v_mfma_f32_16x16x32_bf16 v[32:35], v[152:155], v[168:171], v[32:35]
	v_mfma_f32_16x16x32_bf16 v[20:23], v[136:139], v[230:233], v[20:23]
	v_mfma_f32_16x16x32_bf16 v[16:19], v[152:155], v[230:233], v[16:19]
	v_mfma_f32_16x16x32_bf16 v[4:7], v[136:139], v[238:241], v[4:7]
	v_mfma_f32_16x16x32_bf16 v[0:3], v[152:155], v[238:241], v[0:3]
	v_mfma_f32_16x16x32_bf16 v[52:55], v[140:143], v[164:167], v[52:55]
	v_mfma_f32_16x16x32_bf16 v[48:51], v[156:159], v[164:167], v[48:51]
	v_mfma_f32_16x16x32_bf16 v[36:39], v[140:143], v[172:175], v[36:39]
	v_mfma_f32_16x16x32_bf16 v[32:35], v[156:159], v[172:175], v[32:35]
	v_mfma_f32_16x16x32_bf16 v[20:23], v[140:143], v[234:237], v[20:23]
	v_mfma_f32_16x16x32_bf16 v[16:19], v[156:159], v[234:237], v[16:19]
	v_mfma_f32_16x16x32_bf16 v[4:7], v[140:143], v[242:245], v[4:7]
	v_mfma_f32_16x16x32_bf16 v[0:3], v[156:159], v[242:245], v[0:3]
	s_setprio 0
	s_barrier
	s_add_i32 s15, 0, 0x18000
	s_add_i32 s20, 0, 0x1c000
	v_add_u32_e32 v124, s15, v209
	v_add_u32_e32 v156, s20, v209
	ds_read_b128 v[112:115], v124
	ds_read_b128 v[116:119], v124 offset:1024
	ds_read_b128 v[120:123], v124 offset:2048
	ds_read_b128 v[124:127], v124 offset:3072
	ds_read_b128 v[136:139], v156
	ds_read_b128 v[140:143], v156 offset:1024
	ds_read_b128 v[152:155], v156 offset:2048
	ds_read_b128 v[156:159], v156 offset:3072
	s_add_u32 s12, s12, 0x80000
	s_addc_u32 s13, s13, 0
	s_mov_b32 m0, s42
	ds_read_b128 v[160:163], v228 offset:32768
	ds_read_b128 v[164:167], v228 offset:33792
	ds_read_b128 v[168:171], v228 offset:34816
	ds_read_b128 v[172:175], v228 offset:35840
	ds_read_b128 v[230:233], v228 offset:36864
	ds_read_b128 v[234:237], v228 offset:37888
	ds_read_b128 v[238:241], v228 offset:38912
	ds_read_b128 v[242:245], v228 offset:39936
	global_load_lds_dwordx4 v178, s[12:13]
	s_mov_b32 m0, s43
	s_nop 0
	global_load_lds_dwordx4 v180, s[12:13]
	s_waitcnt vmcnt(8)
	s_waitcnt lgkmcnt(0)
	s_barrier
	s_setprio 1
	s_waitcnt lgkmcnt(0)
	v_mfma_f32_16x16x32_bf16 v[148:151], v[112:115], v[160:163], v[148:151]
	v_mfma_f32_16x16x32_bf16 v[144:147], v[120:123], v[160:163], v[144:147]
	v_mfma_f32_16x16x32_bf16 v[108:111], v[112:115], v[168:171], v[108:111]
	v_mfma_f32_16x16x32_bf16 v[104:107], v[120:123], v[168:171], v[104:107]
	v_mfma_f32_16x16x32_bf16 v[92:95], v[112:115], v[230:233], v[92:95]
	v_mfma_f32_16x16x32_bf16 v[88:91], v[120:123], v[230:233], v[88:91]
	v_mfma_f32_16x16x32_bf16 v[76:79], v[112:115], v[238:241], v[76:79]
	v_mfma_f32_16x16x32_bf16 v[72:75], v[120:123], v[238:241], v[72:75]
	v_mfma_f32_16x16x32_bf16 v[148:151], v[116:119], v[164:167], v[148:151]
	v_mfma_f32_16x16x32_bf16 v[144:147], v[124:127], v[164:167], v[144:147]
	v_mfma_f32_16x16x32_bf16 v[108:111], v[116:119], v[172:175], v[108:111]
	v_mfma_f32_16x16x32_bf16 v[104:107], v[124:127], v[172:175], v[104:107]
	v_mfma_f32_16x16x32_bf16 v[92:95], v[116:119], v[234:237], v[92:95]
	v_mfma_f32_16x16x32_bf16 v[88:91], v[124:127], v[234:237], v[88:91]
	v_mfma_f32_16x16x32_bf16 v[76:79], v[116:119], v[242:245], v[76:79]
	v_mfma_f32_16x16x32_bf16 v[72:75], v[124:127], v[242:245], v[72:75]
	s_setprio 0
	s_setprio 1
	v_mfma_f32_16x16x32_bf16 v[132:135], v[136:139], v[160:163], v[132:135]
	v_mfma_f32_16x16x32_bf16 v[128:131], v[152:155], v[160:163], v[128:131]
	v_mfma_f32_16x16x32_bf16 v[100:103], v[136:139], v[168:171], v[100:103]
	v_mfma_f32_16x16x32_bf16 v[96:99], v[152:155], v[168:171], v[96:99]
	v_mfma_f32_16x16x32_bf16 v[84:87], v[136:139], v[230:233], v[84:87]
	v_mfma_f32_16x16x32_bf16 v[80:83], v[152:155], v[230:233], v[80:83]
	v_mfma_f32_16x16x32_bf16 v[68:71], v[136:139], v[238:241], v[68:71]
	v_mfma_f32_16x16x32_bf16 v[64:67], v[152:155], v[238:241], v[64:67]
	v_mfma_f32_16x16x32_bf16 v[132:135], v[140:143], v[164:167], v[132:135]
	v_mfma_f32_16x16x32_bf16 v[128:131], v[156:159], v[164:167], v[128:131]
	v_mfma_f32_16x16x32_bf16 v[100:103], v[140:143], v[172:175], v[100:103]
	v_mfma_f32_16x16x32_bf16 v[96:99], v[156:159], v[172:175], v[96:99]
	v_mfma_f32_16x16x32_bf16 v[84:87], v[140:143], v[234:237], v[84:87]
	v_mfma_f32_16x16x32_bf16 v[80:83], v[156:159], v[234:237], v[80:83]
	v_mfma_f32_16x16x32_bf16 v[68:71], v[140:143], v[242:245], v[68:71]
	v_mfma_f32_16x16x32_bf16 v[64:67], v[156:159], v[242:245], v[64:67]
	s_setprio 0
	s_barrier
	s_add_i32 s12, s15, s29
	s_mov_b32 m0, s12
	ds_read_b128 v[160:163], v228 offset:49152
	ds_read_b128 v[164:167], v228 offset:50176
	ds_read_b128 v[168:171], v228 offset:51200
	ds_read_b128 v[172:175], v228 offset:52224
	ds_read_b128 v[230:233], v228 offset:53248
	ds_read_b128 v[234:237], v228 offset:54272
	ds_read_b128 v[238:241], v228 offset:55296
	ds_read_b128 v[242:245], v228 offset:56320
	s_add_u32 s98, s10, 0x80
	s_addc_u32 s99, s11, 0
	global_load_lds_dwordx4 v176, s[98:99]
	s_add_i32 m0, s12, 0x2000
	s_add_u32 s10, s10, 0x80080
	s_addc_u32 s11, s11, 0
	s_add_i32 s12, s20, s29
	s_add_u32 s98, s10, 0xfff80000
	s_addc_u32 s99, s11, -1
	global_load_lds_dwordx4 v182, s[98:99]
	s_mov_b32 m0, s12
	s_nop 0
	global_load_lds_dwordx4 v176, s[10:11]
	s_add_i32 m0, s12, 0x2000
	s_nop 0
	global_load_lds_dwordx4 v182, s[10:11]
	s_mov_b32 m0, s58
	s_nop 0
	global_load_lds_dwordx4 v178, s[50:51]
	s_mov_b32 m0, s59
	s_nop 0
	global_load_lds_dwordx4 v180, s[50:51]
	s_waitcnt vmcnt(8)
	s_waitcnt lgkmcnt(0)
	s_barrier
	s_setprio 1
	s_waitcnt lgkmcnt(0)
	v_mfma_f32_16x16x32_bf16 v[60:63], v[112:115], v[160:163], v[60:63]
	v_mfma_f32_16x16x32_bf16 v[56:59], v[120:123], v[160:163], v[56:59]
	v_mfma_f32_16x16x32_bf16 v[44:47], v[112:115], v[168:171], v[44:47]
	v_mfma_f32_16x16x32_bf16 v[40:43], v[120:123], v[168:171], v[40:43]
	v_mfma_f32_16x16x32_bf16 v[28:31], v[112:115], v[230:233], v[28:31]
	v_mfma_f32_16x16x32_bf16 v[24:27], v[120:123], v[230:233], v[24:27]
	v_mfma_f32_16x16x32_bf16 v[12:15], v[112:115], v[238:241], v[12:15]
	v_mfma_f32_16x16x32_bf16 v[8:11], v[120:123], v[238:241], v[8:11]
	v_mfma_f32_16x16x32_bf16 v[60:63], v[116:119], v[164:167], v[60:63]
	v_mfma_f32_16x16x32_bf16 v[56:59], v[124:127], v[164:167], v[56:59]
	v_mfma_f32_16x16x32_bf16 v[44:47], v[116:119], v[172:175], v[44:47]
	v_mfma_f32_16x16x32_bf16 v[40:43], v[124:127], v[172:175], v[40:43]
	v_mfma_f32_16x16x32_bf16 v[28:31], v[116:119], v[234:237], v[28:31]
	v_mfma_f32_16x16x32_bf16 v[24:27], v[124:127], v[234:237], v[24:27]
	v_mfma_f32_16x16x32_bf16 v[12:15], v[116:119], v[242:245], v[12:15]
	v_mfma_f32_16x16x32_bf16 v[8:11], v[124:127], v[242:245], v[8:11]
	s_setprio 0
	s_setprio 1
	v_mfma_f32_16x16x32_bf16 v[52:55], v[136:139], v[160:163], v[52:55]
	v_mfma_f32_16x16x32_bf16 v[48:51], v[152:155], v[160:163], v[48:51]
	v_mfma_f32_16x16x32_bf16 v[36:39], v[136:139], v[168:171], v[36:39]
	v_mfma_f32_16x16x32_bf16 v[32:35], v[152:155], v[168:171], v[32:35]
	v_mfma_f32_16x16x32_bf16 v[20:23], v[136:139], v[230:233], v[20:23]
	v_mfma_f32_16x16x32_bf16 v[16:19], v[152:155], v[230:233], v[16:19]
	v_mfma_f32_16x16x32_bf16 v[4:7], v[136:139], v[238:241], v[4:7]
	v_mfma_f32_16x16x32_bf16 v[0:3], v[152:155], v[238:241], v[0:3]
	v_mfma_f32_16x16x32_bf16 v[52:55], v[140:143], v[164:167], v[52:55]
	v_mfma_f32_16x16x32_bf16 v[48:51], v[156:159], v[164:167], v[48:51]
	v_mfma_f32_16x16x32_bf16 v[36:39], v[140:143], v[172:175], v[36:39]
	v_mfma_f32_16x16x32_bf16 v[32:35], v[156:159], v[172:175], v[32:35]
	v_mfma_f32_16x16x32_bf16 v[20:23], v[140:143], v[234:237], v[20:23]
	v_mfma_f32_16x16x32_bf16 v[16:19], v[156:159], v[234:237], v[16:19]
	v_mfma_f32_16x16x32_bf16 v[4:7], v[140:143], v[242:245], v[4:7]
	v_mfma_f32_16x16x32_bf16 v[0:3], v[156:159], v[242:245], v[0:3]
	s_setprio 0
	s_barrier
	s_add_i32 s14, s14, 2
	s_add_u32 s8, s8, 0x100
	s_addc_u32 s9, s9, 0
	s_add_u32 s1, s1, 0x100
	s_addc_u32 s3, s3, 0
	s_cmp_gt_u32 s14, 29
	s_cbranch_scc0 .LBB0_290
	s_and_b64 vcc, exec, s[56:57]
	s_cbranch_vccz .LBB0_293
	s_barrier

.LBB0_420:
	s_add_u32 s6, s4, 0xfff80080
	s_addc_u32 s7, s5, -1
	s_add_i32 s37, 0, 0x10000
	s_cmp_eq_u32 s36, 28
	s_cselect_b32 s9, s15, s7
	s_cselect_b32 s8, s30, s6
	v_add_u32_e32 v129, s37, v149
	s_cselect_b32 s7, s19, s35
	s_cselect_b32 s6, s31, s34
	s_add_i32 s56, 0, 0x14000
	ds_read_b128 v[130:133], v129
	ds_read_b128 v[134:137], v129 offset:1024
	ds_read_b128 v[154:157], v129 offset:2048
	ds_read_b128 v[162:165], v129 offset:3072
	v_add_u32_e32 v129, s56, v149
	ds_read_b128 v[166:169], v129
	ds_read_b128 v[170:173], v129 offset:1024
	ds_read_b128 v[178:181], v129 offset:2048
	ds_read_b128 v[182:185], v129 offset:3072
	s_add_i32 m0, s38, 0xc000
	ds_read_b128 v[186:189], v161
	ds_read_b128 v[190:193], v161 offset:1024
	ds_read_b128 v[194:197], v161 offset:2048
	ds_read_b128 v[198:201], v161 offset:3072
	ds_read_b128 v[202:205], v161 offset:4096
	ds_read_b128 v[206:209], v161 offset:5120
	ds_read_b128 v[220:223], v161 offset:6144
	ds_read_b128 v[224:227], v161 offset:7168
	global_load_lds_dwordx4 v150, s[4:5]
	s_add_i32 m0, s38, 0xe000
	s_nop 0
	global_load_lds_dwordx4 v152, s[4:5]
	s_waitcnt vmcnt(8)
	s_waitcnt lgkmcnt(0)
	s_barrier
	s_setprio 1
	s_waitcnt lgkmcnt(0)
	v_mfma_f32_16x16x32_bf16 v[124:127], v[130:133], v[186:189], v[124:127]
	v_mfma_f32_16x16x32_bf16 v[120:123], v[154:157], v[186:189], v[120:123]
	v_mfma_f32_16x16x32_bf16 v[108:111], v[130:133], v[194:197], v[108:111]
	v_mfma_f32_16x16x32_bf16 v[104:107], v[154:157], v[194:197], v[104:107]
	v_mfma_f32_16x16x32_bf16 v[92:95], v[130:133], v[202:205], v[92:95]
	v_mfma_f32_16x16x32_bf16 v[88:91], v[154:157], v[202:205], v[88:91]
	v_mfma_f32_16x16x32_bf16 v[76:79], v[130:133], v[220:223], v[76:79]
	v_mfma_f32_16x16x32_bf16 v[72:75], v[154:157], v[220:223], v[72:75]
	v_mfma_f32_16x16x32_bf16 v[124:127], v[134:137], v[190:193], v[124:127]
	v_mfma_f32_16x16x32_bf16 v[120:123], v[162:165], v[190:193], v[120:123]
	v_mfma_f32_16x16x32_bf16 v[108:111], v[134:137], v[198:201], v[108:111]
	v_mfma_f32_16x16x32_bf16 v[104:107], v[162:165], v[198:201], v[104:107]
	v_mfma_f32_16x16x32_bf16 v[92:95], v[134:137], v[206:209], v[92:95]
	v_mfma_f32_16x16x32_bf16 v[88:91], v[162:165], v[206:209], v[88:91]
	v_mfma_f32_16x16x32_bf16 v[76:79], v[134:137], v[224:227], v[76:79]
	v_mfma_f32_16x16x32_bf16 v[72:75], v[162:165], v[224:227], v[72:75]
	s_setprio 0
	s_setprio 1
	v_mfma_f32_16x16x32_bf16 v[116:119], v[166:169], v[186:189], v[116:119]
	v_mfma_f32_16x16x32_bf16 v[112:115], v[178:181], v[186:189], v[112:115]
	v_mfma_f32_16x16x32_bf16 v[100:103], v[166:169], v[194:197], v[100:103]
	v_mfma_f32_16x16x32_bf16 v[96:99], v[178:181], v[194:197], v[96:99]
	v_mfma_f32_16x16x32_bf16 v[84:87], v[166:169], v[202:205], v[84:87]
	v_mfma_f32_16x16x32_bf16 v[80:83], v[178:181], v[202:205], v[80:83]
	v_mfma_f32_16x16x32_bf16 v[68:71], v[166:169], v[220:223], v[68:71]
	v_mfma_f32_16x16x32_bf16 v[64:67], v[178:181], v[220:223], v[64:67]
	v_mfma_f32_16x16x32_bf16 v[116:119], v[170:173], v[190:193], v[116:119]
	v_mfma_f32_16x16x32_bf16 v[112:115], v[182:185], v[190:193], v[112:115]
	v_mfma_f32_16x16x32_bf16 v[100:103], v[170:173], v[198:201], v[100:103]
	v_mfma_f32_16x16x32_bf16 v[96:99], v[182:185], v[198:201], v[96:99]
	v_mfma_f32_16x16x32_bf16 v[84:87], v[170:173], v[206:209], v[84:87]
	v_mfma_f32_16x16x32_bf16 v[80:83], v[182:185], v[206:209], v[80:83]
	v_mfma_f32_16x16x32_bf16 v[68:71], v[170:173], v[224:227], v[68:71]
	v_mfma_f32_16x16x32_bf16 v[64:67], v[182:185], v[224:227], v[64:67]
	s_setprio 0
	s_barrier
	s_add_i32 s37, s37, s33
	s_mov_b32 m0, s37
	ds_read_b128 v[186:189], v161 offset:16384
	ds_read_b128 v[190:193], v161 offset:17408
	ds_read_b128 v[194:197], v161 offset:18432
	ds_read_b128 v[198:201], v161 offset:19456
	ds_read_b128 v[202:205], v161 offset:20480
	ds_read_b128 v[206:209], v161 offset:21504
	ds_read_b128 v[220:223], v161 offset:22528
	ds_read_b128 v[224:227], v161 offset:23552
	global_load_lds_dwordx4 v142, s[6:7]
	s_add_i32 m0, s37, 0x2000
	s_add_u32 s54, s6, 0x80000
	s_addc_u32 s55, s7, 0
	s_add_i32 s37, s56, s33
	global_load_lds_dwordx4 v138, s[6:7]
	s_mov_b32 m0, s37
	s_nop 0
	global_load_lds_dwordx4 v142, s[54:55]
	s_add_i32 m0, s37, 0x2000
	s_nop 0
	global_load_lds_dwordx4 v138, s[54:55]
	s_add_u32 s60, s8, 0x80
	s_addc_u32 s61, s9, 0
	s_mov_b32 m0, s38
	s_nop 0
	global_load_lds_dwordx4 v144, s[8:9]
	s_mov_b32 m0, s39
	s_nop 0
	global_load_lds_dwordx4 v140, s[8:9]
	s_waitcnt vmcnt(8)
	s_waitcnt lgkmcnt(0)
	s_barrier
	s_setprio 1
	s_waitcnt lgkmcnt(0)
	v_mfma_f32_16x16x32_bf16 v[60:63], v[130:133], v[186:189], v[60:63]
	v_mfma_f32_16x16x32_bf16 v[56:59], v[154:157], v[186:189], v[56:59]
	v_mfma_f32_16x16x32_bf16 v[44:47], v[130:133], v[194:197], v[44:47]
	v_mfma_f32_16x16x32_bf16 v[40:43], v[154:157], v[194:197], v[40:43]
	v_mfma_f32_16x16x32_bf16 v[28:31], v[130:133], v[202:205], v[28:31]
	v_mfma_f32_16x16x32_bf16 v[24:27], v[154:157], v[202:205], v[24:27]
	v_mfma_f32_16x16x32_bf16 v[12:15], v[130:133], v[220:223], v[12:15]
	v_mfma_f32_16x16x32_bf16 v[8:11], v[154:157], v[220:223], v[8:11]
	v_mfma_f32_16x16x32_bf16 v[60:63], v[134:137], v[190:193], v[60:63]
	v_mfma_f32_16x16x32_bf16 v[56:59], v[162:165], v[190:193], v[56:59]
	v_mfma_f32_16x16x32_bf16 v[44:47], v[134:137], v[198:201], v[44:47]
	v_mfma_f32_16x16x32_bf16 v[40:43], v[162:165], v[198:201], v[40:43]
	v_mfma_f32_16x16x32_bf16 v[28:31], v[134:137], v[206:209], v[28:31]
	v_mfma_f32_16x16x32_bf16 v[24:27], v[162:165], v[206:209], v[24:27]
	v_mfma_f32_16x16x32_bf16 v[12:15], v[134:137], v[224:227], v[12:15]
	v_mfma_f32_16x16x32_bf16 v[8:11], v[162:165], v[224:227], v[8:11]
	s_setprio 0
	s_setprio 1
	v_mfma_f32_16x16x32_bf16 v[52:55], v[166:169], v[186:189], v[52:55]
	v_mfma_f32_16x16x32_bf16 v[48:51], v[178:181], v[186:189], v[48:51]
	v_mfma_f32_16x16x32_bf16 v[36:39], v[166:169], v[194:197], v[36:39]
	v_mfma_f32_16x16x32_bf16 v[32:35], v[178:181], v[194:197], v[32:35]
	v_mfma_f32_16x16x32_bf16 v[20:23], v[166:169], v[202:205], v[20:23]
	v_mfma_f32_16x16x32_bf16 v[16:19], v[178:181], v[202:205], v[16:19]
	v_mfma_f32_16x16x32_bf16 v[4:7], v[166:169], v[220:223], v[4:7]
	v_mfma_f32_16x16x32_bf16 v[0:3], v[178:181], v[220:223], v[0:3]
	v_mfma_f32_16x16x32_bf16 v[52:55], v[170:173], v[190:193], v[52:55]
	v_mfma_f32_16x16x32_bf16 v[48:51], v[182:185], v[190:193], v[48:51]
	v_mfma_f32_16x16x32_bf16 v[36:39], v[170:173], v[198:201], v[36:39]
	v_mfma_f32_16x16x32_bf16 v[32:35], v[182:185], v[198:201], v[32:35]
	v_mfma_f32_16x16x32_bf16 v[20:23], v[170:173], v[206:209], v[20:23]
	v_mfma_f32_16x16x32_bf16 v[16:19], v[182:185], v[206:209], v[16:19]
	v_mfma_f32_16x16x32_bf16 v[4:7], v[170:173], v[224:227], v[4:7]
	v_mfma_f32_16x16x32_bf16 v[0:3], v[182:185], v[224:227], v[0:3]
	s_setprio 0
	s_barrier
	s_add_i32 s37, 0, 0x18000
	v_add_u32_e32 v129, s37, v149
	s_add_i32 s54, 0, 0x1c000
	ds_read_b128 v[130:133], v129
	ds_read_b128 v[134:137], v129 offset:1024
	ds_read_b128 v[154:157], v129 offset:2048
	ds_read_b128 v[162:165], v129 offset:3072
	v_add_u32_e32 v129, s54, v149
	ds_read_b128 v[166:169], v129
	ds_read_b128 v[170:173], v129 offset:1024
	ds_read_b128 v[178:181], v129 offset:2048
	ds_read_b128 v[182:185], v129 offset:3072
	s_add_u32 s8, s8, 0x80000
	s_addc_u32 s9, s9, 0
	s_mov_b32 m0, s40
	ds_read_b128 v[186:189], v161 offset:32768
	ds_read_b128 v[190:193], v161 offset:33792
	ds_read_b128 v[194:197], v161 offset:34816
	ds_read_b128 v[198:201], v161 offset:35840
	ds_read_b128 v[202:205], v161 offset:36864
	ds_read_b128 v[206:209], v161 offset:37888
	ds_read_b128 v[220:223], v161 offset:38912
	ds_read_b128 v[224:227], v161 offset:39936
	global_load_lds_dwordx4 v144, s[8:9]
	s_mov_b32 m0, s41
	s_nop 0
	global_load_lds_dwordx4 v140, s[8:9]
	s_waitcnt vmcnt(8)
	s_waitcnt lgkmcnt(0)
	s_barrier
	s_setprio 1
	s_waitcnt lgkmcnt(0)
	v_mfma_f32_16x16x32_bf16 v[124:127], v[130:133], v[186:189], v[124:127]
	v_mfma_f32_16x16x32_bf16 v[120:123], v[154:157], v[186:189], v[120:123]
	v_mfma_f32_16x16x32_bf16 v[108:111], v[130:133], v[194:197], v[108:111]
	v_mfma_f32_16x16x32_bf16 v[104:107], v[154:157], v[194:197], v[104:107]
	v_mfma_f32_16x16x32_bf16 v[92:95], v[130:133], v[202:205], v[92:95]
	v_mfma_f32_16x16x32_bf16 v[88:91], v[154:157], v[202:205], v[88:91]
	v_mfma_f32_16x16x32_bf16 v[76:79], v[130:133], v[220:223], v[76:79]
	v_mfma_f32_16x16x32_bf16 v[72:75], v[154:157], v[220:223], v[72:75]
	v_mfma_f32_16x16x32_bf16 v[124:127], v[134:137], v[190:193], v[124:127]
	v_mfma_f32_16x16x32_bf16 v[120:123], v[162:165], v[190:193], v[120:123]
	v_mfma_f32_16x16x32_bf16 v[108:111], v[134:137], v[198:201], v[108:111]
	v_mfma_f32_16x16x32_bf16 v[104:107], v[162:165], v[198:201], v[104:107]
	v_mfma_f32_16x16x32_bf16 v[92:95], v[134:137], v[206:209], v[92:95]
	v_mfma_f32_16x16x32_bf16 v[88:91], v[162:165], v[206:209], v[88:91]
	v_mfma_f32_16x16x32_bf16 v[76:79], v[134:137], v[224:227], v[76:79]
	v_mfma_f32_16x16x32_bf16 v[72:75], v[162:165], v[224:227], v[72:75]
	s_setprio 0
	s_setprio 1
	v_mfma_f32_16x16x32_bf16 v[116:119], v[166:169], v[186:189], v[116:119]
	v_mfma_f32_16x16x32_bf16 v[112:115], v[178:181], v[186:189], v[112:115]
	v_mfma_f32_16x16x32_bf16 v[100:103], v[166:169], v[194:197], v[100:103]
	v_mfma_f32_16x16x32_bf16 v[96:99], v[178:181], v[194:197], v[96:99]
	v_mfma_f32_16x16x32_bf16 v[84:87], v[166:169], v[202:205], v[84:87]
	v_mfma_f32_16x16x32_bf16 v[80:83], v[178:181], v[202:205], v[80:83]
	v_mfma_f32_16x16x32_bf16 v[68:71], v[166:169], v[220:223], v[68:71]
	v_mfma_f32_16x16x32_bf16 v[64:67], v[178:181], v[220:223], v[64:67]
	v_mfma_f32_16x16x32_bf16 v[116:119], v[170:173], v[190:193], v[116:119]
	v_mfma_f32_16x16x32_bf16 v[112:115], v[182:185], v[190:193], v[112:115]
	v_mfma_f32_16x16x32_bf16 v[100:103], v[170:173], v[198:201], v[100:103]
	v_mfma_f32_16x16x32_bf16 v[96:99], v[182:185], v[198:201], v[96:99]
	v_mfma_f32_16x16x32_bf16 v[84:87], v[170:173], v[206:209], v[84:87]
	v_mfma_f32_16x16x32_bf16 v[80:83], v[182:185], v[206:209], v[80:83]
	v_mfma_f32_16x16x32_bf16 v[68:71], v[170:173], v[224:227], v[68:71]
	v_mfma_f32_16x16x32_bf16 v[64:67], v[182:185], v[224:227], v[64:67]
	s_setprio 0
	s_barrier
	s_add_i32 s8, s37, s33
	s_mov_b32 m0, s8
	ds_read_b128 v[186:189], v161 offset:49152
	ds_read_b128 v[190:193], v161 offset:50176
	ds_read_b128 v[194:197], v161 offset:51200
	ds_read_b128 v[198:201], v161 offset:52224
	ds_read_b128 v[202:205], v161 offset:53248
	ds_read_b128 v[206:209], v161 offset:54272
	ds_read_b128 v[220:223], v161 offset:55296
	ds_read_b128 v[224:227], v161 offset:56320
	s_add_u32 s98, s6, 0x80
	s_addc_u32 s99, s7, 0
	global_load_lds_dwordx4 v142, s[98:99]
	s_add_i32 m0, s8, 0x2000
	s_add_u32 s6, s6, 0x80080
	s_addc_u32 s7, s7, 0
	s_add_i32 s8, s54, s33
	s_add_u32 s98, s6, 0xfff80000
	s_addc_u32 s99, s7, -1
	global_load_lds_dwordx4 v138, s[98:99]
	s_mov_b32 m0, s8
	s_nop 0
	global_load_lds_dwordx4 v142, s[6:7]
	s_add_i32 m0, s8, 0x2000
	s_nop 0
	global_load_lds_dwordx4 v138, s[6:7]
	s_mov_b32 m0, s49
	s_nop 0
	global_load_lds_dwordx4 v144, s[60:61]
	s_mov_b32 m0, s50
	s_nop 0
	global_load_lds_dwordx4 v140, s[60:61]
	s_waitcnt vmcnt(8)
	s_waitcnt lgkmcnt(0)
	s_barrier
	s_setprio 1
	s_waitcnt lgkmcnt(0)
	v_mfma_f32_16x16x32_bf16 v[60:63], v[130:133], v[186:189], v[60:63]
	v_mfma_f32_16x16x32_bf16 v[56:59], v[154:157], v[186:189], v[56:59]
	v_mfma_f32_16x16x32_bf16 v[44:47], v[130:133], v[194:197], v[44:47]
	v_mfma_f32_16x16x32_bf16 v[40:43], v[154:157], v[194:197], v[40:43]
	v_mfma_f32_16x16x32_bf16 v[28:31], v[130:133], v[202:205], v[28:31]
	v_mfma_f32_16x16x32_bf16 v[24:27], v[154:157], v[202:205], v[24:27]
	v_mfma_f32_16x16x32_bf16 v[12:15], v[130:133], v[220:223], v[12:15]
	v_mfma_f32_16x16x32_bf16 v[8:11], v[154:157], v[220:223], v[8:11]
	v_mfma_f32_16x16x32_bf16 v[60:63], v[134:137], v[190:193], v[60:63]
	v_mfma_f32_16x16x32_bf16 v[56:59], v[162:165], v[190:193], v[56:59]
	v_mfma_f32_16x16x32_bf16 v[44:47], v[134:137], v[198:201], v[44:47]
	v_mfma_f32_16x16x32_bf16 v[40:43], v[162:165], v[198:201], v[40:43]
	v_mfma_f32_16x16x32_bf16 v[28:31], v[134:137], v[206:209], v[28:31]
	v_mfma_f32_16x16x32_bf16 v[24:27], v[162:165], v[206:209], v[24:27]
	v_mfma_f32_16x16x32_bf16 v[12:15], v[134:137], v[224:227], v[12:15]
	v_mfma_f32_16x16x32_bf16 v[8:11], v[162:165], v[224:227], v[8:11]
	s_setprio 0
	s_setprio 1
	v_mfma_f32_16x16x32_bf16 v[52:55], v[166:169], v[186:189], v[52:55]
	v_mfma_f32_16x16x32_bf16 v[48:51], v[178:181], v[186:189], v[48:51]
	v_mfma_f32_16x16x32_bf16 v[36:39], v[166:169], v[194:197], v[36:39]
	v_mfma_f32_16x16x32_bf16 v[32:35], v[178:181], v[194:197], v[32:35]
	v_mfma_f32_16x16x32_bf16 v[20:23], v[166:169], v[202:205], v[20:23]
	v_mfma_f32_16x16x32_bf16 v[16:19], v[178:181], v[202:205], v[16:19]
	v_mfma_f32_16x16x32_bf16 v[4:7], v[166:169], v[220:223], v[4:7]
	v_mfma_f32_16x16x32_bf16 v[0:3], v[178:181], v[220:223], v[0:3]
	v_mfma_f32_16x16x32_bf16 v[52:55], v[170:173], v[190:193], v[52:55]
	v_mfma_f32_16x16x32_bf16 v[48:51], v[182:185], v[190:193], v[48:51]
	v_mfma_f32_16x16x32_bf16 v[36:39], v[170:173], v[198:201], v[36:39]
	v_mfma_f32_16x16x32_bf16 v[32:35], v[182:185], v[198:201], v[32:35]
	v_mfma_f32_16x16x32_bf16 v[20:23], v[170:173], v[206:209], v[20:23]
	v_mfma_f32_16x16x32_bf16 v[16:19], v[182:185], v[206:209], v[16:19]
	v_mfma_f32_16x16x32_bf16 v[4:7], v[170:173], v[224:227], v[4:7]
	v_mfma_f32_16x16x32_bf16 v[0:3], v[182:185], v[224:227], v[0:3]
	s_setprio 0
	s_barrier
	s_add_i32 s36, s36, 2
	s_add_u32 s4, s4, 0x100
	s_addc_u32 s5, s5, 0
	s_add_u32 s34, s34, 0x100
	s_addc_u32 s35, s35, 0
	s_cmp_gt_u32 s36, 29
	s_cbranch_scc0 .LBB0_420
	s_and_b64 vcc, exec, s[12:13]
	s_cbranch_vccz .LBB0_423
	s_barrier

.LBB0_524:
	s_add_u32 s37, s24, s36
	s_addc_u32 s42, s25, 0
	s_add_u32 s40, s37, 0x100
	s_addc_u32 s41, s42, 0
	s_and_b64 s[38:39], s[34:35], exec
	s_cselect_b32 s39, s13, s41
	s_cselect_b32 s38, s15, s40
	s_add_u32 s36, s22, s36
	s_addc_u32 s40, s23, 0
	s_add_u32 s36, s36, 0x100
	s_addc_u32 s40, s40, 0
	s_add_i32 s65, 0, 0x10000
	s_and_b64 s[34:35], s[34:35], exec
	s_cselect_b32 s41, s17, s40
	s_cselect_b32 s40, s16, s36
	s_add_i32 s35, 0, 0x14000
	s_add_u32 s46, s37, 0x10080
	s_addc_u32 s47, s42, 0
	s_add_i32 s64, s65, s26
	s_add_i32 m0, s27, 0xc000
	s_add_i32 s67, s27, 0xe000
	s_add_i32 s60, s64, 0x2000
	v_add_u32_e32 v139, s65, v137
	s_add_u32 s42, s40, 0xc0000
	ds_read_b128 v[140:143], v139
	ds_read_b128 v[144:147], v139 offset:1024
	ds_read_b128 v[148:151], v139 offset:2048
	ds_read_b128 v[152:155], v139 offset:3072
	v_add_u32_e32 v139, s35, v137
	s_addc_u32 s43, s41, 0
	s_add_i32 s63, s35, s26
	ds_read_b128 v[156:159], v139
	ds_read_b128 v[160:163], v139 offset:1024
	ds_read_b128 v[164:167], v139 offset:2048
	ds_read_b128 v[168:171], v139 offset:3072
	s_add_i32 s61, s63, 0x2000
	s_add_i32 s59, 0, 0x18000
	s_add_i32 s58, 0, 0x1c000
	s_add_u32 s36, s38, 0x10000
	s_addc_u32 s37, s39, 0
	s_add_i32 s57, s59, s26
	s_add_i32 s56, s57, 0x2000
	s_add_u32 s34, s40, 0xc0080
	s_addc_u32 s35, s41, 0
	s_add_i32 s66, s58, s26
	s_add_i32 s65, s66, 0x2000
	ds_read_b128 v[172:175], v138
	ds_read_b128 v[178:181], v138 offset:1024
	ds_read_b128 v[182:185], v138 offset:2048
	ds_read_b128 v[186:189], v138 offset:3072
	ds_read_b128 v[190:193], v138 offset:4096
	ds_read_b128 v[194:197], v138 offset:5120
	ds_read_b128 v[198:201], v138 offset:6144
	ds_read_b128 v[202:205], v138 offset:7168
	global_load_lds_dwordx4 v134, s[46:47]
	s_mov_b32 m0, s67
	s_nop 0
	global_load_lds_dwordx4 v130, s[46:47]
	s_waitcnt vmcnt(8)
	s_waitcnt lgkmcnt(0)
	s_barrier
	s_setprio 1
	s_waitcnt lgkmcnt(0)
	v_mfma_f32_16x16x32_bf16 v[124:127], v[140:143], v[172:175], v[124:127]
	v_mfma_f32_16x16x32_bf16 v[120:123], v[148:151], v[172:175], v[120:123]
	v_mfma_f32_16x16x32_bf16 v[116:119], v[140:143], v[182:185], v[116:119]
	v_mfma_f32_16x16x32_bf16 v[112:115], v[148:151], v[182:185], v[112:115]
	v_mfma_f32_16x16x32_bf16 v[100:103], v[140:143], v[190:193], v[100:103]
	v_mfma_f32_16x16x32_bf16 v[96:99], v[148:151], v[190:193], v[96:99]
	v_mfma_f32_16x16x32_bf16 v[84:87], v[140:143], v[198:201], v[84:87]
	v_mfma_f32_16x16x32_bf16 v[80:83], v[148:151], v[198:201], v[80:83]
	v_mfma_f32_16x16x32_bf16 v[124:127], v[144:147], v[178:181], v[124:127]
	v_mfma_f32_16x16x32_bf16 v[120:123], v[152:155], v[178:181], v[120:123]
	v_mfma_f32_16x16x32_bf16 v[116:119], v[144:147], v[186:189], v[116:119]
	v_mfma_f32_16x16x32_bf16 v[112:115], v[152:155], v[186:189], v[112:115]
	v_mfma_f32_16x16x32_bf16 v[100:103], v[144:147], v[194:197], v[100:103]
	v_mfma_f32_16x16x32_bf16 v[96:99], v[152:155], v[194:197], v[96:99]
	v_mfma_f32_16x16x32_bf16 v[84:87], v[144:147], v[202:205], v[84:87]
	v_mfma_f32_16x16x32_bf16 v[80:83], v[152:155], v[202:205], v[80:83]
	s_setprio 0
	s_setprio 1
	v_mfma_f32_16x16x32_bf16 v[108:111], v[156:159], v[172:175], v[108:111]
	v_mfma_f32_16x16x32_bf16 v[104:107], v[164:167], v[172:175], v[104:107]
	v_mfma_f32_16x16x32_bf16 v[92:95], v[156:159], v[182:185], v[92:95]
	v_mfma_f32_16x16x32_bf16 v[88:91], v[164:167], v[182:185], v[88:91]
	v_mfma_f32_16x16x32_bf16 v[76:79], v[156:159], v[190:193], v[76:79]
	v_mfma_f32_16x16x32_bf16 v[72:75], v[164:167], v[190:193], v[72:75]
	v_mfma_f32_16x16x32_bf16 v[68:71], v[156:159], v[198:201], v[68:71]
	v_mfma_f32_16x16x32_bf16 v[64:67], v[164:167], v[198:201], v[64:67]
	v_mfma_f32_16x16x32_bf16 v[108:111], v[160:163], v[178:181], v[108:111]
	v_mfma_f32_16x16x32_bf16 v[104:107], v[168:171], v[178:181], v[104:107]
	v_mfma_f32_16x16x32_bf16 v[92:95], v[160:163], v[186:189], v[92:95]
	v_mfma_f32_16x16x32_bf16 v[88:91], v[168:171], v[186:189], v[88:91]
	v_mfma_f32_16x16x32_bf16 v[76:79], v[160:163], v[194:197], v[76:79]
	v_mfma_f32_16x16x32_bf16 v[72:75], v[168:171], v[194:197], v[72:75]
	v_mfma_f32_16x16x32_bf16 v[68:71], v[160:163], v[202:205], v[68:71]
	v_mfma_f32_16x16x32_bf16 v[64:67], v[168:171], v[202:205], v[64:67]
	s_setprio 0
	s_barrier
	s_mov_b32 m0, s64
	ds_read_b128 v[172:175], v138 offset:16384
	ds_read_b128 v[178:181], v138 offset:17408
	ds_read_b128 v[182:185], v138 offset:18432
	ds_read_b128 v[186:189], v138 offset:19456
	ds_read_b128 v[190:193], v138 offset:20480
	ds_read_b128 v[194:197], v138 offset:21504
	ds_read_b128 v[198:201], v138 offset:22528
	ds_read_b128 v[202:205], v138 offset:23552
	global_load_lds_dwordx4 v132, s[40:41]
	s_mov_b32 m0, s60
	s_nop 0
	global_load_lds_dwordx4 v128, s[40:41]
	s_mov_b32 m0, s63
	s_nop 0
	global_load_lds_dwordx4 v132, s[42:43]
	s_mov_b32 m0, s61
	s_nop 0
	global_load_lds_dwordx4 v128, s[42:43]
	s_mov_b32 m0, s27
	s_nop 0
	global_load_lds_dwordx4 v134, s[38:39]
	s_mov_b32 m0, s33
	s_nop 0
	global_load_lds_dwordx4 v130, s[38:39]
	s_waitcnt vmcnt(8)
	s_waitcnt lgkmcnt(0)
	s_barrier
	s_setprio 1
	s_waitcnt lgkmcnt(0)
	v_mfma_f32_16x16x32_bf16 v[60:63], v[140:143], v[172:175], v[60:63]
	v_mfma_f32_16x16x32_bf16 v[56:59], v[148:151], v[172:175], v[56:59]
	v_mfma_f32_16x16x32_bf16 v[52:55], v[140:143], v[182:185], v[52:55]
	v_mfma_f32_16x16x32_bf16 v[48:51], v[148:151], v[182:185], v[48:51]
	v_mfma_f32_16x16x32_bf16 v[36:39], v[140:143], v[190:193], v[36:39]
	v_mfma_f32_16x16x32_bf16 v[32:35], v[148:151], v[190:193], v[32:35]
	v_mfma_f32_16x16x32_bf16 v[20:23], v[140:143], v[198:201], v[20:23]
	v_mfma_f32_16x16x32_bf16 v[16:19], v[148:151], v[198:201], v[16:19]
	v_mfma_f32_16x16x32_bf16 v[60:63], v[144:147], v[178:181], v[60:63]
	v_mfma_f32_16x16x32_bf16 v[56:59], v[152:155], v[178:181], v[56:59]
	v_mfma_f32_16x16x32_bf16 v[52:55], v[144:147], v[186:189], v[52:55]
	v_mfma_f32_16x16x32_bf16 v[48:51], v[152:155], v[186:189], v[48:51]
	v_mfma_f32_16x16x32_bf16 v[36:39], v[144:147], v[194:197], v[36:39]
	v_mfma_f32_16x16x32_bf16 v[32:35], v[152:155], v[194:197], v[32:35]
	v_mfma_f32_16x16x32_bf16 v[20:23], v[144:147], v[202:205], v[20:23]
	v_mfma_f32_16x16x32_bf16 v[16:19], v[152:155], v[202:205], v[16:19]
	s_setprio 0
	s_setprio 1
	v_mfma_f32_16x16x32_bf16 v[44:47], v[156:159], v[172:175], v[44:47]
	v_mfma_f32_16x16x32_bf16 v[40:43], v[164:167], v[172:175], v[40:43]
	v_mfma_f32_16x16x32_bf16 v[28:31], v[156:159], v[182:185], v[28:31]
	v_mfma_f32_16x16x32_bf16 v[24:27], v[164:167], v[182:185], v[24:27]
	v_mfma_f32_16x16x32_bf16 v[12:15], v[156:159], v[190:193], v[12:15]
	v_mfma_f32_16x16x32_bf16 v[8:11], v[164:167], v[190:193], v[8:11]
	v_mfma_f32_16x16x32_bf16 v[4:7], v[156:159], v[198:201], v[4:7]
	v_mfma_f32_16x16x32_bf16 v[0:3], v[164:167], v[198:201], v[0:3]
	v_mfma_f32_16x16x32_bf16 v[44:47], v[160:163], v[178:181], v[44:47]
	v_mfma_f32_16x16x32_bf16 v[40:43], v[168:171], v[178:181], v[40:43]
	v_mfma_f32_16x16x32_bf16 v[28:31], v[160:163], v[186:189], v[28:31]
	v_mfma_f32_16x16x32_bf16 v[24:27], v[168:171], v[186:189], v[24:27]
	v_mfma_f32_16x16x32_bf16 v[12:15], v[160:163], v[194:197], v[12:15]
	v_mfma_f32_16x16x32_bf16 v[8:11], v[168:171], v[194:197], v[8:11]
	v_mfma_f32_16x16x32_bf16 v[4:7], v[160:163], v[202:205], v[4:7]
	v_mfma_f32_16x16x32_bf16 v[0:3], v[168:171], v[202:205], v[0:3]
	s_setprio 0
	s_barrier
	v_add_u32_e32 v139, s59, v137
	ds_read_b128 v[140:143], v139
	ds_read_b128 v[144:147], v139 offset:1024
	ds_read_b128 v[148:151], v139 offset:2048
	ds_read_b128 v[152:155], v139 offset:3072
	v_add_u32_e32 v139, s58, v137
	ds_read_b128 v[156:159], v139
	ds_read_b128 v[160:163], v139 offset:1024
	ds_read_b128 v[164:167], v139 offset:2048
	ds_read_b128 v[168:171], v139 offset:3072
	s_mov_b32 m0, s44
	ds_read_b128 v[172:175], v138 offset:32768
	ds_read_b128 v[178:181], v138 offset:33792
	ds_read_b128 v[182:185], v138 offset:34816
	ds_read_b128 v[186:189], v138 offset:35840
	ds_read_b128 v[190:193], v138 offset:36864
	ds_read_b128 v[194:197], v138 offset:37888
	ds_read_b128 v[198:201], v138 offset:38912
	ds_read_b128 v[202:205], v138 offset:39936
	global_load_lds_dwordx4 v134, s[36:37]
	s_mov_b32 m0, s45
	s_nop 0
	global_load_lds_dwordx4 v130, s[36:37]
	s_waitcnt vmcnt(8)
	s_waitcnt lgkmcnt(0)
	s_barrier
	s_setprio 1
	s_waitcnt lgkmcnt(0)
	v_mfma_f32_16x16x32_bf16 v[124:127], v[140:143], v[172:175], v[124:127]
	v_mfma_f32_16x16x32_bf16 v[120:123], v[148:151], v[172:175], v[120:123]
	v_mfma_f32_16x16x32_bf16 v[116:119], v[140:143], v[182:185], v[116:119]
	v_mfma_f32_16x16x32_bf16 v[112:115], v[148:151], v[182:185], v[112:115]
	v_mfma_f32_16x16x32_bf16 v[100:103], v[140:143], v[190:193], v[100:103]
	v_mfma_f32_16x16x32_bf16 v[96:99], v[148:151], v[190:193], v[96:99]
	v_mfma_f32_16x16x32_bf16 v[84:87], v[140:143], v[198:201], v[84:87]
	v_mfma_f32_16x16x32_bf16 v[80:83], v[148:151], v[198:201], v[80:83]
	v_mfma_f32_16x16x32_bf16 v[124:127], v[144:147], v[178:181], v[124:127]
	v_mfma_f32_16x16x32_bf16 v[120:123], v[152:155], v[178:181], v[120:123]
	v_mfma_f32_16x16x32_bf16 v[116:119], v[144:147], v[186:189], v[116:119]
	v_mfma_f32_16x16x32_bf16 v[112:115], v[152:155], v[186:189], v[112:115]
	v_mfma_f32_16x16x32_bf16 v[100:103], v[144:147], v[194:197], v[100:103]
	v_mfma_f32_16x16x32_bf16 v[96:99], v[152:155], v[194:197], v[96:99]
	v_mfma_f32_16x16x32_bf16 v[84:87], v[144:147], v[202:205], v[84:87]
	v_mfma_f32_16x16x32_bf16 v[80:83], v[152:155], v[202:205], v[80:83]
	s_setprio 0
	s_setprio 1
	v_mfma_f32_16x16x32_bf16 v[108:111], v[156:159], v[172:175], v[108:111]
	v_mfma_f32_16x16x32_bf16 v[104:107], v[164:167], v[172:175], v[104:107]
	v_mfma_f32_16x16x32_bf16 v[92:95], v[156:159], v[182:185], v[92:95]
	v_mfma_f32_16x16x32_bf16 v[88:91], v[164:167], v[182:185], v[88:91]
	v_mfma_f32_16x16x32_bf16 v[76:79], v[156:159], v[190:193], v[76:79]
	v_mfma_f32_16x16x32_bf16 v[72:75], v[164:167], v[190:193], v[72:75]
	v_mfma_f32_16x16x32_bf16 v[68:71], v[156:159], v[198:201], v[68:71]
	v_mfma_f32_16x16x32_bf16 v[64:67], v[164:167], v[198:201], v[64:67]
	v_mfma_f32_16x16x32_bf16 v[108:111], v[160:163], v[178:181], v[108:111]
	v_mfma_f32_16x16x32_bf16 v[104:107], v[168:171], v[178:181], v[104:107]
	v_mfma_f32_16x16x32_bf16 v[92:95], v[160:163], v[186:189], v[92:95]
	v_mfma_f32_16x16x32_bf16 v[88:91], v[168:171], v[186:189], v[88:91]
	v_mfma_f32_16x16x32_bf16 v[76:79], v[160:163], v[194:197], v[76:79]
	v_mfma_f32_16x16x32_bf16 v[72:75], v[168:171], v[194:197], v[72:75]
	v_mfma_f32_16x16x32_bf16 v[68:71], v[160:163], v[202:205], v[68:71]
	v_mfma_f32_16x16x32_bf16 v[64:67], v[168:171], v[202:205], v[64:67]
	s_setprio 0
	s_barrier
	s_mov_b32 m0, s57
	ds_read_b128 v[172:175], v138 offset:49152
	ds_read_b128 v[178:181], v138 offset:50176
	ds_read_b128 v[182:185], v138 offset:51200
	ds_read_b128 v[186:189], v138 offset:52224
	ds_read_b128 v[190:193], v138 offset:53248
	ds_read_b128 v[194:197], v138 offset:54272
	ds_read_b128 v[198:201], v138 offset:55296
	ds_read_b128 v[202:205], v138 offset:56320
	s_add_u32 s98, s40, 0x80
	s_addc_u32 s99, s41, 0
	global_load_lds_dwordx4 v132, s[98:99]
	s_mov_b32 m0, s56
	s_nop 0
	s_add_u32 s98, s40, 0x80
	s_addc_u32 s99, s41, 0
	global_load_lds_dwordx4 v128, s[98:99]
	s_mov_b32 m0, s66
	s_nop 0
	global_load_lds_dwordx4 v132, s[34:35]
	s_mov_b32 m0, s65
	s_nop 0
	global_load_lds_dwordx4 v128, s[34:35]
	s_mov_b32 m0, s50
	s_nop 0
	s_add_u32 s98, s38, 0x80
	s_addc_u32 s99, s39, 0
	global_load_lds_dwordx4 v134, s[98:99]
	s_mov_b32 m0, s51
	s_nop 0
	s_add_u32 s98, s38, 0x80
	s_addc_u32 s99, s39, 0
	global_load_lds_dwordx4 v130, s[98:99]
	s_waitcnt vmcnt(8)
	s_waitcnt lgkmcnt(0)
	s_barrier
	s_setprio 1
	s_waitcnt lgkmcnt(0)
	v_mfma_f32_16x16x32_bf16 v[60:63], v[140:143], v[172:175], v[60:63]
	v_mfma_f32_16x16x32_bf16 v[56:59], v[148:151], v[172:175], v[56:59]
	v_mfma_f32_16x16x32_bf16 v[52:55], v[140:143], v[182:185], v[52:55]
	v_mfma_f32_16x16x32_bf16 v[48:51], v[148:151], v[182:185], v[48:51]
	v_mfma_f32_16x16x32_bf16 v[36:39], v[140:143], v[190:193], v[36:39]
	v_mfma_f32_16x16x32_bf16 v[32:35], v[148:151], v[190:193], v[32:35]
	v_mfma_f32_16x16x32_bf16 v[20:23], v[140:143], v[198:201], v[20:23]
	v_mfma_f32_16x16x32_bf16 v[16:19], v[148:151], v[198:201], v[16:19]
	v_mfma_f32_16x16x32_bf16 v[60:63], v[144:147], v[178:181], v[60:63]
	v_mfma_f32_16x16x32_bf16 v[56:59], v[152:155], v[178:181], v[56:59]
	v_mfma_f32_16x16x32_bf16 v[52:55], v[144:147], v[186:189], v[52:55]
	v_mfma_f32_16x16x32_bf16 v[48:51], v[152:155], v[186:189], v[48:51]
	v_mfma_f32_16x16x32_bf16 v[36:39], v[144:147], v[194:197], v[36:39]
	v_mfma_f32_16x16x32_bf16 v[32:35], v[152:155], v[194:197], v[32:35]
	v_mfma_f32_16x16x32_bf16 v[20:23], v[144:147], v[202:205], v[20:23]
	v_mfma_f32_16x16x32_bf16 v[16:19], v[152:155], v[202:205], v[16:19]
	s_setprio 0
	s_setprio 1
	v_mfma_f32_16x16x32_bf16 v[44:47], v[156:159], v[172:175], v[44:47]
	v_mfma_f32_16x16x32_bf16 v[40:43], v[164:167], v[172:175], v[40:43]
	v_mfma_f32_16x16x32_bf16 v[28:31], v[156:159], v[182:185], v[28:31]
	v_mfma_f32_16x16x32_bf16 v[24:27], v[164:167], v[182:185], v[24:27]
	v_mfma_f32_16x16x32_bf16 v[12:15], v[156:159], v[190:193], v[12:15]
	v_mfma_f32_16x16x32_bf16 v[8:11], v[164:167], v[190:193], v[8:11]
	v_mfma_f32_16x16x32_bf16 v[4:7], v[156:159], v[198:201], v[4:7]
	v_mfma_f32_16x16x32_bf16 v[0:3], v[164:167], v[198:201], v[0:3]
	v_mfma_f32_16x16x32_bf16 v[44:47], v[160:163], v[178:181], v[44:47]
	v_mfma_f32_16x16x32_bf16 v[40:43], v[168:171], v[178:181], v[40:43]
	v_mfma_f32_16x16x32_bf16 v[28:31], v[160:163], v[186:189], v[28:31]
	v_mfma_f32_16x16x32_bf16 v[24:27], v[168:171], v[186:189], v[24:27]
	v_mfma_f32_16x16x32_bf16 v[12:15], v[160:163], v[194:197], v[12:15]
	v_mfma_f32_16x16x32_bf16 v[8:11], v[168:171], v[194:197], v[8:11]
	v_mfma_f32_16x16x32_bf16 v[4:7], v[160:163], v[202:205], v[4:7]
	v_mfma_f32_16x16x32_bf16 v[0:3], v[168:171], v[202:205], v[0:3]
	s_setprio 0
	s_barrier
	s_movk_i32 s36, 0x100
	s_andn2_b64 vcc, exec, s[30:31]
	s_mov_b64 s[34:35], -1
	s_mov_b64 s[30:31], 0
	s_cbranch_vccz .LBB0_524
	s_and_b64 vcc, exec, s[8:9]
	s_cbranch_vccz .LBB0_527
	s_barrier

.LBB0_730:
	s_add_u32 s16, s18, 0xffe00080
	s_addc_u32 s17, s19, -1
	s_add_i32 s42, 0, 0x10000
	s_cmpk_eq_i32 s41, 0x7c
	s_cselect_b32 s25, s15, s17
	s_cselect_b32 s24, s14, s16
	s_cselect_b32 s23, s13, s40
	s_cselect_b32 s22, s12, s7
	s_add_i32 s16, 0, 0x14000
	v_add_u32_e32 v156, s42, v142
	v_add_u32_e32 v172, s16, v142
	ds_read_b128 v[144:147], v156
	ds_read_b128 v[148:151], v156 offset:1024
	ds_read_b128 v[152:155], v156 offset:2048
	ds_read_b128 v[156:159], v156 offset:3072
	ds_read_b128 v[160:163], v172
	ds_read_b128 v[164:167], v172 offset:1024
	ds_read_b128 v[168:171], v172 offset:2048
	ds_read_b128 v[172:175], v172 offset:3072
	s_add_i32 m0, s31, 0xc000
	ds_read_b128 v[178:181], v143
	ds_read_b128 v[182:185], v143 offset:1024
	ds_read_b128 v[186:189], v143 offset:2048
	ds_read_b128 v[190:193], v143 offset:3072
	ds_read_b128 v[194:197], v143 offset:4096
	ds_read_b128 v[198:201], v143 offset:5120
	ds_read_b128 v[202:205], v143 offset:6144
	ds_read_b128 v[206:209], v143 offset:7168
	global_load_lds_dwordx4 v138, s[18:19]
	s_add_i32 m0, s31, 0xe000
	s_nop 0
	global_load_lds_dwordx4 v140, s[18:19]
	s_waitcnt vmcnt(8)
	s_waitcnt lgkmcnt(0)
	s_barrier
	s_setprio 1
	s_waitcnt lgkmcnt(0)
	v_mfma_f32_16x16x32_bf16 v[124:127], v[144:147], v[178:181], v[124:127]
	v_mfma_f32_16x16x32_bf16 v[120:123], v[152:155], v[178:181], v[120:123]
	v_mfma_f32_16x16x32_bf16 v[116:119], v[144:147], v[186:189], v[116:119]
	v_mfma_f32_16x16x32_bf16 v[112:115], v[152:155], v[186:189], v[112:115]
	v_mfma_f32_16x16x32_bf16 v[100:103], v[144:147], v[194:197], v[100:103]
	v_mfma_f32_16x16x32_bf16 v[96:99], v[152:155], v[194:197], v[96:99]
	v_mfma_f32_16x16x32_bf16 v[84:87], v[144:147], v[202:205], v[84:87]
	v_mfma_f32_16x16x32_bf16 v[80:83], v[152:155], v[202:205], v[80:83]
	v_mfma_f32_16x16x32_bf16 v[124:127], v[148:151], v[182:185], v[124:127]
	v_mfma_f32_16x16x32_bf16 v[120:123], v[156:159], v[182:185], v[120:123]
	v_mfma_f32_16x16x32_bf16 v[116:119], v[148:151], v[190:193], v[116:119]
	v_mfma_f32_16x16x32_bf16 v[112:115], v[156:159], v[190:193], v[112:115]
	v_mfma_f32_16x16x32_bf16 v[100:103], v[148:151], v[198:201], v[100:103]
	v_mfma_f32_16x16x32_bf16 v[96:99], v[156:159], v[198:201], v[96:99]
	v_mfma_f32_16x16x32_bf16 v[84:87], v[148:151], v[206:209], v[84:87]
	v_mfma_f32_16x16x32_bf16 v[80:83], v[156:159], v[206:209], v[80:83]
	s_setprio 0
	s_setprio 1
	v_mfma_f32_16x16x32_bf16 v[108:111], v[160:163], v[178:181], v[108:111]
	v_mfma_f32_16x16x32_bf16 v[104:107], v[168:171], v[178:181], v[104:107]
	v_mfma_f32_16x16x32_bf16 v[92:95], v[160:163], v[186:189], v[92:95]
	v_mfma_f32_16x16x32_bf16 v[88:91], v[168:171], v[186:189], v[88:91]
	v_mfma_f32_16x16x32_bf16 v[76:79], v[160:163], v[194:197], v[76:79]
	v_mfma_f32_16x16x32_bf16 v[72:75], v[168:171], v[194:197], v[72:75]
	v_mfma_f32_16x16x32_bf16 v[68:71], v[160:163], v[202:205], v[68:71]
	v_mfma_f32_16x16x32_bf16 v[64:67], v[168:171], v[202:205], v[64:67]
	v_mfma_f32_16x16x32_bf16 v[108:111], v[164:167], v[182:185], v[108:111]
	v_mfma_f32_16x16x32_bf16 v[104:107], v[172:175], v[182:185], v[104:107]
	v_mfma_f32_16x16x32_bf16 v[92:95], v[164:167], v[190:193], v[92:95]
	v_mfma_f32_16x16x32_bf16 v[88:91], v[172:175], v[190:193], v[88:91]
	v_mfma_f32_16x16x32_bf16 v[76:79], v[164:167], v[198:201], v[76:79]
	v_mfma_f32_16x16x32_bf16 v[72:75], v[172:175], v[198:201], v[72:75]
	v_mfma_f32_16x16x32_bf16 v[68:71], v[164:167], v[206:209], v[68:71]
	v_mfma_f32_16x16x32_bf16 v[64:67], v[172:175], v[206:209], v[64:67]
	s_setprio 0
	s_barrier
	s_add_i32 s17, s42, s28
	s_mov_b32 m0, s17
	ds_read_b128 v[178:181], v143 offset:16384
	ds_read_b128 v[182:185], v143 offset:17408
	ds_read_b128 v[186:189], v143 offset:18432
	ds_read_b128 v[190:193], v143 offset:19456
	ds_read_b128 v[194:197], v143 offset:20480
	ds_read_b128 v[198:201], v143 offset:21504
	ds_read_b128 v[202:205], v143 offset:22528
	ds_read_b128 v[206:209], v143 offset:23552
	global_load_lds_dwordx4 v132, s[22:23]
	s_add_i32 m0, s17, 0x2000
	s_add_u32 s42, s22, 0x400000
	s_addc_u32 s43, s23, 0
	s_add_i32 s16, s16, s28
	global_load_lds_dwordx4 v128, s[22:23]
	s_mov_b32 m0, s16
	s_nop 0
	global_load_lds_dwordx4 v132, s[42:43]
	s_add_i32 m0, s16, 0x2000
	s_nop 0
	global_load_lds_dwordx4 v128, s[42:43]
	s_mov_b32 m0, s31
	s_nop 0
	global_load_lds_dwordx4 v134, s[24:25]
	s_mov_b32 m0, s8
	s_nop 0
	global_load_lds_dwordx4 v130, s[24:25]
	s_waitcnt vmcnt(8)
	s_waitcnt lgkmcnt(0)
	s_barrier
	s_setprio 1
	s_waitcnt lgkmcnt(0)
	v_mfma_f32_16x16x32_bf16 v[60:63], v[144:147], v[178:181], v[60:63]
	v_mfma_f32_16x16x32_bf16 v[56:59], v[152:155], v[178:181], v[56:59]
	v_mfma_f32_16x16x32_bf16 v[52:55], v[144:147], v[186:189], v[52:55]
	v_mfma_f32_16x16x32_bf16 v[48:51], v[152:155], v[186:189], v[48:51]
	v_mfma_f32_16x16x32_bf16 v[36:39], v[144:147], v[194:197], v[36:39]
	v_mfma_f32_16x16x32_bf16 v[32:35], v[152:155], v[194:197], v[32:35]
	v_mfma_f32_16x16x32_bf16 v[20:23], v[144:147], v[202:205], v[20:23]
	v_mfma_f32_16x16x32_bf16 v[16:19], v[152:155], v[202:205], v[16:19]
	v_mfma_f32_16x16x32_bf16 v[60:63], v[148:151], v[182:185], v[60:63]
	v_mfma_f32_16x16x32_bf16 v[56:59], v[156:159], v[182:185], v[56:59]
	v_mfma_f32_16x16x32_bf16 v[52:55], v[148:151], v[190:193], v[52:55]
	v_mfma_f32_16x16x32_bf16 v[48:51], v[156:159], v[190:193], v[48:51]
	v_mfma_f32_16x16x32_bf16 v[36:39], v[148:151], v[198:201], v[36:39]
	v_mfma_f32_16x16x32_bf16 v[32:35], v[156:159], v[198:201], v[32:35]
	v_mfma_f32_16x16x32_bf16 v[20:23], v[148:151], v[206:209], v[20:23]
	v_mfma_f32_16x16x32_bf16 v[16:19], v[156:159], v[206:209], v[16:19]
	s_setprio 0
	s_setprio 1
	v_mfma_f32_16x16x32_bf16 v[44:47], v[160:163], v[178:181], v[44:47]
	v_mfma_f32_16x16x32_bf16 v[40:43], v[168:171], v[178:181], v[40:43]
	v_mfma_f32_16x16x32_bf16 v[28:31], v[160:163], v[186:189], v[28:31]
	v_mfma_f32_16x16x32_bf16 v[24:27], v[168:171], v[186:189], v[24:27]
	v_mfma_f32_16x16x32_bf16 v[12:15], v[160:163], v[194:197], v[12:15]
	v_mfma_f32_16x16x32_bf16 v[8:11], v[168:171], v[194:197], v[8:11]
	v_mfma_f32_16x16x32_bf16 v[4:7], v[160:163], v[202:205], v[4:7]
	v_mfma_f32_16x16x32_bf16 v[0:3], v[168:171], v[202:205], v[0:3]
	v_mfma_f32_16x16x32_bf16 v[44:47], v[164:167], v[182:185], v[44:47]
	v_mfma_f32_16x16x32_bf16 v[40:43], v[172:175], v[182:185], v[40:43]
	v_mfma_f32_16x16x32_bf16 v[28:31], v[164:167], v[190:193], v[28:31]
	v_mfma_f32_16x16x32_bf16 v[24:27], v[172:175], v[190:193], v[24:27]
	v_mfma_f32_16x16x32_bf16 v[12:15], v[164:167], v[198:201], v[12:15]
	v_mfma_f32_16x16x32_bf16 v[8:11], v[172:175], v[198:201], v[8:11]
	v_mfma_f32_16x16x32_bf16 v[4:7], v[164:167], v[206:209], v[4:7]
	v_mfma_f32_16x16x32_bf16 v[0:3], v[172:175], v[206:209], v[0:3]
	s_setprio 0
	s_barrier
	s_add_i32 s16, 0, 0x18000
	s_add_i32 s17, 0, 0x1c000
	v_add_u32_e32 v156, s16, v142
	v_add_u32_e32 v172, s17, v142
	ds_read_b128 v[144:147], v156
	ds_read_b128 v[148:151], v156 offset:1024
	ds_read_b128 v[152:155], v156 offset:2048
	ds_read_b128 v[156:159], v156 offset:3072
	ds_read_b128 v[160:163], v172
	ds_read_b128 v[164:167], v172 offset:1024
	ds_read_b128 v[168:171], v172 offset:2048
	ds_read_b128 v[172:175], v172 offset:3072
	s_add_u32 s24, s24, 0x200000
	s_addc_u32 s25, s25, 0
	s_mov_b32 m0, s9
	ds_read_b128 v[178:181], v143 offset:32768
	ds_read_b128 v[182:185], v143 offset:33792
	ds_read_b128 v[186:189], v143 offset:34816
	ds_read_b128 v[190:193], v143 offset:35840
	ds_read_b128 v[194:197], v143 offset:36864
	ds_read_b128 v[198:201], v143 offset:37888
	ds_read_b128 v[202:205], v143 offset:38912
	ds_read_b128 v[206:209], v143 offset:39936
	global_load_lds_dwordx4 v134, s[24:25]
	s_mov_b32 m0, s33
	s_nop 0
	global_load_lds_dwordx4 v130, s[24:25]
	s_waitcnt vmcnt(8)
	s_waitcnt lgkmcnt(0)
	s_barrier
	s_setprio 1
	s_waitcnt lgkmcnt(0)
	v_mfma_f32_16x16x32_bf16 v[124:127], v[144:147], v[178:181], v[124:127]
	v_mfma_f32_16x16x32_bf16 v[120:123], v[152:155], v[178:181], v[120:123]
	v_mfma_f32_16x16x32_bf16 v[116:119], v[144:147], v[186:189], v[116:119]
	v_mfma_f32_16x16x32_bf16 v[112:115], v[152:155], v[186:189], v[112:115]
	v_mfma_f32_16x16x32_bf16 v[100:103], v[144:147], v[194:197], v[100:103]
	v_mfma_f32_16x16x32_bf16 v[96:99], v[152:155], v[194:197], v[96:99]
	v_mfma_f32_16x16x32_bf16 v[84:87], v[144:147], v[202:205], v[84:87]
	v_mfma_f32_16x16x32_bf16 v[80:83], v[152:155], v[202:205], v[80:83]
	v_mfma_f32_16x16x32_bf16 v[124:127], v[148:151], v[182:185], v[124:127]
	v_mfma_f32_16x16x32_bf16 v[120:123], v[156:159], v[182:185], v[120:123]
	v_mfma_f32_16x16x32_bf16 v[116:119], v[148:151], v[190:193], v[116:119]
	v_mfma_f32_16x16x32_bf16 v[112:115], v[156:159], v[190:193], v[112:115]
	v_mfma_f32_16x16x32_bf16 v[100:103], v[148:151], v[198:201], v[100:103]
	v_mfma_f32_16x16x32_bf16 v[96:99], v[156:159], v[198:201], v[96:99]
	v_mfma_f32_16x16x32_bf16 v[84:87], v[148:151], v[206:209], v[84:87]
	v_mfma_f32_16x16x32_bf16 v[80:83], v[156:159], v[206:209], v[80:83]
	s_setprio 0
	s_setprio 1
	v_mfma_f32_16x16x32_bf16 v[108:111], v[160:163], v[178:181], v[108:111]
	v_mfma_f32_16x16x32_bf16 v[104:107], v[168:171], v[178:181], v[104:107]
	v_mfma_f32_16x16x32_bf16 v[92:95], v[160:163], v[186:189], v[92:95]
	v_mfma_f32_16x16x32_bf16 v[88:91], v[168:171], v[186:189], v[88:91]
	v_mfma_f32_16x16x32_bf16 v[76:79], v[160:163], v[194:197], v[76:79]
	v_mfma_f32_16x16x32_bf16 v[72:75], v[168:171], v[194:197], v[72:75]
	v_mfma_f32_16x16x32_bf16 v[68:71], v[160:163], v[202:205], v[68:71]
	v_mfma_f32_16x16x32_bf16 v[64:67], v[168:171], v[202:205], v[64:67]
	v_mfma_f32_16x16x32_bf16 v[108:111], v[164:167], v[182:185], v[108:111]
	v_mfma_f32_16x16x32_bf16 v[104:107], v[172:175], v[182:185], v[104:107]
	v_mfma_f32_16x16x32_bf16 v[92:95], v[164:167], v[190:193], v[92:95]
	v_mfma_f32_16x16x32_bf16 v[88:91], v[172:175], v[190:193], v[88:91]
	v_mfma_f32_16x16x32_bf16 v[76:79], v[164:167], v[198:201], v[76:79]
	v_mfma_f32_16x16x32_bf16 v[72:75], v[172:175], v[198:201], v[72:75]
	v_mfma_f32_16x16x32_bf16 v[68:71], v[164:167], v[206:209], v[68:71]
	v_mfma_f32_16x16x32_bf16 v[64:67], v[172:175], v[206:209], v[64:67]
	s_setprio 0
	s_barrier
	s_add_i32 s16, s16, s28
	s_mov_b32 m0, s16
	ds_read_b128 v[178:181], v143 offset:49152
	ds_read_b128 v[182:185], v143 offset:50176
	ds_read_b128 v[186:189], v143 offset:51200
	ds_read_b128 v[190:193], v143 offset:52224
	ds_read_b128 v[194:197], v143 offset:53248
	ds_read_b128 v[198:201], v143 offset:54272
	ds_read_b128 v[202:205], v143 offset:55296
	ds_read_b128 v[206:209], v143 offset:56320
	s_add_u32 s98, s22, 0x80
	s_addc_u32 s99, s23, 0
	global_load_lds_dwordx4 v132, s[98:99]
	s_add_i32 m0, s16, 0x2000
	s_add_u32 s22, s22, 0x400080
	s_addc_u32 s23, s23, 0
	s_add_i32 s16, s17, s28
	s_add_u32 s98, s42, 0xffc00080
	s_addc_u32 s99, s43, -1
	global_load_lds_dwordx4 v128, s[98:99]
	s_mov_b32 m0, s16
	s_nop 0
	global_load_lds_dwordx4 v132, s[22:23]
	s_add_i32 m0, s16, 0x2000
	s_nop 0
	global_load_lds_dwordx4 v128, s[22:23]
	s_mov_b32 m0, s34
	s_nop 0
	s_add_u32 s98, s24, 0xffe00080
	s_addc_u32 s99, s25, -1
	global_load_lds_dwordx4 v134, s[98:99]
	s_mov_b32 m0, s35
	s_nop 0
	s_add_u32 s98, s24, 0xffe00080
	s_addc_u32 s99, s25, -1
	global_load_lds_dwordx4 v130, s[98:99]
	s_waitcnt vmcnt(8)
	s_waitcnt lgkmcnt(0)
	s_barrier
	s_setprio 1
	s_waitcnt lgkmcnt(0)
	v_mfma_f32_16x16x32_bf16 v[60:63], v[144:147], v[178:181], v[60:63]
	v_mfma_f32_16x16x32_bf16 v[56:59], v[152:155], v[178:181], v[56:59]
	v_mfma_f32_16x16x32_bf16 v[52:55], v[144:147], v[186:189], v[52:55]
	v_mfma_f32_16x16x32_bf16 v[48:51], v[152:155], v[186:189], v[48:51]
	v_mfma_f32_16x16x32_bf16 v[36:39], v[144:147], v[194:197], v[36:39]
	v_mfma_f32_16x16x32_bf16 v[32:35], v[152:155], v[194:197], v[32:35]
	v_mfma_f32_16x16x32_bf16 v[20:23], v[144:147], v[202:205], v[20:23]
	v_mfma_f32_16x16x32_bf16 v[16:19], v[152:155], v[202:205], v[16:19]
	v_mfma_f32_16x16x32_bf16 v[60:63], v[148:151], v[182:185], v[60:63]
	v_mfma_f32_16x16x32_bf16 v[56:59], v[156:159], v[182:185], v[56:59]
	v_mfma_f32_16x16x32_bf16 v[52:55], v[148:151], v[190:193], v[52:55]
	v_mfma_f32_16x16x32_bf16 v[48:51], v[156:159], v[190:193], v[48:51]
	v_mfma_f32_16x16x32_bf16 v[36:39], v[148:151], v[198:201], v[36:39]
	v_mfma_f32_16x16x32_bf16 v[32:35], v[156:159], v[198:201], v[32:35]
	v_mfma_f32_16x16x32_bf16 v[20:23], v[148:151], v[206:209], v[20:23]
	v_mfma_f32_16x16x32_bf16 v[16:19], v[156:159], v[206:209], v[16:19]
	s_setprio 0
	s_setprio 1
	v_mfma_f32_16x16x32_bf16 v[44:47], v[160:163], v[178:181], v[44:47]
	v_mfma_f32_16x16x32_bf16 v[40:43], v[168:171], v[178:181], v[40:43]
	v_mfma_f32_16x16x32_bf16 v[28:31], v[160:163], v[186:189], v[28:31]
	v_mfma_f32_16x16x32_bf16 v[24:27], v[168:171], v[186:189], v[24:27]
	v_mfma_f32_16x16x32_bf16 v[12:15], v[160:163], v[194:197], v[12:15]
	v_mfma_f32_16x16x32_bf16 v[8:11], v[168:171], v[194:197], v[8:11]
	v_mfma_f32_16x16x32_bf16 v[4:7], v[160:163], v[202:205], v[4:7]
	v_mfma_f32_16x16x32_bf16 v[0:3], v[168:171], v[202:205], v[0:3]
	v_mfma_f32_16x16x32_bf16 v[44:47], v[164:167], v[182:185], v[44:47]
	v_mfma_f32_16x16x32_bf16 v[40:43], v[172:175], v[182:185], v[40:43]
	v_mfma_f32_16x16x32_bf16 v[28:31], v[164:167], v[190:193], v[28:31]
	v_mfma_f32_16x16x32_bf16 v[24:27], v[172:175], v[190:193], v[24:27]
	v_mfma_f32_16x16x32_bf16 v[12:15], v[164:167], v[198:201], v[12:15]
	v_mfma_f32_16x16x32_bf16 v[8:11], v[172:175], v[198:201], v[8:11]
	v_mfma_f32_16x16x32_bf16 v[4:7], v[164:167], v[206:209], v[4:7]
	v_mfma_f32_16x16x32_bf16 v[0:3], v[172:175], v[206:209], v[0:3]
	s_setprio 0
	s_barrier
	s_add_i32 s41, s41, 2
	s_add_u32 s18, s18, 0x100
	s_addc_u32 s19, s19, 0
	s_add_u32 s7, s7, 0x100
	s_addc_u32 s40, s40, 0
	s_cmpk_gt_u32 s41, 0x7d
	s_cbranch_scc0 .LBB0_730
	s_and_b64 vcc, exec, s[4:5]
	s_cbranch_vccz .LBB0_733
	s_barrier

.LBB0_748:
	s_add_u32 s18, s16, 0xfff00080
	s_addc_u32 s19, s17, -1
	s_add_i32 s38, 0, 0x10000
	s_cmp_eq_u32 s37, 60
	s_cselect_b32 s23, s15, s19
	s_cselect_b32 s22, s14, s18
	s_cselect_b32 s19, s13, s36
	s_cselect_b32 s18, s12, s7
	s_add_i32 s40, 0, 0x14000
	v_add_u32_e32 v156, s38, v142
	v_add_u32_e32 v172, s40, v142
	ds_read_b128 v[144:147], v156
	ds_read_b128 v[148:151], v156 offset:1024
	ds_read_b128 v[152:155], v156 offset:2048
	ds_read_b128 v[156:159], v156 offset:3072
	ds_read_b128 v[160:163], v172
	ds_read_b128 v[164:167], v172 offset:1024
	ds_read_b128 v[168:171], v172 offset:2048
	ds_read_b128 v[172:175], v172 offset:3072
	s_add_i32 m0, s27, 0xc000
	ds_read_b128 v[178:181], v143
	ds_read_b128 v[182:185], v143 offset:1024
	ds_read_b128 v[186:189], v143 offset:2048
	ds_read_b128 v[190:193], v143 offset:3072
	ds_read_b128 v[194:197], v143 offset:4096
	ds_read_b128 v[198:201], v143 offset:5120
	ds_read_b128 v[202:205], v143 offset:6144
	ds_read_b128 v[206:209], v143 offset:7168
	global_load_lds_dwordx4 v138, s[16:17]
	s_add_i32 m0, s27, 0xe000
	s_nop 0
	global_load_lds_dwordx4 v140, s[16:17]
	s_waitcnt vmcnt(8)
	s_waitcnt lgkmcnt(0)
	s_barrier
	s_setprio 1
	s_waitcnt lgkmcnt(0)
	v_mfma_f32_16x16x32_bf16 v[124:127], v[144:147], v[178:181], v[124:127]
	v_mfma_f32_16x16x32_bf16 v[120:123], v[152:155], v[178:181], v[120:123]
	v_mfma_f32_16x16x32_bf16 v[116:119], v[144:147], v[186:189], v[116:119]
	v_mfma_f32_16x16x32_bf16 v[112:115], v[152:155], v[186:189], v[112:115]
	v_mfma_f32_16x16x32_bf16 v[100:103], v[144:147], v[194:197], v[100:103]
	v_mfma_f32_16x16x32_bf16 v[96:99], v[152:155], v[194:197], v[96:99]
	v_mfma_f32_16x16x32_bf16 v[84:87], v[144:147], v[202:205], v[84:87]
	v_mfma_f32_16x16x32_bf16 v[80:83], v[152:155], v[202:205], v[80:83]
	v_mfma_f32_16x16x32_bf16 v[124:127], v[148:151], v[182:185], v[124:127]
	v_mfma_f32_16x16x32_bf16 v[120:123], v[156:159], v[182:185], v[120:123]
	v_mfma_f32_16x16x32_bf16 v[116:119], v[148:151], v[190:193], v[116:119]
	v_mfma_f32_16x16x32_bf16 v[112:115], v[156:159], v[190:193], v[112:115]
	v_mfma_f32_16x16x32_bf16 v[100:103], v[148:151], v[198:201], v[100:103]
	v_mfma_f32_16x16x32_bf16 v[96:99], v[156:159], v[198:201], v[96:99]
	v_mfma_f32_16x16x32_bf16 v[84:87], v[148:151], v[206:209], v[84:87]
	v_mfma_f32_16x16x32_bf16 v[80:83], v[156:159], v[206:209], v[80:83]
	s_setprio 0
	s_setprio 1
	v_mfma_f32_16x16x32_bf16 v[108:111], v[160:163], v[178:181], v[108:111]
	v_mfma_f32_16x16x32_bf16 v[104:107], v[168:171], v[178:181], v[104:107]
	v_mfma_f32_16x16x32_bf16 v[92:95], v[160:163], v[186:189], v[92:95]
	v_mfma_f32_16x16x32_bf16 v[88:91], v[168:171], v[186:189], v[88:91]
	v_mfma_f32_16x16x32_bf16 v[76:79], v[160:163], v[194:197], v[76:79]
	v_mfma_f32_16x16x32_bf16 v[72:75], v[168:171], v[194:197], v[72:75]
	v_mfma_f32_16x16x32_bf16 v[68:71], v[160:163], v[202:205], v[68:71]
	v_mfma_f32_16x16x32_bf16 v[64:67], v[168:171], v[202:205], v[64:67]
	v_mfma_f32_16x16x32_bf16 v[108:111], v[164:167], v[182:185], v[108:111]
	v_mfma_f32_16x16x32_bf16 v[104:107], v[172:175], v[182:185], v[104:107]
	v_mfma_f32_16x16x32_bf16 v[92:95], v[164:167], v[190:193], v[92:95]
	v_mfma_f32_16x16x32_bf16 v[88:91], v[172:175], v[190:193], v[88:91]
	v_mfma_f32_16x16x32_bf16 v[76:79], v[164:167], v[198:201], v[76:79]
	v_mfma_f32_16x16x32_bf16 v[72:75], v[172:175], v[198:201], v[72:75]
	v_mfma_f32_16x16x32_bf16 v[68:71], v[164:167], v[206:209], v[68:71]
	v_mfma_f32_16x16x32_bf16 v[64:67], v[172:175], v[206:209], v[64:67]
	s_setprio 0
	s_barrier
	s_add_i32 s38, s38, s26
	s_mov_b32 m0, s38
	ds_read_b128 v[178:181], v143 offset:16384
	ds_read_b128 v[182:185], v143 offset:17408
	ds_read_b128 v[186:189], v143 offset:18432
	ds_read_b128 v[190:193], v143 offset:19456
	ds_read_b128 v[194:197], v143 offset:20480
	ds_read_b128 v[198:201], v143 offset:21504
	ds_read_b128 v[202:205], v143 offset:22528
	ds_read_b128 v[206:209], v143 offset:23552
	global_load_lds_dwordx4 v132, s[18:19]
	s_add_i32 m0, s38, 0x2000
	s_add_u32 s38, s18, 0x800000
	s_addc_u32 s39, s19, 0
	s_add_i32 s40, s40, s26
	global_load_lds_dwordx4 v128, s[18:19]
	s_mov_b32 m0, s40
	s_nop 0
	global_load_lds_dwordx4 v132, s[38:39]
	s_add_i32 m0, s40, 0x2000
	s_nop 0
	global_load_lds_dwordx4 v128, s[38:39]
	s_add_u32 s60, s22, 0x80
	s_addc_u32 s61, s23, 0
	s_mov_b32 m0, s27
	s_nop 0
	global_load_lds_dwordx4 v134, s[22:23]
	s_mov_b32 m0, s8
	s_nop 0
	global_load_lds_dwordx4 v130, s[22:23]
	s_waitcnt vmcnt(8)
	s_waitcnt lgkmcnt(0)
	s_barrier
	s_setprio 1
	s_waitcnt lgkmcnt(0)
	v_mfma_f32_16x16x32_bf16 v[60:63], v[144:147], v[178:181], v[60:63]
	v_mfma_f32_16x16x32_bf16 v[56:59], v[152:155], v[178:181], v[56:59]
	v_mfma_f32_16x16x32_bf16 v[52:55], v[144:147], v[186:189], v[52:55]
	v_mfma_f32_16x16x32_bf16 v[48:51], v[152:155], v[186:189], v[48:51]
	v_mfma_f32_16x16x32_bf16 v[36:39], v[144:147], v[194:197], v[36:39]
	v_mfma_f32_16x16x32_bf16 v[32:35], v[152:155], v[194:197], v[32:35]
	v_mfma_f32_16x16x32_bf16 v[20:23], v[144:147], v[202:205], v[20:23]
	v_mfma_f32_16x16x32_bf16 v[16:19], v[152:155], v[202:205], v[16:19]
	v_mfma_f32_16x16x32_bf16 v[60:63], v[148:151], v[182:185], v[60:63]
	v_mfma_f32_16x16x32_bf16 v[56:59], v[156:159], v[182:185], v[56:59]
	v_mfma_f32_16x16x32_bf16 v[52:55], v[148:151], v[190:193], v[52:55]
	v_mfma_f32_16x16x32_bf16 v[48:51], v[156:159], v[190:193], v[48:51]
	v_mfma_f32_16x16x32_bf16 v[36:39], v[148:151], v[198:201], v[36:39]
	v_mfma_f32_16x16x32_bf16 v[32:35], v[156:159], v[198:201], v[32:35]
	v_mfma_f32_16x16x32_bf16 v[20:23], v[148:151], v[206:209], v[20:23]
	v_mfma_f32_16x16x32_bf16 v[16:19], v[156:159], v[206:209], v[16:19]
	s_setprio 0
	s_setprio 1
	v_mfma_f32_16x16x32_bf16 v[44:47], v[160:163], v[178:181], v[44:47]
	v_mfma_f32_16x16x32_bf16 v[40:43], v[168:171], v[178:181], v[40:43]
	v_mfma_f32_16x16x32_bf16 v[28:31], v[160:163], v[186:189], v[28:31]
	v_mfma_f32_16x16x32_bf16 v[24:27], v[168:171], v[186:189], v[24:27]
	v_mfma_f32_16x16x32_bf16 v[12:15], v[160:163], v[194:197], v[12:15]
	v_mfma_f32_16x16x32_bf16 v[8:11], v[168:171], v[194:197], v[8:11]
	v_mfma_f32_16x16x32_bf16 v[4:7], v[160:163], v[202:205], v[4:7]
	v_mfma_f32_16x16x32_bf16 v[0:3], v[168:171], v[202:205], v[0:3]
	v_mfma_f32_16x16x32_bf16 v[44:47], v[164:167], v[182:185], v[44:47]
	v_mfma_f32_16x16x32_bf16 v[40:43], v[172:175], v[182:185], v[40:43]
	v_mfma_f32_16x16x32_bf16 v[28:31], v[164:167], v[190:193], v[28:31]
	v_mfma_f32_16x16x32_bf16 v[24:27], v[172:175], v[190:193], v[24:27]
	v_mfma_f32_16x16x32_bf16 v[12:15], v[164:167], v[198:201], v[12:15]
	v_mfma_f32_16x16x32_bf16 v[8:11], v[172:175], v[198:201], v[8:11]
	v_mfma_f32_16x16x32_bf16 v[4:7], v[164:167], v[206:209], v[4:7]
	v_mfma_f32_16x16x32_bf16 v[0:3], v[172:175], v[206:209], v[0:3]
	s_setprio 0
	s_barrier
	s_add_i32 s38, 0, 0x18000
	s_add_i32 s39, 0, 0x1c000
	v_add_u32_e32 v156, s38, v142
	v_add_u32_e32 v172, s39, v142
	ds_read_b128 v[144:147], v156
	ds_read_b128 v[148:151], v156 offset:1024
	ds_read_b128 v[152:155], v156 offset:2048
	ds_read_b128 v[156:159], v156 offset:3072
	ds_read_b128 v[160:163], v172
	ds_read_b128 v[164:167], v172 offset:1024
	ds_read_b128 v[168:171], v172 offset:2048
	ds_read_b128 v[172:175], v172 offset:3072
	s_add_u32 s22, s22, 0x100000
	s_addc_u32 s23, s23, 0
	s_mov_b32 m0, s9
	ds_read_b128 v[178:181], v143 offset:32768
	ds_read_b128 v[182:185], v143 offset:33792
	ds_read_b128 v[186:189], v143 offset:34816
	ds_read_b128 v[190:193], v143 offset:35840
	ds_read_b128 v[194:197], v143 offset:36864
	ds_read_b128 v[198:201], v143 offset:37888
	ds_read_b128 v[202:205], v143 offset:38912
	ds_read_b128 v[206:209], v143 offset:39936
	global_load_lds_dwordx4 v134, s[22:23]
	s_mov_b32 m0, s28
	s_nop 0
	global_load_lds_dwordx4 v130, s[22:23]
	s_waitcnt vmcnt(8)
	s_waitcnt lgkmcnt(0)
	s_barrier
	s_setprio 1
	s_waitcnt lgkmcnt(0)
	v_mfma_f32_16x16x32_bf16 v[124:127], v[144:147], v[178:181], v[124:127]
	v_mfma_f32_16x16x32_bf16 v[120:123], v[152:155], v[178:181], v[120:123]
	v_mfma_f32_16x16x32_bf16 v[116:119], v[144:147], v[186:189], v[116:119]
	v_mfma_f32_16x16x32_bf16 v[112:115], v[152:155], v[186:189], v[112:115]
	v_mfma_f32_16x16x32_bf16 v[100:103], v[144:147], v[194:197], v[100:103]
	v_mfma_f32_16x16x32_bf16 v[96:99], v[152:155], v[194:197], v[96:99]
	v_mfma_f32_16x16x32_bf16 v[84:87], v[144:147], v[202:205], v[84:87]
	v_mfma_f32_16x16x32_bf16 v[80:83], v[152:155], v[202:205], v[80:83]
	v_mfma_f32_16x16x32_bf16 v[124:127], v[148:151], v[182:185], v[124:127]
	v_mfma_f32_16x16x32_bf16 v[120:123], v[156:159], v[182:185], v[120:123]
	v_mfma_f32_16x16x32_bf16 v[116:119], v[148:151], v[190:193], v[116:119]
	v_mfma_f32_16x16x32_bf16 v[112:115], v[156:159], v[190:193], v[112:115]
	v_mfma_f32_16x16x32_bf16 v[100:103], v[148:151], v[198:201], v[100:103]
	v_mfma_f32_16x16x32_bf16 v[96:99], v[156:159], v[198:201], v[96:99]
	v_mfma_f32_16x16x32_bf16 v[84:87], v[148:151], v[206:209], v[84:87]
	v_mfma_f32_16x16x32_bf16 v[80:83], v[156:159], v[206:209], v[80:83]
	s_setprio 0
	s_setprio 1
	v_mfma_f32_16x16x32_bf16 v[108:111], v[160:163], v[178:181], v[108:111]
	v_mfma_f32_16x16x32_bf16 v[104:107], v[168:171], v[178:181], v[104:107]
	v_mfma_f32_16x16x32_bf16 v[92:95], v[160:163], v[186:189], v[92:95]
	v_mfma_f32_16x16x32_bf16 v[88:91], v[168:171], v[186:189], v[88:91]
	v_mfma_f32_16x16x32_bf16 v[76:79], v[160:163], v[194:197], v[76:79]
	v_mfma_f32_16x16x32_bf16 v[72:75], v[168:171], v[194:197], v[72:75]
	v_mfma_f32_16x16x32_bf16 v[68:71], v[160:163], v[202:205], v[68:71]
	v_mfma_f32_16x16x32_bf16 v[64:67], v[168:171], v[202:205], v[64:67]
	v_mfma_f32_16x16x32_bf16 v[108:111], v[164:167], v[182:185], v[108:111]
	v_mfma_f32_16x16x32_bf16 v[104:107], v[172:175], v[182:185], v[104:107]
	v_mfma_f32_16x16x32_bf16 v[92:95], v[164:167], v[190:193], v[92:95]
	v_mfma_f32_16x16x32_bf16 v[88:91], v[172:175], v[190:193], v[88:91]
	v_mfma_f32_16x16x32_bf16 v[76:79], v[164:167], v[198:201], v[76:79]
	v_mfma_f32_16x16x32_bf16 v[72:75], v[172:175], v[198:201], v[72:75]
	v_mfma_f32_16x16x32_bf16 v[68:71], v[164:167], v[206:209], v[68:71]
	v_mfma_f32_16x16x32_bf16 v[64:67], v[172:175], v[206:209], v[64:67]
	s_setprio 0
	s_barrier
	s_add_i32 s22, s38, s26
	s_mov_b32 m0, s22
	ds_read_b128 v[178:181], v143 offset:49152
	ds_read_b128 v[182:185], v143 offset:50176
	ds_read_b128 v[186:189], v143 offset:51200
	ds_read_b128 v[190:193], v143 offset:52224
	ds_read_b128 v[194:197], v143 offset:53248
	ds_read_b128 v[198:201], v143 offset:54272
	ds_read_b128 v[202:205], v143 offset:55296
	ds_read_b128 v[206:209], v143 offset:56320
	s_add_u32 s98, s18, 0x80
	s_addc_u32 s99, s19, 0
	global_load_lds_dwordx4 v132, s[98:99]
	s_add_i32 m0, s22, 0x2000
	s_add_u32 s18, s18, 0x800080
	s_addc_u32 s19, s19, 0
	s_add_i32 s22, s39, s26
	s_add_u32 s98, s18, 0xff800000
	s_addc_u32 s99, s19, -1
	global_load_lds_dwordx4 v128, s[98:99]
	s_mov_b32 m0, s22
	s_nop 0
	global_load_lds_dwordx4 v132, s[18:19]
	s_add_i32 m0, s22, 0x2000
	s_nop 0
	global_load_lds_dwordx4 v128, s[18:19]
	s_mov_b32 m0, s29
	s_nop 0
	global_load_lds_dwordx4 v134, s[60:61]
	s_mov_b32 m0, s30
	s_nop 0
	global_load_lds_dwordx4 v130, s[60:61]
	s_waitcnt vmcnt(8)
	s_waitcnt lgkmcnt(0)
	s_barrier
	s_setprio 1
	s_waitcnt lgkmcnt(0)
	v_mfma_f32_16x16x32_bf16 v[60:63], v[144:147], v[178:181], v[60:63]
	v_mfma_f32_16x16x32_bf16 v[56:59], v[152:155], v[178:181], v[56:59]
	v_mfma_f32_16x16x32_bf16 v[52:55], v[144:147], v[186:189], v[52:55]
	v_mfma_f32_16x16x32_bf16 v[48:51], v[152:155], v[186:189], v[48:51]
	v_mfma_f32_16x16x32_bf16 v[36:39], v[144:147], v[194:197], v[36:39]
	v_mfma_f32_16x16x32_bf16 v[32:35], v[152:155], v[194:197], v[32:35]
	v_mfma_f32_16x16x32_bf16 v[20:23], v[144:147], v[202:205], v[20:23]
	v_mfma_f32_16x16x32_bf16 v[16:19], v[152:155], v[202:205], v[16:19]
	v_mfma_f32_16x16x32_bf16 v[60:63], v[148:151], v[182:185], v[60:63]
	v_mfma_f32_16x16x32_bf16 v[56:59], v[156:159], v[182:185], v[56:59]
	v_mfma_f32_16x16x32_bf16 v[52:55], v[148:151], v[190:193], v[52:55]
	v_mfma_f32_16x16x32_bf16 v[48:51], v[156:159], v[190:193], v[48:51]
	v_mfma_f32_16x16x32_bf16 v[36:39], v[148:151], v[198:201], v[36:39]
	v_mfma_f32_16x16x32_bf16 v[32:35], v[156:159], v[198:201], v[32:35]
	v_mfma_f32_16x16x32_bf16 v[20:23], v[148:151], v[206:209], v[20:23]
	v_mfma_f32_16x16x32_bf16 v[16:19], v[156:159], v[206:209], v[16:19]
	s_setprio 0
	s_setprio 1
	v_mfma_f32_16x16x32_bf16 v[44:47], v[160:163], v[178:181], v[44:47]
	v_mfma_f32_16x16x32_bf16 v[40:43], v[168:171], v[178:181], v[40:43]
	v_mfma_f32_16x16x32_bf16 v[28:31], v[160:163], v[186:189], v[28:31]
	v_mfma_f32_16x16x32_bf16 v[24:27], v[168:171], v[186:189], v[24:27]
	v_mfma_f32_16x16x32_bf16 v[12:15], v[160:163], v[194:197], v[12:15]
	v_mfma_f32_16x16x32_bf16 v[8:11], v[168:171], v[194:197], v[8:11]
	v_mfma_f32_16x16x32_bf16 v[4:7], v[160:163], v[202:205], v[4:7]
	v_mfma_f32_16x16x32_bf16 v[0:3], v[168:171], v[202:205], v[0:3]
	v_mfma_f32_16x16x32_bf16 v[44:47], v[164:167], v[182:185], v[44:47]
	v_mfma_f32_16x16x32_bf16 v[40:43], v[172:175], v[182:185], v[40:43]
	v_mfma_f32_16x16x32_bf16 v[28:31], v[164:167], v[190:193], v[28:31]
	v_mfma_f32_16x16x32_bf16 v[24:27], v[172:175], v[190:193], v[24:27]
	v_mfma_f32_16x16x32_bf16 v[12:15], v[164:167], v[198:201], v[12:15]
	v_mfma_f32_16x16x32_bf16 v[8:11], v[172:175], v[198:201], v[8:11]
	v_mfma_f32_16x16x32_bf16 v[4:7], v[164:167], v[206:209], v[4:7]
	v_mfma_f32_16x16x32_bf16 v[0:3], v[172:175], v[206:209], v[0:3]
	s_setprio 0
	s_barrier
	s_add_i32 s37, s37, 2
	s_add_u32 s16, s16, 0x100
	s_addc_u32 s17, s17, 0
	s_add_u32 s7, s7, 0x100
	s_addc_u32 s36, s36, 0
	s_cmp_gt_u32 s37, 61
	s_cbranch_scc0 .LBB0_748
	s_and_b64 vcc, exec, s[4:5]
	s_cbranch_vccz .LBB0_751
	s_barrier

.LBB0_830:
	s_add_u32 s8, s6, 0xfff80080
	s_addc_u32 s9, s7, -1
	s_add_i32 s13, 0, 0x10000
	s_cmp_eq_u32 s12, 28
	s_cselect_b32 s11, s31, s9
	s_cselect_b32 s10, s30, s8
	s_cselect_b32 s9, s19, s3
	s_cselect_b32 s8, s18, s1
	s_add_i32 s20, 0, 0x14000
	v_add_u32_e32 v124, s13, v209
	v_add_u32_e32 v156, s20, v209
	ds_read_b128 v[104:107], v124
	ds_read_b128 v[116:119], v124 offset:1024
	ds_read_b128 v[120:123], v124 offset:2048
	ds_read_b128 v[124:127], v124 offset:3072
	ds_read_b128 v[136:139], v156
	ds_read_b128 v[140:143], v156 offset:1024
	ds_read_b128 v[152:155], v156 offset:2048
	ds_read_b128 v[156:159], v156 offset:3072
	s_add_i32 m0, s28, 0xc000
	ds_read_b128 v[160:163], v228
	ds_read_b128 v[164:167], v228 offset:1024
	ds_read_b128 v[168:171], v228 offset:2048
	ds_read_b128 v[172:175], v228 offset:3072
	ds_read_b128 v[230:233], v228 offset:4096
	ds_read_b128 v[234:237], v228 offset:5120
	ds_read_b128 v[238:241], v228 offset:6144
	ds_read_b128 v[242:245], v228 offset:7168
	global_load_lds_dwordx4 v202, s[6:7]
	s_add_i32 m0, s28, 0xe000
	s_nop 0
	global_load_lds_dwordx4 v204, s[6:7]
	s_waitcnt vmcnt(8)
	s_waitcnt lgkmcnt(0)
	s_barrier
	s_setprio 1
	s_waitcnt lgkmcnt(0)
	v_mfma_f32_16x16x32_bf16 v[148:151], v[104:107], v[160:163], v[148:151]
	v_mfma_f32_16x16x32_bf16 v[144:147], v[120:123], v[160:163], v[144:147]
	v_mfma_f32_16x16x32_bf16 v[112:115], v[104:107], v[168:171], v[112:115]
	v_mfma_f32_16x16x32_bf16 v[108:111], v[120:123], v[168:171], v[108:111]
	v_mfma_f32_16x16x32_bf16 v[92:95], v[104:107], v[230:233], v[92:95]
	v_mfma_f32_16x16x32_bf16 v[88:91], v[120:123], v[230:233], v[88:91]
	v_mfma_f32_16x16x32_bf16 v[76:79], v[104:107], v[238:241], v[76:79]
	v_mfma_f32_16x16x32_bf16 v[72:75], v[120:123], v[238:241], v[72:75]
	v_mfma_f32_16x16x32_bf16 v[148:151], v[116:119], v[164:167], v[148:151]
	v_mfma_f32_16x16x32_bf16 v[144:147], v[124:127], v[164:167], v[144:147]
	v_mfma_f32_16x16x32_bf16 v[112:115], v[116:119], v[172:175], v[112:115]
	v_mfma_f32_16x16x32_bf16 v[108:111], v[124:127], v[172:175], v[108:111]
	v_mfma_f32_16x16x32_bf16 v[92:95], v[116:119], v[234:237], v[92:95]
	v_mfma_f32_16x16x32_bf16 v[88:91], v[124:127], v[234:237], v[88:91]
	v_mfma_f32_16x16x32_bf16 v[76:79], v[116:119], v[242:245], v[76:79]
	v_mfma_f32_16x16x32_bf16 v[72:75], v[124:127], v[242:245], v[72:75]
	s_setprio 0
	s_setprio 1
	v_mfma_f32_16x16x32_bf16 v[132:135], v[136:139], v[160:163], v[132:135]
	v_mfma_f32_16x16x32_bf16 v[128:131], v[152:155], v[160:163], v[128:131]
	v_mfma_f32_16x16x32_bf16 v[100:103], v[136:139], v[168:171], v[100:103]
	v_mfma_f32_16x16x32_bf16 v[96:99], v[152:155], v[168:171], v[96:99]
	v_mfma_f32_16x16x32_bf16 v[84:87], v[136:139], v[230:233], v[84:87]
	v_mfma_f32_16x16x32_bf16 v[80:83], v[152:155], v[230:233], v[80:83]
	v_mfma_f32_16x16x32_bf16 v[68:71], v[136:139], v[238:241], v[68:71]
	v_mfma_f32_16x16x32_bf16 v[64:67], v[152:155], v[238:241], v[64:67]
	v_mfma_f32_16x16x32_bf16 v[132:135], v[140:143], v[164:167], v[132:135]
	v_mfma_f32_16x16x32_bf16 v[128:131], v[156:159], v[164:167], v[128:131]
	v_mfma_f32_16x16x32_bf16 v[100:103], v[140:143], v[172:175], v[100:103]
	v_mfma_f32_16x16x32_bf16 v[96:99], v[156:159], v[172:175], v[96:99]
	v_mfma_f32_16x16x32_bf16 v[84:87], v[140:143], v[234:237], v[84:87]
	v_mfma_f32_16x16x32_bf16 v[80:83], v[156:159], v[234:237], v[80:83]
	v_mfma_f32_16x16x32_bf16 v[68:71], v[140:143], v[242:245], v[68:71]
	v_mfma_f32_16x16x32_bf16 v[64:67], v[156:159], v[242:245], v[64:67]
	s_setprio 0
	s_barrier
	s_add_i32 s13, s13, s27
	s_mov_b32 m0, s13
	ds_read_b128 v[160:163], v228 offset:16384
	ds_read_b128 v[164:167], v228 offset:17408
	ds_read_b128 v[168:171], v228 offset:18432
	ds_read_b128 v[172:175], v228 offset:19456
	ds_read_b128 v[230:233], v228 offset:20480
	ds_read_b128 v[234:237], v228 offset:21504
	ds_read_b128 v[238:241], v228 offset:22528
	ds_read_b128 v[242:245], v228 offset:23552
	global_load_lds_dwordx4 v176, s[8:9]
	s_add_i32 m0, s13, 0x2000
	s_add_u32 s14, s8, 0x80000
	s_addc_u32 s15, s9, 0
	s_add_i32 s13, s20, s27
	global_load_lds_dwordx4 v182, s[8:9]
	s_mov_b32 m0, s13
	s_nop 0
	global_load_lds_dwordx4 v176, s[14:15]
	s_add_i32 m0, s13, 0x2000
	s_nop 0
	global_load_lds_dwordx4 v182, s[14:15]
	s_add_u32 s50, s10, 0x80
	s_addc_u32 s51, s11, 0
	s_mov_b32 m0, s28
	s_nop 0
	global_load_lds_dwordx4 v178, s[10:11]
	s_mov_b32 m0, s29
	s_nop 0
	global_load_lds_dwordx4 v180, s[10:11]
	s_waitcnt vmcnt(8)
	s_waitcnt lgkmcnt(0)
	s_barrier
	s_setprio 1
	s_waitcnt lgkmcnt(0)
	v_mfma_f32_16x16x32_bf16 v[60:63], v[104:107], v[160:163], v[60:63]
	v_mfma_f32_16x16x32_bf16 v[56:59], v[120:123], v[160:163], v[56:59]
	v_mfma_f32_16x16x32_bf16 v[44:47], v[104:107], v[168:171], v[44:47]
	v_mfma_f32_16x16x32_bf16 v[40:43], v[120:123], v[168:171], v[40:43]
	v_mfma_f32_16x16x32_bf16 v[28:31], v[104:107], v[230:233], v[28:31]
	v_mfma_f32_16x16x32_bf16 v[24:27], v[120:123], v[230:233], v[24:27]
	v_mfma_f32_16x16x32_bf16 v[12:15], v[104:107], v[238:241], v[12:15]
	v_mfma_f32_16x16x32_bf16 v[8:11], v[120:123], v[238:241], v[8:11]
	v_mfma_f32_16x16x32_bf16 v[60:63], v[116:119], v[164:167], v[60:63]
	v_mfma_f32_16x16x32_bf16 v[56:59], v[124:127], v[164:167], v[56:59]
	v_mfma_f32_16x16x32_bf16 v[44:47], v[116:119], v[172:175], v[44:47]
	v_mfma_f32_16x16x32_bf16 v[40:43], v[124:127], v[172:175], v[40:43]
	v_mfma_f32_16x16x32_bf16 v[28:31], v[116:119], v[234:237], v[28:31]
	v_mfma_f32_16x16x32_bf16 v[24:27], v[124:127], v[234:237], v[24:27]
	v_mfma_f32_16x16x32_bf16 v[12:15], v[116:119], v[242:245], v[12:15]
	v_mfma_f32_16x16x32_bf16 v[8:11], v[124:127], v[242:245], v[8:11]
	s_setprio 0
	s_setprio 1
	v_mfma_f32_16x16x32_bf16 v[52:55], v[136:139], v[160:163], v[52:55]
	v_mfma_f32_16x16x32_bf16 v[48:51], v[152:155], v[160:163], v[48:51]
	v_mfma_f32_16x16x32_bf16 v[36:39], v[136:139], v[168:171], v[36:39]
	v_mfma_f32_16x16x32_bf16 v[32:35], v[152:155], v[168:171], v[32:35]
	v_mfma_f32_16x16x32_bf16 v[20:23], v[136:139], v[230:233], v[20:23]
	v_mfma_f32_16x16x32_bf16 v[16:19], v[152:155], v[230:233], v[16:19]
	v_mfma_f32_16x16x32_bf16 v[4:7], v[136:139], v[238:241], v[4:7]
	v_mfma_f32_16x16x32_bf16 v[0:3], v[152:155], v[238:241], v[0:3]
	v_mfma_f32_16x16x32_bf16 v[52:55], v[140:143], v[164:167], v[52:55]
	v_mfma_f32_16x16x32_bf16 v[48:51], v[156:159], v[164:167], v[48:51]
	v_mfma_f32_16x16x32_bf16 v[36:39], v[140:143], v[172:175], v[36:39]
	v_mfma_f32_16x16x32_bf16 v[32:35], v[156:159], v[172:175], v[32:35]
	v_mfma_f32_16x16x32_bf16 v[20:23], v[140:143], v[234:237], v[20:23]
	v_mfma_f32_16x16x32_bf16 v[16:19], v[156:159], v[234:237], v[16:19]
	v_mfma_f32_16x16x32_bf16 v[4:7], v[140:143], v[242:245], v[4:7]
	v_mfma_f32_16x16x32_bf16 v[0:3], v[156:159], v[242:245], v[0:3]
	s_setprio 0
	s_barrier
	s_add_i32 s13, 0, 0x18000
	s_add_i32 s14, 0, 0x1c000
	v_add_u32_e32 v124, s13, v209
	v_add_u32_e32 v156, s14, v209
	ds_read_b128 v[104:107], v124
	ds_read_b128 v[116:119], v124 offset:1024
	ds_read_b128 v[120:123], v124 offset:2048
	ds_read_b128 v[124:127], v124 offset:3072
	ds_read_b128 v[136:139], v156
	ds_read_b128 v[140:143], v156 offset:1024
	ds_read_b128 v[152:155], v156 offset:2048
	ds_read_b128 v[156:159], v156 offset:3072
	s_add_u32 s10, s10, 0x80000
	s_addc_u32 s11, s11, 0
	s_mov_b32 m0, s38
	ds_read_b128 v[160:163], v228 offset:32768
	ds_read_b128 v[164:167], v228 offset:33792
	ds_read_b128 v[168:171], v228 offset:34816
	ds_read_b128 v[172:175], v228 offset:35840
	ds_read_b128 v[230:233], v228 offset:36864
	ds_read_b128 v[234:237], v228 offset:37888
	ds_read_b128 v[238:241], v228 offset:38912
	ds_read_b128 v[242:245], v228 offset:39936
	global_load_lds_dwordx4 v178, s[10:11]
	s_mov_b32 m0, s39
	s_nop 0
	global_load_lds_dwordx4 v180, s[10:11]
	s_waitcnt vmcnt(8)
	s_waitcnt lgkmcnt(0)
	s_barrier
	s_setprio 1
	s_waitcnt lgkmcnt(0)
	v_mfma_f32_16x16x32_bf16 v[148:151], v[104:107], v[160:163], v[148:151]
	v_mfma_f32_16x16x32_bf16 v[144:147], v[120:123], v[160:163], v[144:147]
	v_mfma_f32_16x16x32_bf16 v[112:115], v[104:107], v[168:171], v[112:115]
	v_mfma_f32_16x16x32_bf16 v[108:111], v[120:123], v[168:171], v[108:111]
	v_mfma_f32_16x16x32_bf16 v[92:95], v[104:107], v[230:233], v[92:95]
	v_mfma_f32_16x16x32_bf16 v[88:91], v[120:123], v[230:233], v[88:91]
	v_mfma_f32_16x16x32_bf16 v[76:79], v[104:107], v[238:241], v[76:79]
	v_mfma_f32_16x16x32_bf16 v[72:75], v[120:123], v[238:241], v[72:75]
	v_mfma_f32_16x16x32_bf16 v[148:151], v[116:119], v[164:167], v[148:151]
	v_mfma_f32_16x16x32_bf16 v[144:147], v[124:127], v[164:167], v[144:147]
	v_mfma_f32_16x16x32_bf16 v[112:115], v[116:119], v[172:175], v[112:115]
	v_mfma_f32_16x16x32_bf16 v[108:111], v[124:127], v[172:175], v[108:111]
	v_mfma_f32_16x16x32_bf16 v[92:95], v[116:119], v[234:237], v[92:95]
	v_mfma_f32_16x16x32_bf16 v[88:91], v[124:127], v[234:237], v[88:91]
	v_mfma_f32_16x16x32_bf16 v[76:79], v[116:119], v[242:245], v[76:79]
	v_mfma_f32_16x16x32_bf16 v[72:75], v[124:127], v[242:245], v[72:75]
	s_setprio 0
	s_setprio 1
	v_mfma_f32_16x16x32_bf16 v[132:135], v[136:139], v[160:163], v[132:135]
	v_mfma_f32_16x16x32_bf16 v[128:131], v[152:155], v[160:163], v[128:131]
	v_mfma_f32_16x16x32_bf16 v[100:103], v[136:139], v[168:171], v[100:103]
	v_mfma_f32_16x16x32_bf16 v[96:99], v[152:155], v[168:171], v[96:99]
	v_mfma_f32_16x16x32_bf16 v[84:87], v[136:139], v[230:233], v[84:87]
	v_mfma_f32_16x16x32_bf16 v[80:83], v[152:155], v[230:233], v[80:83]
	v_mfma_f32_16x16x32_bf16 v[68:71], v[136:139], v[238:241], v[68:71]
	v_mfma_f32_16x16x32_bf16 v[64:67], v[152:155], v[238:241], v[64:67]
	v_mfma_f32_16x16x32_bf16 v[132:135], v[140:143], v[164:167], v[132:135]
	v_mfma_f32_16x16x32_bf16 v[128:131], v[156:159], v[164:167], v[128:131]
	v_mfma_f32_16x16x32_bf16 v[100:103], v[140:143], v[172:175], v[100:103]
	v_mfma_f32_16x16x32_bf16 v[96:99], v[156:159], v[172:175], v[96:99]
	v_mfma_f32_16x16x32_bf16 v[84:87], v[140:143], v[234:237], v[84:87]
	v_mfma_f32_16x16x32_bf16 v[80:83], v[156:159], v[234:237], v[80:83]
	v_mfma_f32_16x16x32_bf16 v[68:71], v[140:143], v[242:245], v[68:71]
	v_mfma_f32_16x16x32_bf16 v[64:67], v[156:159], v[242:245], v[64:67]
	s_setprio 0
	s_barrier
	s_add_i32 s10, s13, s27
	s_mov_b32 m0, s10
	ds_read_b128 v[160:163], v228 offset:49152
	ds_read_b128 v[164:167], v228 offset:50176
	ds_read_b128 v[168:171], v228 offset:51200
	ds_read_b128 v[172:175], v228 offset:52224
	ds_read_b128 v[230:233], v228 offset:53248
	ds_read_b128 v[234:237], v228 offset:54272
	ds_read_b128 v[238:241], v228 offset:55296
	ds_read_b128 v[242:245], v228 offset:56320
	s_add_u32 s98, s8, 0x80
	s_addc_u32 s99, s9, 0
	global_load_lds_dwordx4 v176, s[98:99]
	s_add_i32 m0, s10, 0x2000
	s_add_u32 s8, s8, 0x80080
	s_addc_u32 s9, s9, 0
	s_add_i32 s10, s14, s27
	s_add_u32 s98, s8, 0xfff80000
	s_addc_u32 s99, s9, -1
	global_load_lds_dwordx4 v182, s[98:99]
	s_mov_b32 m0, s10
	s_nop 0
	global_load_lds_dwordx4 v176, s[8:9]
	s_add_i32 m0, s10, 0x2000
	s_nop 0
	global_load_lds_dwordx4 v182, s[8:9]
	s_mov_b32 m0, s44
	s_nop 0
	global_load_lds_dwordx4 v178, s[50:51]
	s_mov_b32 m0, s45
	s_nop 0
	global_load_lds_dwordx4 v180, s[50:51]
	s_waitcnt vmcnt(8)
	s_waitcnt lgkmcnt(0)
	s_barrier
	s_setprio 1
	s_waitcnt lgkmcnt(0)
	v_mfma_f32_16x16x32_bf16 v[60:63], v[104:107], v[160:163], v[60:63]
	v_mfma_f32_16x16x32_bf16 v[56:59], v[120:123], v[160:163], v[56:59]
	v_mfma_f32_16x16x32_bf16 v[44:47], v[104:107], v[168:171], v[44:47]
	v_mfma_f32_16x16x32_bf16 v[40:43], v[120:123], v[168:171], v[40:43]
	v_mfma_f32_16x16x32_bf16 v[28:31], v[104:107], v[230:233], v[28:31]
	v_mfma_f32_16x16x32_bf16 v[24:27], v[120:123], v[230:233], v[24:27]
	v_mfma_f32_16x16x32_bf16 v[12:15], v[104:107], v[238:241], v[12:15]
	v_mfma_f32_16x16x32_bf16 v[8:11], v[120:123], v[238:241], v[8:11]
	v_mfma_f32_16x16x32_bf16 v[60:63], v[116:119], v[164:167], v[60:63]
	v_mfma_f32_16x16x32_bf16 v[56:59], v[124:127], v[164:167], v[56:59]
	v_mfma_f32_16x16x32_bf16 v[44:47], v[116:119], v[172:175], v[44:47]
	v_mfma_f32_16x16x32_bf16 v[40:43], v[124:127], v[172:175], v[40:43]
	v_mfma_f32_16x16x32_bf16 v[28:31], v[116:119], v[234:237], v[28:31]
	v_mfma_f32_16x16x32_bf16 v[24:27], v[124:127], v[234:237], v[24:27]
	v_mfma_f32_16x16x32_bf16 v[12:15], v[116:119], v[242:245], v[12:15]
	v_mfma_f32_16x16x32_bf16 v[8:11], v[124:127], v[242:245], v[8:11]
	s_setprio 0
	s_setprio 1
	v_mfma_f32_16x16x32_bf16 v[52:55], v[136:139], v[160:163], v[52:55]
	v_mfma_f32_16x16x32_bf16 v[48:51], v[152:155], v[160:163], v[48:51]
	v_mfma_f32_16x16x32_bf16 v[36:39], v[136:139], v[168:171], v[36:39]
	v_mfma_f32_16x16x32_bf16 v[32:35], v[152:155], v[168:171], v[32:35]
	v_mfma_f32_16x16x32_bf16 v[20:23], v[136:139], v[230:233], v[20:23]
	v_mfma_f32_16x16x32_bf16 v[16:19], v[152:155], v[230:233], v[16:19]
	v_mfma_f32_16x16x32_bf16 v[4:7], v[136:139], v[238:241], v[4:7]
	v_mfma_f32_16x16x32_bf16 v[0:3], v[152:155], v[238:241], v[0:3]
	v_mfma_f32_16x16x32_bf16 v[52:55], v[140:143], v[164:167], v[52:55]
	v_mfma_f32_16x16x32_bf16 v[48:51], v[156:159], v[164:167], v[48:51]
	v_mfma_f32_16x16x32_bf16 v[36:39], v[140:143], v[172:175], v[36:39]
	v_mfma_f32_16x16x32_bf16 v[32:35], v[156:159], v[172:175], v[32:35]
	v_mfma_f32_16x16x32_bf16 v[20:23], v[140:143], v[234:237], v[20:23]
	v_mfma_f32_16x16x32_bf16 v[16:19], v[156:159], v[234:237], v[16:19]
	v_mfma_f32_16x16x32_bf16 v[4:7], v[140:143], v[242:245], v[4:7]
	v_mfma_f32_16x16x32_bf16 v[0:3], v[156:159], v[242:245], v[0:3]
	s_setprio 0
	s_barrier
	s_add_i32 s12, s12, 2
	s_add_u32 s6, s6, 0x100
	s_addc_u32 s7, s7, 0
	s_add_u32 s1, s1, 0x100
	s_addc_u32 s3, s3, 0
	s_cmp_gt_u32 s12, 29
	s_cbranch_scc0 .LBB0_830
	s_and_b64 vcc, exec, s[52:53]
	s_cbranch_vccz .LBB0_833
	s_barrier

.Lf1g_rss_skip:
.LBB0_966:
	s_add_u32 s30, s4, 0xfff80080
	s_addc_u32 s31, s5, -1
	s_add_i32 s53, 0, 0x10000
	s_cmp_eq_u32 s52, 28
	s_cselect_b32 s35, s17, s31
	s_cselect_b32 s34, s25, s30
	v_add_u32_e32 v142, s53, v143
	s_cselect_b32 s31, s15, s51
	s_cselect_b32 s30, s36, s37
	s_add_i32 s56, 0, 0x14000
	ds_read_b128 v[148:151], v142
	ds_read_b128 v[152:155], v142 offset:1024
	ds_read_b128 v[156:159], v142 offset:2048
	ds_read_b128 v[160:163], v142 offset:3072
	v_add_u32_e32 v142, s56, v143
	ds_read_b128 v[164:167], v142
	ds_read_b128 v[168:171], v142 offset:1024
	ds_read_b128 v[172:175], v142 offset:2048
	ds_read_b128 v[178:181], v142 offset:3072
	s_add_i32 m0, s19, 0xc000
	ds_read_b128 v[182:185], v147
	ds_read_b128 v[186:189], v147 offset:1024
	ds_read_b128 v[190:193], v147 offset:2048
	ds_read_b128 v[194:197], v147 offset:3072
	ds_read_b128 v[198:201], v147 offset:4096
	ds_read_b128 v[202:205], v147 offset:5120
	ds_read_b128 v[206:209], v147 offset:6144
	ds_read_b128 v[220:223], v147 offset:7168
	global_load_lds_dwordx4 v138, s[4:5]
	s_add_i32 m0, s19, 0xe000
	s_nop 0
	global_load_lds_dwordx4 v140, s[4:5]
	s_waitcnt vmcnt(8)
	s_waitcnt lgkmcnt(0)
	s_barrier
	s_setprio 1
	s_waitcnt lgkmcnt(0)
	v_mfma_f32_16x16x32_bf16 v[124:127], v[148:151], v[182:185], v[124:127]
	v_mfma_f32_16x16x32_bf16 v[120:123], v[156:159], v[182:185], v[120:123]
	v_mfma_f32_16x16x32_bf16 v[108:111], v[148:151], v[190:193], v[108:111]
	v_mfma_f32_16x16x32_bf16 v[104:107], v[156:159], v[190:193], v[104:107]
	v_mfma_f32_16x16x32_bf16 v[92:95], v[148:151], v[198:201], v[92:95]
	v_mfma_f32_16x16x32_bf16 v[88:91], v[156:159], v[198:201], v[88:91]
	v_mfma_f32_16x16x32_bf16 v[76:79], v[148:151], v[206:209], v[76:79]
	v_mfma_f32_16x16x32_bf16 v[72:75], v[156:159], v[206:209], v[72:75]
	v_mfma_f32_16x16x32_bf16 v[124:127], v[152:155], v[186:189], v[124:127]
	v_mfma_f32_16x16x32_bf16 v[120:123], v[160:163], v[186:189], v[120:123]
	v_mfma_f32_16x16x32_bf16 v[108:111], v[152:155], v[194:197], v[108:111]
	v_mfma_f32_16x16x32_bf16 v[104:107], v[160:163], v[194:197], v[104:107]
	v_mfma_f32_16x16x32_bf16 v[92:95], v[152:155], v[202:205], v[92:95]
	v_mfma_f32_16x16x32_bf16 v[88:91], v[160:163], v[202:205], v[88:91]
	v_mfma_f32_16x16x32_bf16 v[76:79], v[152:155], v[220:223], v[76:79]
	v_mfma_f32_16x16x32_bf16 v[72:75], v[160:163], v[220:223], v[72:75]
	s_setprio 0
	s_setprio 1
	v_mfma_f32_16x16x32_bf16 v[116:119], v[164:167], v[182:185], v[116:119]
	v_mfma_f32_16x16x32_bf16 v[112:115], v[172:175], v[182:185], v[112:115]
	v_mfma_f32_16x16x32_bf16 v[100:103], v[164:167], v[190:193], v[100:103]
	v_mfma_f32_16x16x32_bf16 v[96:99], v[172:175], v[190:193], v[96:99]
	v_mfma_f32_16x16x32_bf16 v[84:87], v[164:167], v[198:201], v[84:87]
	v_mfma_f32_16x16x32_bf16 v[80:83], v[172:175], v[198:201], v[80:83]
	v_mfma_f32_16x16x32_bf16 v[68:71], v[164:167], v[206:209], v[68:71]
	v_mfma_f32_16x16x32_bf16 v[64:67], v[172:175], v[206:209], v[64:67]
	v_mfma_f32_16x16x32_bf16 v[116:119], v[168:171], v[186:189], v[116:119]
	v_mfma_f32_16x16x32_bf16 v[112:115], v[178:181], v[186:189], v[112:115]
	v_mfma_f32_16x16x32_bf16 v[100:103], v[168:171], v[194:197], v[100:103]
	v_mfma_f32_16x16x32_bf16 v[96:99], v[178:181], v[194:197], v[96:99]
	v_mfma_f32_16x16x32_bf16 v[84:87], v[168:171], v[202:205], v[84:87]
	v_mfma_f32_16x16x32_bf16 v[80:83], v[178:181], v[202:205], v[80:83]
	v_mfma_f32_16x16x32_bf16 v[68:71], v[168:171], v[220:223], v[68:71]
	v_mfma_f32_16x16x32_bf16 v[64:67], v[178:181], v[220:223], v[64:67]
	s_setprio 0
	s_barrier
	s_add_i32 s53, s53, s26
	s_mov_b32 m0, s53
	ds_read_b128 v[182:185], v147 offset:16384
	ds_read_b128 v[186:189], v147 offset:17408
	ds_read_b128 v[190:193], v147 offset:18432
	ds_read_b128 v[194:197], v147 offset:19456
	ds_read_b128 v[198:201], v147 offset:20480
	ds_read_b128 v[202:205], v147 offset:21504
	ds_read_b128 v[206:209], v147 offset:22528
	ds_read_b128 v[220:223], v147 offset:23552
	global_load_lds_dwordx4 v130, s[30:31]
	s_add_i32 m0, s53, 0x2000
	s_add_u32 s54, s30, 0x80000
	s_addc_u32 s55, s31, 0
	s_add_i32 s53, s56, s26
	global_load_lds_dwordx4 v134, s[30:31]
	s_mov_b32 m0, s53
	s_nop 0
	global_load_lds_dwordx4 v130, s[54:55]
	s_add_i32 m0, s53, 0x2000
	s_nop 0
	global_load_lds_dwordx4 v134, s[54:55]
	s_add_u32 s60, s34, 0x80
	s_addc_u32 s61, s35, 0
	s_mov_b32 m0, s19
	s_nop 0
	global_load_lds_dwordx4 v128, s[34:35]
	s_mov_b32 m0, s38
	s_nop 0
	global_load_lds_dwordx4 v132, s[34:35]
	s_waitcnt vmcnt(8)
	s_waitcnt lgkmcnt(0)
	s_barrier
	s_setprio 1
	s_waitcnt lgkmcnt(0)
	v_mfma_f32_16x16x32_bf16 v[60:63], v[148:151], v[182:185], v[60:63]
	v_mfma_f32_16x16x32_bf16 v[56:59], v[156:159], v[182:185], v[56:59]
	v_mfma_f32_16x16x32_bf16 v[44:47], v[148:151], v[190:193], v[44:47]
	v_mfma_f32_16x16x32_bf16 v[40:43], v[156:159], v[190:193], v[40:43]
	v_mfma_f32_16x16x32_bf16 v[28:31], v[148:151], v[198:201], v[28:31]
	v_mfma_f32_16x16x32_bf16 v[24:27], v[156:159], v[198:201], v[24:27]
	v_mfma_f32_16x16x32_bf16 v[12:15], v[148:151], v[206:209], v[12:15]
	v_mfma_f32_16x16x32_bf16 v[8:11], v[156:159], v[206:209], v[8:11]
	v_mfma_f32_16x16x32_bf16 v[60:63], v[152:155], v[186:189], v[60:63]
	v_mfma_f32_16x16x32_bf16 v[56:59], v[160:163], v[186:189], v[56:59]
	v_mfma_f32_16x16x32_bf16 v[44:47], v[152:155], v[194:197], v[44:47]
	v_mfma_f32_16x16x32_bf16 v[40:43], v[160:163], v[194:197], v[40:43]
	v_mfma_f32_16x16x32_bf16 v[28:31], v[152:155], v[202:205], v[28:31]
	v_mfma_f32_16x16x32_bf16 v[24:27], v[160:163], v[202:205], v[24:27]
	v_mfma_f32_16x16x32_bf16 v[12:15], v[152:155], v[220:223], v[12:15]
	v_mfma_f32_16x16x32_bf16 v[8:11], v[160:163], v[220:223], v[8:11]
	s_setprio 0
	s_setprio 1
	v_mfma_f32_16x16x32_bf16 v[52:55], v[164:167], v[182:185], v[52:55]
	v_mfma_f32_16x16x32_bf16 v[48:51], v[172:175], v[182:185], v[48:51]
	v_mfma_f32_16x16x32_bf16 v[36:39], v[164:167], v[190:193], v[36:39]
	v_mfma_f32_16x16x32_bf16 v[32:35], v[172:175], v[190:193], v[32:35]
	v_mfma_f32_16x16x32_bf16 v[20:23], v[164:167], v[198:201], v[20:23]
	v_mfma_f32_16x16x32_bf16 v[16:19], v[172:175], v[198:201], v[16:19]
	v_mfma_f32_16x16x32_bf16 v[4:7], v[164:167], v[206:209], v[4:7]
	v_mfma_f32_16x16x32_bf16 v[0:3], v[172:175], v[206:209], v[0:3]
	v_mfma_f32_16x16x32_bf16 v[52:55], v[168:171], v[186:189], v[52:55]
	v_mfma_f32_16x16x32_bf16 v[48:51], v[178:181], v[186:189], v[48:51]
	v_mfma_f32_16x16x32_bf16 v[36:39], v[168:171], v[194:197], v[36:39]
	v_mfma_f32_16x16x32_bf16 v[32:35], v[178:181], v[194:197], v[32:35]
	v_mfma_f32_16x16x32_bf16 v[20:23], v[168:171], v[202:205], v[20:23]
	v_mfma_f32_16x16x32_bf16 v[16:19], v[178:181], v[202:205], v[16:19]
	v_mfma_f32_16x16x32_bf16 v[4:7], v[168:171], v[220:223], v[4:7]
	v_mfma_f32_16x16x32_bf16 v[0:3], v[178:181], v[220:223], v[0:3]
	s_setprio 0
	s_barrier
	s_add_i32 s53, 0, 0x18000
	v_add_u32_e32 v142, s53, v143
	s_add_i32 s54, 0, 0x1c000
	ds_read_b128 v[148:151], v142
	ds_read_b128 v[152:155], v142 offset:1024
	ds_read_b128 v[156:159], v142 offset:2048
	ds_read_b128 v[160:163], v142 offset:3072
	v_add_u32_e32 v142, s54, v143
	ds_read_b128 v[164:167], v142
	ds_read_b128 v[168:171], v142 offset:1024
	ds_read_b128 v[172:175], v142 offset:2048
	ds_read_b128 v[178:181], v142 offset:3072
	s_add_u32 s34, s34, 0x80000
	s_addc_u32 s35, s35, 0
	s_mov_b32 m0, s39
	ds_read_b128 v[182:185], v147 offset:32768
	ds_read_b128 v[186:189], v147 offset:33792
	ds_read_b128 v[190:193], v147 offset:34816
	ds_read_b128 v[194:197], v147 offset:35840
	ds_read_b128 v[198:201], v147 offset:36864
	ds_read_b128 v[202:205], v147 offset:37888
	ds_read_b128 v[206:209], v147 offset:38912
	ds_read_b128 v[220:223], v147 offset:39936
	global_load_lds_dwordx4 v128, s[34:35]
	s_mov_b32 m0, s40
	s_nop 0
	global_load_lds_dwordx4 v132, s[34:35]
	s_waitcnt vmcnt(8)
	s_waitcnt lgkmcnt(0)
	s_barrier
	s_setprio 1
	s_waitcnt lgkmcnt(0)
	v_mfma_f32_16x16x32_bf16 v[124:127], v[148:151], v[182:185], v[124:127]
	v_mfma_f32_16x16x32_bf16 v[120:123], v[156:159], v[182:185], v[120:123]
	v_mfma_f32_16x16x32_bf16 v[108:111], v[148:151], v[190:193], v[108:111]
	v_mfma_f32_16x16x32_bf16 v[104:107], v[156:159], v[190:193], v[104:107]
	v_mfma_f32_16x16x32_bf16 v[92:95], v[148:151], v[198:201], v[92:95]
	v_mfma_f32_16x16x32_bf16 v[88:91], v[156:159], v[198:201], v[88:91]
	v_mfma_f32_16x16x32_bf16 v[76:79], v[148:151], v[206:209], v[76:79]
	v_mfma_f32_16x16x32_bf16 v[72:75], v[156:159], v[206:209], v[72:75]
	v_mfma_f32_16x16x32_bf16 v[124:127], v[152:155], v[186:189], v[124:127]
	v_mfma_f32_16x16x32_bf16 v[120:123], v[160:163], v[186:189], v[120:123]
	v_mfma_f32_16x16x32_bf16 v[108:111], v[152:155], v[194:197], v[108:111]
	v_mfma_f32_16x16x32_bf16 v[104:107], v[160:163], v[194:197], v[104:107]
	v_mfma_f32_16x16x32_bf16 v[92:95], v[152:155], v[202:205], v[92:95]
	v_mfma_f32_16x16x32_bf16 v[88:91], v[160:163], v[202:205], v[88:91]
	v_mfma_f32_16x16x32_bf16 v[76:79], v[152:155], v[220:223], v[76:79]
	v_mfma_f32_16x16x32_bf16 v[72:75], v[160:163], v[220:223], v[72:75]
	s_setprio 0
	s_setprio 1
	v_mfma_f32_16x16x32_bf16 v[116:119], v[164:167], v[182:185], v[116:119]
	v_mfma_f32_16x16x32_bf16 v[112:115], v[172:175], v[182:185], v[112:115]
	v_mfma_f32_16x16x32_bf16 v[100:103], v[164:167], v[190:193], v[100:103]
	v_mfma_f32_16x16x32_bf16 v[96:99], v[172:175], v[190:193], v[96:99]
	v_mfma_f32_16x16x32_bf16 v[84:87], v[164:167], v[198:201], v[84:87]
	v_mfma_f32_16x16x32_bf16 v[80:83], v[172:175], v[198:201], v[80:83]
	v_mfma_f32_16x16x32_bf16 v[68:71], v[164:167], v[206:209], v[68:71]
	v_mfma_f32_16x16x32_bf16 v[64:67], v[172:175], v[206:209], v[64:67]
	v_mfma_f32_16x16x32_bf16 v[116:119], v[168:171], v[186:189], v[116:119]
	v_mfma_f32_16x16x32_bf16 v[112:115], v[178:181], v[186:189], v[112:115]
	v_mfma_f32_16x16x32_bf16 v[100:103], v[168:171], v[194:197], v[100:103]
	v_mfma_f32_16x16x32_bf16 v[96:99], v[178:181], v[194:197], v[96:99]
	v_mfma_f32_16x16x32_bf16 v[84:87], v[168:171], v[202:205], v[84:87]
	v_mfma_f32_16x16x32_bf16 v[80:83], v[178:181], v[202:205], v[80:83]
	v_mfma_f32_16x16x32_bf16 v[68:71], v[168:171], v[220:223], v[68:71]
	v_mfma_f32_16x16x32_bf16 v[64:67], v[178:181], v[220:223], v[64:67]
	s_setprio 0
	s_barrier
	s_add_i32 s34, s53, s26
	s_mov_b32 m0, s34
	ds_read_b128 v[182:185], v147 offset:49152
	ds_read_b128 v[186:189], v147 offset:50176
	ds_read_b128 v[190:193], v147 offset:51200
	ds_read_b128 v[194:197], v147 offset:52224
	ds_read_b128 v[198:201], v147 offset:53248
	ds_read_b128 v[202:205], v147 offset:54272
	ds_read_b128 v[206:209], v147 offset:55296
	ds_read_b128 v[220:223], v147 offset:56320
	s_add_u32 s98, s30, 0x80
	s_addc_u32 s99, s31, 0
	global_load_lds_dwordx4 v130, s[98:99]
	s_add_i32 m0, s34, 0x2000
	s_add_u32 s30, s30, 0x80080
	s_addc_u32 s31, s31, 0
	s_add_i32 s34, s54, s26
	s_add_u32 s98, s30, 0xfff80000
	s_addc_u32 s99, s31, -1
	global_load_lds_dwordx4 v134, s[98:99]
	s_mov_b32 m0, s34
	s_nop 0
	global_load_lds_dwordx4 v130, s[30:31]
	s_add_i32 m0, s34, 0x2000
	s_nop 0
	global_load_lds_dwordx4 v134, s[30:31]
	s_mov_b32 m0, s47
	s_nop 0
	global_load_lds_dwordx4 v128, s[60:61]
	s_mov_b32 m0, s48
	s_nop 0
	global_load_lds_dwordx4 v132, s[60:61]
	s_waitcnt vmcnt(8)
	s_waitcnt lgkmcnt(0)
	s_barrier
	s_setprio 1
	s_waitcnt lgkmcnt(0)
	v_mfma_f32_16x16x32_bf16 v[60:63], v[148:151], v[182:185], v[60:63]
	v_mfma_f32_16x16x32_bf16 v[56:59], v[156:159], v[182:185], v[56:59]
	v_mfma_f32_16x16x32_bf16 v[44:47], v[148:151], v[190:193], v[44:47]
	v_mfma_f32_16x16x32_bf16 v[40:43], v[156:159], v[190:193], v[40:43]
	v_mfma_f32_16x16x32_bf16 v[28:31], v[148:151], v[198:201], v[28:31]
	v_mfma_f32_16x16x32_bf16 v[24:27], v[156:159], v[198:201], v[24:27]
	v_mfma_f32_16x16x32_bf16 v[12:15], v[148:151], v[206:209], v[12:15]
	v_mfma_f32_16x16x32_bf16 v[8:11], v[156:159], v[206:209], v[8:11]
	v_mfma_f32_16x16x32_bf16 v[60:63], v[152:155], v[186:189], v[60:63]
	v_mfma_f32_16x16x32_bf16 v[56:59], v[160:163], v[186:189], v[56:59]
	v_mfma_f32_16x16x32_bf16 v[44:47], v[152:155], v[194:197], v[44:47]
	v_mfma_f32_16x16x32_bf16 v[40:43], v[160:163], v[194:197], v[40:43]
	v_mfma_f32_16x16x32_bf16 v[28:31], v[152:155], v[202:205], v[28:31]
	v_mfma_f32_16x16x32_bf16 v[24:27], v[160:163], v[202:205], v[24:27]
	v_mfma_f32_16x16x32_bf16 v[12:15], v[152:155], v[220:223], v[12:15]
	v_mfma_f32_16x16x32_bf16 v[8:11], v[160:163], v[220:223], v[8:11]
	s_setprio 0
	s_setprio 1
	v_mfma_f32_16x16x32_bf16 v[52:55], v[164:167], v[182:185], v[52:55]
	v_mfma_f32_16x16x32_bf16 v[48:51], v[172:175], v[182:185], v[48:51]
	v_mfma_f32_16x16x32_bf16 v[36:39], v[164:167], v[190:193], v[36:39]
	v_mfma_f32_16x16x32_bf16 v[32:35], v[172:175], v[190:193], v[32:35]
	v_mfma_f32_16x16x32_bf16 v[20:23], v[164:167], v[198:201], v[20:23]
	v_mfma_f32_16x16x32_bf16 v[16:19], v[172:175], v[198:201], v[16:19]
	v_mfma_f32_16x16x32_bf16 v[4:7], v[164:167], v[206:209], v[4:7]
	v_mfma_f32_16x16x32_bf16 v[0:3], v[172:175], v[206:209], v[0:3]
	v_mfma_f32_16x16x32_bf16 v[52:55], v[168:171], v[186:189], v[52:55]
	v_mfma_f32_16x16x32_bf16 v[48:51], v[178:181], v[186:189], v[48:51]
	v_mfma_f32_16x16x32_bf16 v[36:39], v[168:171], v[194:197], v[36:39]
	v_mfma_f32_16x16x32_bf16 v[32:35], v[178:181], v[194:197], v[32:35]
	v_mfma_f32_16x16x32_bf16 v[20:23], v[168:171], v[202:205], v[20:23]
	v_mfma_f32_16x16x32_bf16 v[16:19], v[178:181], v[202:205], v[16:19]
	v_mfma_f32_16x16x32_bf16 v[4:7], v[168:171], v[220:223], v[4:7]
	v_mfma_f32_16x16x32_bf16 v[0:3], v[178:181], v[220:223], v[0:3]
	s_setprio 0
	s_barrier
	s_add_i32 s52, s52, 2
	s_add_u32 s4, s4, 0x100
	s_addc_u32 s5, s5, 0
	s_add_u32 s37, s37, 0x100
	s_addc_u32 s51, s51, 0
	s_cmp_gt_u32 s52, 29
	s_cbranch_scc0 .LBB0_966
	s_and_b64 vcc, exec, s[8:9]
	s_cbranch_vccz .LBB0_969
	s_barrier

.LBB0_1057:
	s_add_u32 s12, s0, 0xfff80080
	s_addc_u32 s13, s1, -1
	s_add_i32 s50, 0, 0x10000
	s_cmp_eq_u32 s33, 28
	s_cselect_b32 s15, s20, s13
	s_cselect_b32 s14, s21, s12
	s_cselect_b32 s13, s22, s27
	s_cselect_b32 s12, s23, s26
	s_add_i32 s53, 0, 0x14000
	v_add_u32_e32 v100, s50, v222
	v_add_u32_e32 v120, s53, v222
	ds_read_b128 v[88:91], v100
	ds_read_b128 v[92:95], v100 offset:1024
	ds_read_b128 v[96:99], v100 offset:2048
	ds_read_b128 v[100:103], v100 offset:3072
	ds_read_b128 v[108:111], v120
	ds_read_b128 v[112:115], v120 offset:1024
	ds_read_b128 v[116:119], v120 offset:2048
	ds_read_b128 v[120:123], v120 offset:3072
	s_add_i32 m0, s42, 0xc000
	ds_read_b128 v[152:155], v224
	ds_read_b128 v[164:167], v224 offset:1024
	ds_read_b128 v[168:171], v224 offset:2048
	ds_read_b128 v[172:175], v224 offset:3072
	ds_read_b128 v[188:191], v224 offset:4096
	ds_read_b128 v[192:195], v224 offset:5120
	ds_read_b128 v[196:199], v224 offset:6144
	ds_read_b128 v[200:203], v224 offset:7168
	global_load_lds_dwordx4 v184, s[0:1]
	s_add_i32 m0, s42, 0xe000
	s_nop 0
	global_load_lds_dwordx4 v186, s[0:1]
	s_waitcnt vmcnt(8)
	s_waitcnt lgkmcnt(0)
	s_barrier
	s_setprio 1
	s_waitcnt lgkmcnt(0)
	v_mfma_f32_16x16x32_bf16 v[160:163], v[88:91], v[152:155], v[160:163]
	v_mfma_f32_16x16x32_bf16 v[156:159], v[96:99], v[152:155], v[156:159]
	v_mfma_f32_16x16x32_bf16 v[148:151], v[88:91], v[168:171], v[148:151]
	v_mfma_f32_16x16x32_bf16 v[144:147], v[96:99], v[168:171], v[144:147]
	v_mfma_f32_16x16x32_bf16 v[140:143], v[88:91], v[188:191], v[140:143]
	v_mfma_f32_16x16x32_bf16 v[136:139], v[96:99], v[188:191], v[136:139]
	v_mfma_f32_16x16x32_bf16 v[132:135], v[88:91], v[196:199], v[132:135]
	v_mfma_f32_16x16x32_bf16 v[128:131], v[96:99], v[196:199], v[128:131]
	v_mfma_f32_16x16x32_bf16 v[160:163], v[92:95], v[164:167], v[160:163]
	v_mfma_f32_16x16x32_bf16 v[156:159], v[100:103], v[164:167], v[156:159]
	v_mfma_f32_16x16x32_bf16 v[148:151], v[92:95], v[172:175], v[148:151]
	v_mfma_f32_16x16x32_bf16 v[144:147], v[100:103], v[172:175], v[144:147]
	v_mfma_f32_16x16x32_bf16 v[140:143], v[92:95], v[192:195], v[140:143]
	v_mfma_f32_16x16x32_bf16 v[136:139], v[100:103], v[192:195], v[136:139]
	v_mfma_f32_16x16x32_bf16 v[132:135], v[92:95], v[200:203], v[132:135]
	v_mfma_f32_16x16x32_bf16 v[128:131], v[100:103], v[200:203], v[128:131]
	s_setprio 0
	s_setprio 1
	v_mfma_f32_16x16x32_bf16 v[60:63], v[108:111], v[152:155], v[60:63]
	v_mfma_f32_16x16x32_bf16 v[56:59], v[116:119], v[152:155], v[56:59]
	v_mfma_f32_16x16x32_bf16 v[52:55], v[108:111], v[168:171], v[52:55]
	v_mfma_f32_16x16x32_bf16 v[48:51], v[116:119], v[168:171], v[48:51]
	v_mfma_f32_16x16x32_bf16 v[44:47], v[108:111], v[188:191], v[44:47]
	v_mfma_f32_16x16x32_bf16 v[40:43], v[116:119], v[188:191], v[40:43]
	v_mfma_f32_16x16x32_bf16 v[36:39], v[108:111], v[196:199], v[36:39]
	v_mfma_f32_16x16x32_bf16 v[32:35], v[116:119], v[196:199], v[32:35]
	v_mfma_f32_16x16x32_bf16 v[60:63], v[112:115], v[164:167], v[60:63]
	v_mfma_f32_16x16x32_bf16 v[56:59], v[120:123], v[164:167], v[56:59]
	v_mfma_f32_16x16x32_bf16 v[52:55], v[112:115], v[172:175], v[52:55]
	v_mfma_f32_16x16x32_bf16 v[48:51], v[120:123], v[172:175], v[48:51]
	v_mfma_f32_16x16x32_bf16 v[44:47], v[112:115], v[192:195], v[44:47]
	v_mfma_f32_16x16x32_bf16 v[40:43], v[120:123], v[192:195], v[40:43]
	v_mfma_f32_16x16x32_bf16 v[36:39], v[112:115], v[200:203], v[36:39]
	v_mfma_f32_16x16x32_bf16 v[32:35], v[120:123], v[200:203], v[32:35]
	s_setprio 0
	s_barrier
	s_add_i32 s50, s50, s39
	s_mov_b32 m0, s50
	ds_read_b128 v[152:155], v224 offset:16384
	ds_read_b128 v[164:167], v224 offset:17408
	ds_read_b128 v[168:171], v224 offset:18432
	ds_read_b128 v[172:175], v224 offset:19456
	ds_read_b128 v[188:191], v224 offset:20480
	ds_read_b128 v[192:195], v224 offset:21504
	ds_read_b128 v[196:199], v224 offset:22528
	ds_read_b128 v[200:203], v224 offset:23552
	global_load_lds_dwordx4 v176, s[12:13]
	s_add_i32 m0, s50, 0x2000
	s_add_u32 s50, s12, 0x80000
	s_addc_u32 s51, s13, 0
	s_add_i32 s53, s53, s39
	global_load_lds_dwordx4 v178, s[12:13]
	s_mov_b32 m0, s53
	s_nop 0
	global_load_lds_dwordx4 v176, s[50:51]
	s_add_i32 m0, s53, 0x2000
	s_nop 0
	global_load_lds_dwordx4 v178, s[50:51]
	s_add_u32 s62, s14, 0x80
	s_addc_u32 s63, s15, 0
	s_mov_b32 m0, s42
	s_nop 0
	global_load_lds_dwordx4 v182, s[14:15]
	s_mov_b32 m0, s43
	s_nop 0
	global_load_lds_dwordx4 v180, s[14:15]
	s_waitcnt vmcnt(8)
	s_waitcnt lgkmcnt(0)
	s_barrier
	s_setprio 1
	s_waitcnt lgkmcnt(0)
	v_mfma_f32_16x16x32_bf16 v[124:127], v[88:91], v[152:155], v[124:127]
	v_mfma_f32_16x16x32_bf16 v[104:107], v[96:99], v[152:155], v[104:107]
	v_mfma_f32_16x16x32_bf16 v[84:87], v[88:91], v[168:171], v[84:87]
	v_mfma_f32_16x16x32_bf16 v[80:83], v[96:99], v[168:171], v[80:83]
	v_mfma_f32_16x16x32_bf16 v[76:79], v[88:91], v[188:191], v[76:79]
	v_mfma_f32_16x16x32_bf16 v[72:75], v[96:99], v[188:191], v[72:75]
	v_mfma_f32_16x16x32_bf16 v[68:71], v[88:91], v[196:199], v[68:71]
	v_mfma_f32_16x16x32_bf16 v[64:67], v[96:99], v[196:199], v[64:67]
	v_mfma_f32_16x16x32_bf16 v[124:127], v[92:95], v[164:167], v[124:127]
	v_mfma_f32_16x16x32_bf16 v[104:107], v[100:103], v[164:167], v[104:107]
	v_mfma_f32_16x16x32_bf16 v[84:87], v[92:95], v[172:175], v[84:87]
	v_mfma_f32_16x16x32_bf16 v[80:83], v[100:103], v[172:175], v[80:83]
	v_mfma_f32_16x16x32_bf16 v[76:79], v[92:95], v[192:195], v[76:79]
	v_mfma_f32_16x16x32_bf16 v[72:75], v[100:103], v[192:195], v[72:75]
	v_mfma_f32_16x16x32_bf16 v[68:71], v[92:95], v[200:203], v[68:71]
	v_mfma_f32_16x16x32_bf16 v[64:67], v[100:103], v[200:203], v[64:67]
	s_setprio 0
	s_setprio 1
	v_mfma_f32_16x16x32_bf16 v[28:31], v[108:111], v[152:155], v[28:31]
	v_mfma_f32_16x16x32_bf16 v[24:27], v[116:119], v[152:155], v[24:27]
	v_mfma_f32_16x16x32_bf16 v[20:23], v[108:111], v[168:171], v[20:23]
	v_mfma_f32_16x16x32_bf16 v[16:19], v[116:119], v[168:171], v[16:19]
	v_mfma_f32_16x16x32_bf16 v[12:15], v[108:111], v[188:191], v[12:15]
	v_mfma_f32_16x16x32_bf16 v[8:11], v[116:119], v[188:191], v[8:11]
	v_mfma_f32_16x16x32_bf16 v[4:7], v[108:111], v[196:199], v[4:7]
	v_mfma_f32_16x16x32_bf16 v[0:3], v[116:119], v[196:199], v[0:3]
	v_mfma_f32_16x16x32_bf16 v[28:31], v[112:115], v[164:167], v[28:31]
	v_mfma_f32_16x16x32_bf16 v[24:27], v[120:123], v[164:167], v[24:27]
	v_mfma_f32_16x16x32_bf16 v[20:23], v[112:115], v[172:175], v[20:23]
	v_mfma_f32_16x16x32_bf16 v[16:19], v[120:123], v[172:175], v[16:19]
	v_mfma_f32_16x16x32_bf16 v[12:15], v[112:115], v[192:195], v[12:15]
	v_mfma_f32_16x16x32_bf16 v[8:11], v[120:123], v[192:195], v[8:11]
	v_mfma_f32_16x16x32_bf16 v[4:7], v[112:115], v[200:203], v[4:7]
	v_mfma_f32_16x16x32_bf16 v[0:3], v[120:123], v[200:203], v[0:3]
	s_setprio 0
	s_barrier
	s_add_i32 s50, 0, 0x18000
	s_add_i32 s51, 0, 0x1c000
	v_add_u32_e32 v100, s50, v222
	v_add_u32_e32 v120, s51, v222
	ds_read_b128 v[88:91], v100
	ds_read_b128 v[92:95], v100 offset:1024
	ds_read_b128 v[96:99], v100 offset:2048
	ds_read_b128 v[100:103], v100 offset:3072
	ds_read_b128 v[108:111], v120
	ds_read_b128 v[112:115], v120 offset:1024
	ds_read_b128 v[116:119], v120 offset:2048
	ds_read_b128 v[120:123], v120 offset:3072
	s_add_u32 s14, s14, 0x80000
	s_addc_u32 s15, s15, 0
	s_mov_b32 m0, s44
	ds_read_b128 v[152:155], v224 offset:32768
	ds_read_b128 v[164:167], v224 offset:33792
	ds_read_b128 v[168:171], v224 offset:34816
	ds_read_b128 v[172:175], v224 offset:35840
	ds_read_b128 v[188:191], v224 offset:36864
	ds_read_b128 v[192:195], v224 offset:37888
	ds_read_b128 v[196:199], v224 offset:38912
	ds_read_b128 v[200:203], v224 offset:39936
	global_load_lds_dwordx4 v182, s[14:15]
	s_mov_b32 m0, s45
	s_nop 0
	global_load_lds_dwordx4 v180, s[14:15]
	s_waitcnt vmcnt(8)
	s_waitcnt lgkmcnt(0)
	s_barrier
	s_setprio 1
	s_waitcnt lgkmcnt(0)
	v_mfma_f32_16x16x32_bf16 v[160:163], v[88:91], v[152:155], v[160:163]
	v_mfma_f32_16x16x32_bf16 v[156:159], v[96:99], v[152:155], v[156:159]
	v_mfma_f32_16x16x32_bf16 v[148:151], v[88:91], v[168:171], v[148:151]
	v_mfma_f32_16x16x32_bf16 v[144:147], v[96:99], v[168:171], v[144:147]
	v_mfma_f32_16x16x32_bf16 v[140:143], v[88:91], v[188:191], v[140:143]
	v_mfma_f32_16x16x32_bf16 v[136:139], v[96:99], v[188:191], v[136:139]
	v_mfma_f32_16x16x32_bf16 v[132:135], v[88:91], v[196:199], v[132:135]
	v_mfma_f32_16x16x32_bf16 v[128:131], v[96:99], v[196:199], v[128:131]
	v_mfma_f32_16x16x32_bf16 v[160:163], v[92:95], v[164:167], v[160:163]
	v_mfma_f32_16x16x32_bf16 v[156:159], v[100:103], v[164:167], v[156:159]
	v_mfma_f32_16x16x32_bf16 v[148:151], v[92:95], v[172:175], v[148:151]
	v_mfma_f32_16x16x32_bf16 v[144:147], v[100:103], v[172:175], v[144:147]
	v_mfma_f32_16x16x32_bf16 v[140:143], v[92:95], v[192:195], v[140:143]
	v_mfma_f32_16x16x32_bf16 v[136:139], v[100:103], v[192:195], v[136:139]
	v_mfma_f32_16x16x32_bf16 v[132:135], v[92:95], v[200:203], v[132:135]
	v_mfma_f32_16x16x32_bf16 v[128:131], v[100:103], v[200:203], v[128:131]
	s_setprio 0
	s_setprio 1
	v_mfma_f32_16x16x32_bf16 v[60:63], v[108:111], v[152:155], v[60:63]
	v_mfma_f32_16x16x32_bf16 v[56:59], v[116:119], v[152:155], v[56:59]
	v_mfma_f32_16x16x32_bf16 v[52:55], v[108:111], v[168:171], v[52:55]
	v_mfma_f32_16x16x32_bf16 v[48:51], v[116:119], v[168:171], v[48:51]
	v_mfma_f32_16x16x32_bf16 v[44:47], v[108:111], v[188:191], v[44:47]
	v_mfma_f32_16x16x32_bf16 v[40:43], v[116:119], v[188:191], v[40:43]
	v_mfma_f32_16x16x32_bf16 v[36:39], v[108:111], v[196:199], v[36:39]
	v_mfma_f32_16x16x32_bf16 v[32:35], v[116:119], v[196:199], v[32:35]
	v_mfma_f32_16x16x32_bf16 v[60:63], v[112:115], v[164:167], v[60:63]
	v_mfma_f32_16x16x32_bf16 v[56:59], v[120:123], v[164:167], v[56:59]
	v_mfma_f32_16x16x32_bf16 v[52:55], v[112:115], v[172:175], v[52:55]
	v_mfma_f32_16x16x32_bf16 v[48:51], v[120:123], v[172:175], v[48:51]
	v_mfma_f32_16x16x32_bf16 v[44:47], v[112:115], v[192:195], v[44:47]
	v_mfma_f32_16x16x32_bf16 v[40:43], v[120:123], v[192:195], v[40:43]
	v_mfma_f32_16x16x32_bf16 v[36:39], v[112:115], v[200:203], v[36:39]
	v_mfma_f32_16x16x32_bf16 v[32:35], v[120:123], v[200:203], v[32:35]
	s_setprio 0
	s_barrier
	s_add_i32 s14, s50, s39
	s_mov_b32 m0, s14
	ds_read_b128 v[152:155], v224 offset:49152
	ds_read_b128 v[164:167], v224 offset:50176
	ds_read_b128 v[168:171], v224 offset:51200
	ds_read_b128 v[172:175], v224 offset:52224
	ds_read_b128 v[188:191], v224 offset:53248
	ds_read_b128 v[192:195], v224 offset:54272
	ds_read_b128 v[196:199], v224 offset:55296
	ds_read_b128 v[200:203], v224 offset:56320
	s_add_u32 s98, s12, 0x80
	s_addc_u32 s99, s13, 0
	global_load_lds_dwordx4 v176, s[98:99]
	s_add_i32 m0, s14, 0x2000
	s_add_u32 s12, s12, 0x80080
	s_addc_u32 s13, s13, 0
	s_add_i32 s14, s51, s39
	s_add_u32 s98, s12, 0xfff80000
	s_addc_u32 s99, s13, -1
	global_load_lds_dwordx4 v178, s[98:99]
	s_mov_b32 m0, s14
	s_nop 0
	global_load_lds_dwordx4 v176, s[12:13]
	s_add_i32 m0, s14, 0x2000
	s_nop 0
	global_load_lds_dwordx4 v178, s[12:13]
	s_mov_b32 m0, s61
	s_nop 0
	global_load_lds_dwordx4 v182, s[62:63]
	s_mov_b32 m0, s64
	s_nop 0
	global_load_lds_dwordx4 v180, s[62:63]
	s_waitcnt vmcnt(8)
	s_waitcnt lgkmcnt(0)
	s_barrier
	s_setprio 1
	s_waitcnt lgkmcnt(0)
	v_mfma_f32_16x16x32_bf16 v[124:127], v[88:91], v[152:155], v[124:127]
	v_mfma_f32_16x16x32_bf16 v[104:107], v[96:99], v[152:155], v[104:107]
	v_mfma_f32_16x16x32_bf16 v[84:87], v[88:91], v[168:171], v[84:87]
	v_mfma_f32_16x16x32_bf16 v[80:83], v[96:99], v[168:171], v[80:83]
	v_mfma_f32_16x16x32_bf16 v[76:79], v[88:91], v[188:191], v[76:79]
	v_mfma_f32_16x16x32_bf16 v[72:75], v[96:99], v[188:191], v[72:75]
	v_mfma_f32_16x16x32_bf16 v[68:71], v[88:91], v[196:199], v[68:71]
	v_mfma_f32_16x16x32_bf16 v[64:67], v[96:99], v[196:199], v[64:67]
	v_mfma_f32_16x16x32_bf16 v[124:127], v[92:95], v[164:167], v[124:127]
	v_mfma_f32_16x16x32_bf16 v[104:107], v[100:103], v[164:167], v[104:107]
	v_mfma_f32_16x16x32_bf16 v[84:87], v[92:95], v[172:175], v[84:87]
	v_mfma_f32_16x16x32_bf16 v[80:83], v[100:103], v[172:175], v[80:83]
	v_mfma_f32_16x16x32_bf16 v[76:79], v[92:95], v[192:195], v[76:79]
	v_mfma_f32_16x16x32_bf16 v[72:75], v[100:103], v[192:195], v[72:75]
	v_mfma_f32_16x16x32_bf16 v[68:71], v[92:95], v[200:203], v[68:71]
	v_mfma_f32_16x16x32_bf16 v[64:67], v[100:103], v[200:203], v[64:67]
	s_setprio 0
	s_setprio 1
	v_mfma_f32_16x16x32_bf16 v[28:31], v[108:111], v[152:155], v[28:31]
	v_mfma_f32_16x16x32_bf16 v[24:27], v[116:119], v[152:155], v[24:27]
	v_mfma_f32_16x16x32_bf16 v[20:23], v[108:111], v[168:171], v[20:23]
	v_mfma_f32_16x16x32_bf16 v[16:19], v[116:119], v[168:171], v[16:19]
	v_mfma_f32_16x16x32_bf16 v[12:15], v[108:111], v[188:191], v[12:15]
	v_mfma_f32_16x16x32_bf16 v[8:11], v[116:119], v[188:191], v[8:11]
	v_mfma_f32_16x16x32_bf16 v[4:7], v[108:111], v[196:199], v[4:7]
	v_mfma_f32_16x16x32_bf16 v[0:3], v[116:119], v[196:199], v[0:3]
	v_mfma_f32_16x16x32_bf16 v[28:31], v[112:115], v[164:167], v[28:31]
	v_mfma_f32_16x16x32_bf16 v[24:27], v[120:123], v[164:167], v[24:27]
	v_mfma_f32_16x16x32_bf16 v[20:23], v[112:115], v[172:175], v[20:23]
	v_mfma_f32_16x16x32_bf16 v[16:19], v[120:123], v[172:175], v[16:19]
	v_mfma_f32_16x16x32_bf16 v[12:15], v[112:115], v[192:195], v[12:15]
	v_mfma_f32_16x16x32_bf16 v[8:11], v[120:123], v[192:195], v[8:11]
	v_mfma_f32_16x16x32_bf16 v[4:7], v[112:115], v[200:203], v[4:7]
	v_mfma_f32_16x16x32_bf16 v[0:3], v[120:123], v[200:203], v[0:3]
	s_setprio 0
	s_barrier
	s_add_i32 s33, s33, 2
	s_add_u32 s0, s0, 0x100
	s_addc_u32 s1, s1, 0
	s_add_u32 s26, s26, 0x100
	s_addc_u32 s27, s27, 0
	s_cmp_gt_u32 s33, 29
	s_cbranch_scc0 .LBB0_1057
	s_and_b64 vcc, exec, s[40:41]
	s_cbranch_vccz .LBB0_1060
	s_barrier

.LBB0_1160:
	s_add_u32 s6, s0, 0x100
	s_addc_u32 s7, s1, 0
	s_add_i32 s15, 0, 0x10000
	s_cmpk_eq_i32 s14, 0x54
	s_cselect_b32 s13, s69, s7
	s_cselect_b32 s12, s68, s6
	s_cselect_b32 s9, s31, s3
	s_cselect_b32 s8, s30, s2
	s_add_i32 s20, 0, 0x14000
	v_add_u32_e32 v116, s15, v204
	v_add_u32_e32 v156, s20, v204
	ds_read_b128 v[100:103], v116
	ds_read_b128 v[108:111], v116 offset:1024
	ds_read_b128 v[112:115], v116 offset:2048
	ds_read_b128 v[116:119], v116 offset:3072
	ds_read_b128 v[136:139], v156
	ds_read_b128 v[148:151], v156 offset:1024
	ds_read_b128 v[152:155], v156 offset:2048
	ds_read_b128 v[156:159], v156 offset:3072
	s_add_i32 m0, s28, 0xc000
	ds_read_b128 v[160:163], v223
	ds_read_b128 v[164:167], v223 offset:1024
	ds_read_b128 v[168:171], v223 offset:2048
	ds_read_b128 v[172:175], v223 offset:3072
	ds_read_b128 v[200:203], v223 offset:4096
	ds_read_b128 v[226:229], v223 offset:5120
	ds_read_b128 v[230:233], v223 offset:6144
	ds_read_b128 v[234:237], v223 offset:7168
	global_load_lds_dwordx4 v196, s[0:1]
	s_add_i32 m0, s28, 0xe000
	s_nop 0
	global_load_lds_dwordx4 v198, s[0:1]
	s_waitcnt vmcnt(8)
	s_waitcnt lgkmcnt(0)
	s_barrier
	s_setprio 1
	s_waitcnt lgkmcnt(0)
	v_mfma_f32_16x16x32_bf16 v[144:147], v[100:103], v[160:163], v[144:147]
	v_mfma_f32_16x16x32_bf16 v[140:143], v[112:115], v[160:163], v[140:143]
	v_mfma_f32_16x16x32_bf16 v[124:127], v[100:103], v[168:171], v[124:127]
	v_mfma_f32_16x16x32_bf16 v[120:123], v[112:115], v[168:171], v[120:123]
	v_mfma_f32_16x16x32_bf16 v[92:95], v[100:103], v[200:203], v[92:95]
	v_mfma_f32_16x16x32_bf16 v[88:91], v[112:115], v[200:203], v[88:91]
	v_mfma_f32_16x16x32_bf16 v[76:79], v[100:103], v[230:233], v[76:79]
	v_mfma_f32_16x16x32_bf16 v[72:75], v[112:115], v[230:233], v[72:75]
	v_mfma_f32_16x16x32_bf16 v[144:147], v[108:111], v[164:167], v[144:147]
	v_mfma_f32_16x16x32_bf16 v[140:143], v[116:119], v[164:167], v[140:143]
	v_mfma_f32_16x16x32_bf16 v[124:127], v[108:111], v[172:175], v[124:127]
	v_mfma_f32_16x16x32_bf16 v[120:123], v[116:119], v[172:175], v[120:123]
	v_mfma_f32_16x16x32_bf16 v[92:95], v[108:111], v[226:229], v[92:95]
	v_mfma_f32_16x16x32_bf16 v[88:91], v[116:119], v[226:229], v[88:91]
	v_mfma_f32_16x16x32_bf16 v[76:79], v[108:111], v[234:237], v[76:79]
	v_mfma_f32_16x16x32_bf16 v[72:75], v[116:119], v[234:237], v[72:75]
	s_setprio 0
	s_setprio 1
	v_mfma_f32_16x16x32_bf16 v[132:135], v[136:139], v[160:163], v[132:135]
	v_mfma_f32_16x16x32_bf16 v[128:131], v[152:155], v[160:163], v[128:131]
	v_mfma_f32_16x16x32_bf16 v[104:107], v[136:139], v[168:171], v[104:107]
	v_mfma_f32_16x16x32_bf16 v[96:99], v[152:155], v[168:171], v[96:99]
	v_mfma_f32_16x16x32_bf16 v[84:87], v[136:139], v[200:203], v[84:87]
	v_mfma_f32_16x16x32_bf16 v[80:83], v[152:155], v[200:203], v[80:83]
	v_mfma_f32_16x16x32_bf16 v[68:71], v[136:139], v[230:233], v[68:71]
	v_mfma_f32_16x16x32_bf16 v[64:67], v[152:155], v[230:233], v[64:67]
	v_mfma_f32_16x16x32_bf16 v[132:135], v[148:151], v[164:167], v[132:135]
	v_mfma_f32_16x16x32_bf16 v[128:131], v[156:159], v[164:167], v[128:131]
	v_mfma_f32_16x16x32_bf16 v[104:107], v[148:151], v[172:175], v[104:107]
	v_mfma_f32_16x16x32_bf16 v[96:99], v[156:159], v[172:175], v[96:99]
	v_mfma_f32_16x16x32_bf16 v[84:87], v[148:151], v[226:229], v[84:87]
	v_mfma_f32_16x16x32_bf16 v[80:83], v[156:159], v[226:229], v[80:83]
	v_mfma_f32_16x16x32_bf16 v[68:71], v[148:151], v[234:237], v[68:71]
	v_mfma_f32_16x16x32_bf16 v[64:67], v[156:159], v[234:237], v[64:67]
	s_setprio 0
	s_barrier
	s_add_i32 s0, s15, s27
	s_mov_b32 m0, s0
	ds_read_b128 v[160:163], v223 offset:16384
	ds_read_b128 v[164:167], v223 offset:17408
	ds_read_b128 v[168:171], v223 offset:18432
	ds_read_b128 v[172:175], v223 offset:19456
	ds_read_b128 v[200:203], v223 offset:20480
	ds_read_b128 v[226:229], v223 offset:21504
	ds_read_b128 v[230:233], v223 offset:22528
	ds_read_b128 v[234:237], v223 offset:23552
	global_load_lds_dwordx4 v176, s[8:9]
	s_add_i32 m0, s0, 0x2000
	s_add_u32 s0, s8, 0x160000
	s_addc_u32 s1, s9, 0
	s_add_i32 s15, s20, s27
	global_load_lds_dwordx4 v182, s[8:9]
	s_mov_b32 m0, s15
	s_nop 0
	global_load_lds_dwordx4 v176, s[0:1]
	s_add_i32 m0, s15, 0x2000
	s_nop 0
	global_load_lds_dwordx4 v182, s[0:1]
	s_mov_b32 m0, s28
	s_nop 0
	global_load_lds_dwordx4 v178, s[12:13]
	s_mov_b32 m0, s29
	s_nop 0
	global_load_lds_dwordx4 v180, s[12:13]
	s_waitcnt vmcnt(8)
	s_waitcnt lgkmcnt(0)
	s_barrier
	s_setprio 1
	s_waitcnt lgkmcnt(0)
	v_mfma_f32_16x16x32_bf16 v[60:63], v[100:103], v[160:163], v[60:63]
	v_mfma_f32_16x16x32_bf16 v[56:59], v[112:115], v[160:163], v[56:59]
	v_mfma_f32_16x16x32_bf16 v[44:47], v[100:103], v[168:171], v[44:47]
	v_mfma_f32_16x16x32_bf16 v[40:43], v[112:115], v[168:171], v[40:43]
	v_mfma_f32_16x16x32_bf16 v[28:31], v[100:103], v[200:203], v[28:31]
	v_mfma_f32_16x16x32_bf16 v[24:27], v[112:115], v[200:203], v[24:27]
	v_mfma_f32_16x16x32_bf16 v[12:15], v[100:103], v[230:233], v[12:15]
	v_mfma_f32_16x16x32_bf16 v[8:11], v[112:115], v[230:233], v[8:11]
	v_mfma_f32_16x16x32_bf16 v[60:63], v[108:111], v[164:167], v[60:63]
	v_mfma_f32_16x16x32_bf16 v[56:59], v[116:119], v[164:167], v[56:59]
	v_mfma_f32_16x16x32_bf16 v[44:47], v[108:111], v[172:175], v[44:47]
	v_mfma_f32_16x16x32_bf16 v[40:43], v[116:119], v[172:175], v[40:43]
	v_mfma_f32_16x16x32_bf16 v[28:31], v[108:111], v[226:229], v[28:31]
	v_mfma_f32_16x16x32_bf16 v[24:27], v[116:119], v[226:229], v[24:27]
	v_mfma_f32_16x16x32_bf16 v[12:15], v[108:111], v[234:237], v[12:15]
	v_mfma_f32_16x16x32_bf16 v[8:11], v[116:119], v[234:237], v[8:11]
	s_setprio 0
	s_setprio 1
	v_mfma_f32_16x16x32_bf16 v[52:55], v[136:139], v[160:163], v[52:55]
	v_mfma_f32_16x16x32_bf16 v[48:51], v[152:155], v[160:163], v[48:51]
	v_mfma_f32_16x16x32_bf16 v[36:39], v[136:139], v[168:171], v[36:39]
	v_mfma_f32_16x16x32_bf16 v[32:35], v[152:155], v[168:171], v[32:35]
	v_mfma_f32_16x16x32_bf16 v[20:23], v[136:139], v[200:203], v[20:23]
	v_mfma_f32_16x16x32_bf16 v[16:19], v[152:155], v[200:203], v[16:19]
	v_mfma_f32_16x16x32_bf16 v[4:7], v[136:139], v[230:233], v[4:7]
	v_mfma_f32_16x16x32_bf16 v[0:3], v[152:155], v[230:233], v[0:3]
	v_mfma_f32_16x16x32_bf16 v[52:55], v[148:151], v[164:167], v[52:55]
	v_mfma_f32_16x16x32_bf16 v[48:51], v[156:159], v[164:167], v[48:51]
	v_mfma_f32_16x16x32_bf16 v[36:39], v[148:151], v[172:175], v[36:39]
	v_mfma_f32_16x16x32_bf16 v[32:35], v[156:159], v[172:175], v[32:35]
	v_mfma_f32_16x16x32_bf16 v[20:23], v[148:151], v[226:229], v[20:23]
	v_mfma_f32_16x16x32_bf16 v[16:19], v[156:159], v[226:229], v[16:19]
	v_mfma_f32_16x16x32_bf16 v[4:7], v[148:151], v[234:237], v[4:7]
	v_mfma_f32_16x16x32_bf16 v[0:3], v[156:159], v[234:237], v[0:3]
	s_setprio 0
	s_barrier
	s_add_i32 s15, 0, 0x18000
	s_add_i32 s20, 0, 0x1c000
	v_add_u32_e32 v116, s15, v204
	v_add_u32_e32 v156, s20, v204
	ds_read_b128 v[100:103], v116
	ds_read_b128 v[108:111], v116 offset:1024
	ds_read_b128 v[112:115], v116 offset:2048
	ds_read_b128 v[116:119], v116 offset:3072
	ds_read_b128 v[136:139], v156
	ds_read_b128 v[148:151], v156 offset:1024
	ds_read_b128 v[152:155], v156 offset:2048
	ds_read_b128 v[156:159], v156 offset:3072
	s_add_u32 s0, s12, 0x160000
	s_addc_u32 s1, s13, 0
	s_mov_b32 m0, s38
	ds_read_b128 v[160:163], v223 offset:32768
	ds_read_b128 v[164:167], v223 offset:33792
	ds_read_b128 v[168:171], v223 offset:34816
	ds_read_b128 v[172:175], v223 offset:35840
	ds_read_b128 v[200:203], v223 offset:36864
	ds_read_b128 v[226:229], v223 offset:37888
	ds_read_b128 v[230:233], v223 offset:38912
	ds_read_b128 v[234:237], v223 offset:39936
	global_load_lds_dwordx4 v178, s[0:1]
	s_mov_b32 m0, s39
	s_nop 0
	global_load_lds_dwordx4 v180, s[0:1]
	s_waitcnt vmcnt(8)
	s_waitcnt lgkmcnt(0)
	s_barrier
	s_setprio 1
	s_waitcnt lgkmcnt(0)
	v_mfma_f32_16x16x32_bf16 v[144:147], v[100:103], v[160:163], v[144:147]
	v_mfma_f32_16x16x32_bf16 v[140:143], v[112:115], v[160:163], v[140:143]
	v_mfma_f32_16x16x32_bf16 v[124:127], v[100:103], v[168:171], v[124:127]
	v_mfma_f32_16x16x32_bf16 v[120:123], v[112:115], v[168:171], v[120:123]
	v_mfma_f32_16x16x32_bf16 v[92:95], v[100:103], v[200:203], v[92:95]
	v_mfma_f32_16x16x32_bf16 v[88:91], v[112:115], v[200:203], v[88:91]
	v_mfma_f32_16x16x32_bf16 v[76:79], v[100:103], v[230:233], v[76:79]
	v_mfma_f32_16x16x32_bf16 v[72:75], v[112:115], v[230:233], v[72:75]
	v_mfma_f32_16x16x32_bf16 v[144:147], v[108:111], v[164:167], v[144:147]
	v_mfma_f32_16x16x32_bf16 v[140:143], v[116:119], v[164:167], v[140:143]
	v_mfma_f32_16x16x32_bf16 v[124:127], v[108:111], v[172:175], v[124:127]
	v_mfma_f32_16x16x32_bf16 v[120:123], v[116:119], v[172:175], v[120:123]
	v_mfma_f32_16x16x32_bf16 v[92:95], v[108:111], v[226:229], v[92:95]
	v_mfma_f32_16x16x32_bf16 v[88:91], v[116:119], v[226:229], v[88:91]
	v_mfma_f32_16x16x32_bf16 v[76:79], v[108:111], v[234:237], v[76:79]
	v_mfma_f32_16x16x32_bf16 v[72:75], v[116:119], v[234:237], v[72:75]
	s_setprio 0
	s_setprio 1
	v_mfma_f32_16x16x32_bf16 v[132:135], v[136:139], v[160:163], v[132:135]
	v_mfma_f32_16x16x32_bf16 v[128:131], v[152:155], v[160:163], v[128:131]
	v_mfma_f32_16x16x32_bf16 v[104:107], v[136:139], v[168:171], v[104:107]
	v_mfma_f32_16x16x32_bf16 v[96:99], v[152:155], v[168:171], v[96:99]
	v_mfma_f32_16x16x32_bf16 v[84:87], v[136:139], v[200:203], v[84:87]
	v_mfma_f32_16x16x32_bf16 v[80:83], v[152:155], v[200:203], v[80:83]
	v_mfma_f32_16x16x32_bf16 v[68:71], v[136:139], v[230:233], v[68:71]
	v_mfma_f32_16x16x32_bf16 v[64:67], v[152:155], v[230:233], v[64:67]
	v_mfma_f32_16x16x32_bf16 v[132:135], v[148:151], v[164:167], v[132:135]
	v_mfma_f32_16x16x32_bf16 v[128:131], v[156:159], v[164:167], v[128:131]
	v_mfma_f32_16x16x32_bf16 v[104:107], v[148:151], v[172:175], v[104:107]
	v_mfma_f32_16x16x32_bf16 v[96:99], v[156:159], v[172:175], v[96:99]
	v_mfma_f32_16x16x32_bf16 v[84:87], v[148:151], v[226:229], v[84:87]
	v_mfma_f32_16x16x32_bf16 v[80:83], v[156:159], v[226:229], v[80:83]
	v_mfma_f32_16x16x32_bf16 v[68:71], v[148:151], v[234:237], v[68:71]
	v_mfma_f32_16x16x32_bf16 v[64:67], v[156:159], v[234:237], v[64:67]
	s_setprio 0
	s_barrier
	s_add_i32 s0, s15, s27
	s_mov_b32 m0, s0
	ds_read_b128 v[160:163], v223 offset:49152
	ds_read_b128 v[164:167], v223 offset:50176
	ds_read_b128 v[168:171], v223 offset:51200
	ds_read_b128 v[172:175], v223 offset:52224
	ds_read_b128 v[200:203], v223 offset:53248
	ds_read_b128 v[226:229], v223 offset:54272
	ds_read_b128 v[230:233], v223 offset:55296
	ds_read_b128 v[234:237], v223 offset:56320
	s_add_u32 s98, s8, 0x80
	s_addc_u32 s99, s9, 0
	global_load_lds_dwordx4 v176, s[98:99]
	s_add_i32 m0, s0, 0x2000
	s_add_u32 s0, s8, 0x160080
	s_addc_u32 s1, s9, 0
	s_add_i32 s8, s20, s27
	s_add_u32 s98, s0, 0xffea0000
	s_addc_u32 s99, s1, -1
	global_load_lds_dwordx4 v182, s[98:99]
	s_mov_b32 m0, s8
	s_nop 0
	global_load_lds_dwordx4 v176, s[0:1]
	s_add_i32 m0, s8, 0x2000
	s_nop 0
	global_load_lds_dwordx4 v182, s[0:1]
	s_mov_b32 m0, s44
	s_nop 0
	s_add_u32 s98, s12, 0x80
	s_addc_u32 s99, s13, 0
	global_load_lds_dwordx4 v178, s[98:99]
	s_mov_b32 m0, s45
	s_nop 0
	s_add_u32 s98, s12, 0x80
	s_addc_u32 s99, s13, 0
	global_load_lds_dwordx4 v180, s[98:99]
	s_waitcnt vmcnt(8)
	s_waitcnt lgkmcnt(0)
	s_barrier
	s_setprio 1
	s_waitcnt lgkmcnt(0)
	v_mfma_f32_16x16x32_bf16 v[60:63], v[100:103], v[160:163], v[60:63]
	v_mfma_f32_16x16x32_bf16 v[56:59], v[112:115], v[160:163], v[56:59]
	v_mfma_f32_16x16x32_bf16 v[44:47], v[100:103], v[168:171], v[44:47]
	v_mfma_f32_16x16x32_bf16 v[40:43], v[112:115], v[168:171], v[40:43]
	v_mfma_f32_16x16x32_bf16 v[28:31], v[100:103], v[200:203], v[28:31]
	v_mfma_f32_16x16x32_bf16 v[24:27], v[112:115], v[200:203], v[24:27]
	v_mfma_f32_16x16x32_bf16 v[12:15], v[100:103], v[230:233], v[12:15]
	v_mfma_f32_16x16x32_bf16 v[8:11], v[112:115], v[230:233], v[8:11]
	v_mfma_f32_16x16x32_bf16 v[60:63], v[108:111], v[164:167], v[60:63]
	v_mfma_f32_16x16x32_bf16 v[56:59], v[116:119], v[164:167], v[56:59]
	v_mfma_f32_16x16x32_bf16 v[44:47], v[108:111], v[172:175], v[44:47]
	v_mfma_f32_16x16x32_bf16 v[40:43], v[116:119], v[172:175], v[40:43]
	v_mfma_f32_16x16x32_bf16 v[28:31], v[108:111], v[226:229], v[28:31]
	v_mfma_f32_16x16x32_bf16 v[24:27], v[116:119], v[226:229], v[24:27]
	v_mfma_f32_16x16x32_bf16 v[12:15], v[108:111], v[234:237], v[12:15]
	v_mfma_f32_16x16x32_bf16 v[8:11], v[116:119], v[234:237], v[8:11]
	s_setprio 0
	s_setprio 1
	v_mfma_f32_16x16x32_bf16 v[52:55], v[136:139], v[160:163], v[52:55]
	v_mfma_f32_16x16x32_bf16 v[48:51], v[152:155], v[160:163], v[48:51]
	v_mfma_f32_16x16x32_bf16 v[36:39], v[136:139], v[168:171], v[36:39]
	v_mfma_f32_16x16x32_bf16 v[32:35], v[152:155], v[168:171], v[32:35]
	v_mfma_f32_16x16x32_bf16 v[20:23], v[136:139], v[200:203], v[20:23]
	v_mfma_f32_16x16x32_bf16 v[16:19], v[152:155], v[200:203], v[16:19]
	v_mfma_f32_16x16x32_bf16 v[4:7], v[136:139], v[230:233], v[4:7]
	v_mfma_f32_16x16x32_bf16 v[0:3], v[152:155], v[230:233], v[0:3]
	v_mfma_f32_16x16x32_bf16 v[52:55], v[148:151], v[164:167], v[52:55]
	v_mfma_f32_16x16x32_bf16 v[48:51], v[156:159], v[164:167], v[48:51]
	v_mfma_f32_16x16x32_bf16 v[36:39], v[148:151], v[172:175], v[36:39]
	v_mfma_f32_16x16x32_bf16 v[32:35], v[156:159], v[172:175], v[32:35]
	v_mfma_f32_16x16x32_bf16 v[20:23], v[148:151], v[226:229], v[20:23]
	v_mfma_f32_16x16x32_bf16 v[16:19], v[156:159], v[226:229], v[16:19]
	v_mfma_f32_16x16x32_bf16 v[4:7], v[148:151], v[234:237], v[4:7]
	v_mfma_f32_16x16x32_bf16 v[0:3], v[156:159], v[234:237], v[0:3]
	s_setprio 0
	s_barrier
	s_add_i32 s14, s14, 2
	s_add_u32 s2, s2, 0x100
	s_addc_u32 s3, s3, 0
	s_cmpk_gt_u32 s14, 0x55
	s_mov_b64 s[0:1], s[6:7]
	s_cbranch_scc0 .LBB0_1160
	s_and_b64 vcc, exec, s[52:53]
	s_cbranch_vccz .LBB0_1163
	s_barrier
